# per-phase pointer reloads from the argument copy (a dependent L2 round trip at the start of 10 phase instances) replaced by reads of spare spill lanes filled once at kernel entry
# baseline (speedup 1.0000x reference)
; #define LAS __attribute__((address_space(3)))
; __device__ __forceinline__ unsigned xb_add(unsigned* p, unsigned v) { return __hip_atomic_fetch_add(p, v, __ATOMIC_RELAXED, __HIP_MEMORY_SCOPE_AGENT); }
; __device__ __forceinline__ unsigned xb_xcc_id() { return (unsigned)__builtin_amdgcn_s_getreg((3 << 11) | 20) & 0xFu; }
; __device__ __forceinline__ XcdBarrier xcd_barrier_post(unsigned* bar, volatile LAS unsigned* st) {
;     XcdBarrier b; b.bar = bar; b.x = xb_xcc_id(); b.st = st;
;     if (threadIdx.x == 0) (void)xb_add(&bar[XB_XCNT(b.x)], 1u);
;     return b;
; __global__ void __launch_bounds__(512, 2) fwd_megakernel(Args a) {
;     ...
;     if (threadIdx.x < 4) xst[threadIdx.x] = 0u;
;     __syncthreads();
;     XcdBarrier xb0 = xcd_barrier_post((unsigned*)(ws + WS_BAR), xst); (void)xb0;
_Z14fwd_megakernel4Args:
	s_load_dwordx2 s[78:79], s[0:1], 0xa8
	s_load_dwordx2 s[84:85], s[0:1], 0x0
	s_load_dwordx2 s[86:87], s[0:1], 0x10
	s_load_dwordx2 s[88:89], s[0:1], 0x30
	s_load_dwordx2 s[90:91], s[0:1], 0x38
	s_load_dwordx2 s[92:93], s[0:1], 0x68
	s_load_dwordx2 s[94:95], s[0:1], 0x90
	s_load_dwordx2 s[96:97], s[0:1], 0xa0
	v_and_b32_e32 v152, 0x3ff, v0
	v_cmp_gt_u32_e32 vcc, 4, v152
	s_and_saveexec_b64 s[4:5], vcc
	v_lshl_add_u32 v1, v152, 2, 0
	v_add_u32_e32 v1, 0x23ff0, v1
	v_mov_b32_e32 v2, 0
	ds_write_b32 v1, v2
	s_or_b64 exec, exec, s[4:5]
	s_waitcnt lgkmcnt(0)
	v_writelane_b32 v240, s84, 50
	v_writelane_b32 v240, s85, 51
	v_writelane_b32 v240, s86, 52
	v_writelane_b32 v240, s87, 53
	v_writelane_b32 v240, s88, 54
	v_writelane_b32 v240, s89, 55
	v_writelane_b32 v240, s90, 56
	v_writelane_b32 v240, s91, 57
	v_writelane_b32 v240, s92, 58
	v_writelane_b32 v240, s93, 59
	v_writelane_b32 v240, s94, 60
	v_writelane_b32 v240, s95, 61
	v_writelane_b32 v240, s96, 62
	v_writelane_b32 v240, s97, 63
	s_add_u32 s4, s78, 0x10000
	s_addc_u32 s5, s79, 0
	s_barrier
	v_writelane_b32 v241, s4, 0
	s_getreg_b32 s3, hwreg(HW_REG_XCC_ID, 0, 4)
	v_cmp_eq_u32_e64 s[54:55], 0, v152
	v_mov_b64_e32 v[2:3], s[78:79]
	v_writelane_b32 v241, s5, 1
	s_and_saveexec_b64 s[4:5], s[54:55]
	s_cbranch_execz .LBB0_6
	s_mov_b64 s[8:9], exec
	v_mbcnt_lo_u32_b32 v1, s8, 0
	v_mbcnt_hi_u32_b32 v1, s9, v1
	v_cmp_eq_u32_e32 vcc, 0, v1
	v_mov_b64_e32 v[2:3], s[78:79]
	s_and_saveexec_b64 s[6:7], vcc
	s_cbranch_execz .LBB0_5
	s_lshl_b32 s3, s3, 8
	s_bcnt1_i32_b64 s8, s[8:9]
	s_and_b32 s3, s3, 0xf00
	v_mov_b32_e32 v2, s8
	v_readlane_b32 s8, v241, 0
	v_mov_b32_e32 v1, s3
	v_readlane_b32 s9, v241, 1
	s_nop 4
	global_atomic_add v1, v2, s[8:9] offset:1024
	v_mov_b64_e32 v[2:3], s[78:79]

; __device__ __forceinline__ void norm_phase(const void* src_lat, int lat_f32, const float* src_ctx, int nrows, const float* gvec, const float* mods_l, int sh_off, int sc_off, bf16_t* U, const float* part, int nparts, float* ctx_out) {
;     int tid_ = threadIdx.x; asm volatile("" : "+v"(tid_));
;     const int lane = tid_ & 63, w = __builtin_amdgcn_readfirstlane(tid_ >> 6);
;     const int gw = blockIdx.x * 8 + w, ngw = gridDim.x * 8;
;     f32x4 gv[4];
; #pragma unroll
;     for (int j = 0; j < 4; ++j) gv[j] = *(const f32x4*)(gvec + 4 * lane + 256 * j);
;     for (int row = gw; row < nrows; row += ngw) {
;         const int s = row < MLAT ? (row >> 13) : 4;
;         f32x4 v[4]; float ss = 0.f;
;         if (row < MLAT && !lat_f32) { const bf16_t* src = (const bf16_t*)src_lat + (size_t)row * DM + 4 * lane;
; #pragma unroll
;             for (int j = 0; j < 4; ++j) { const u32x2 w = *(const u32x2*)(src + 256 * j);
;                 v[j] = (f32x4){__uint_as_float(w.x << 16), __uint_as_float(w.x & 0xffff0000u), __uint_as_float(w.y << 16), __uint_as_float(w.y & 0xffff0000u)}; } }
;         else { const float* src = row < MLAT ? (const float*)src_lat + (size_t)row * DM : src_ctx + (size_t)(row - MLAT) * DM;
; #pragma unroll
;             for (int j = 0; j < 4; ++j) v[j] = *(const f32x4*)(src + 4 * lane + 256 * j); }
; #pragma unroll
;         for (int j = 0; j < 4; ++j) { ss += (v[j][0] * v[j][0] + v[j][1] * v[j][1]) + (v[j][2] * v[j][2] + v[j][3] * v[j][3]); }
;         if (nparts != 0 && row >= MLAT) {
;             for (int ch = 0; ch < nparts; ch += 4) {
;                 f32x4 pv[4][4];
; #pragma unroll
;                 for (int c4 = 0; c4 < 4; ++c4) { const float* pr = part + ((size_t)(ch + c4) * MCTX + (row - MLAT)) * DM + 4 * lane;
; #pragma unroll
;                     for (int j = 0; j < 4; ++j) pv[c4][j] = *(const f32x4*)(pr + 256 * j); }
; #pragma unroll
;                 for (int c4 = 0; c4 < 4; ++c4)
; #pragma unroll
;                     for (int j = 0; j < 4; ++j) v[j] = v[j] + pv[c4][j]; }
; __global__ void __launch_bounds__(512, 2) fwd_megakernel(Args a) {
;     ...
;         norm_phase(l == 0 ? (const void*)A->x : (const void*)WSP(bf16_t, WS_HB), l == 0, l == 0 ? A->ctx : WSP(float, WS_HC), MALL, A->g_mix + l * DM, WSP(float, WS_MODS) + l * 5 * 6144, 0, 1024, WSP(bf16_t, WS_U), WSP(const float, WS_PART), l == 0 ? 0 : 16, WSP(float, WS_HC));
.LBB0_134:
	v_writelane_b32 v240, s6, 36
	s_and_b64 vcc, exec, s[6:7]
	v_mov_b64_e32 v[32:33], s[70:71]
	v_writelane_b32 v240, s7, 37
	s_cbranch_vccz .LBB0_136
	v_readlane_b32 s98, v240, 50
	v_readlane_b32 s99, v240, 51
	v_mov_b32_e32 v32, s98
	v_mov_b32_e32 v33, s99
.LBB0_136:
	v_readlane_b32 s6, v240, 36
	v_readlane_b32 s7, v240, 37
	s_mov_b32 s11, 0x800000
	s_mov_b32 s10, 16
	v_cndmask_b32_e64 v0, 0, 1, s[6:7]
	v_cmp_ne_u32_e64 s[0:1], 1, v0
	s_andn2_b64 vcc, exec, s[6:7]
	v_mov_b64_e32 v[34:35], s[72:73]
	v_writelane_b32 v240, s0, 40
	s_nop 1
	v_writelane_b32 v240, s1, 41
	s_cbranch_vccnz .LBB0_138
	v_readlane_b32 s98, v240, 52
	v_readlane_b32 s99, v240, 53
	v_mov_b32_e32 v34, s98
	v_mov_b32_e32 v35, s99
	s_mov_b32 s10, 0
.LBB0_138:
	v_readlane_b32 s98, v240, 54
	v_readlane_b32 s99, v240, 55
	v_mov_b32_e32 v0, s98
	v_mov_b32_e32 v1, s99
	v_readlane_b32 s0, v240, 36
	v_readlane_b32 s1, v240, 37
	s_xor_b64 s[0:1], s[0:1], -1
	v_writelane_b32 v240, s0, 38
	v_readlane_b32 s6, v241, 5
	v_mov_b32_e32 v16, v152
	v_writelane_b32 v240, s1, 39
	s_mov_b32 s9, s83
	v_readlane_b32 s0, v240, 16
	s_mul_i32 s82, s0, 0x7800
	s_lshl_b32 s8, s0, 10
	s_lshl_b64 s[0:1], s[82:83], 2
	s_add_u32 s0, s6, s0
	v_writelane_b32 v240, s0, 42
	v_readlane_b32 s0, v241, 6
	s_addc_u32 s0, s0, s1
	s_nop 0
	v_writelane_b32 v240, s0, 43
	v_readfirstlane_b32 s0, v16
	s_ashr_i32 s1, s0, 6
	v_readlane_b32 s0, v241, 4
	s_add_i32 s0, s1, s0
	s_cmp_gt_i32 s0, 0x83ff
	v_writelane_b32 v240, s8, 44
	s_nop 1
	v_writelane_b32 v240, s9, 45
	s_cbranch_scc1 .LBB0_150
	v_readlane_b32 s6, v240, 44
	v_readlane_b32 s7, v240, 45
	v_lshlrev_b32_e32 v2, 2, v16
	s_lshl_b64 s[6:7], s[6:7], 2
	v_and_b32_e32 v36, 0xfc, v2
	s_waitcnt vmcnt(0)
	v_lshl_add_u64 v[0:1], v[0:1], 0, s[6:7]
	v_lshlrev_b32_e32 v154, 2, v36
	v_lshl_add_u64 v[12:13], v[0:1], 0, v[154:155]
	flat_load_dwordx4 v[0:3], v[12:13]
	flat_load_dwordx4 v[4:7], v[12:13] offset:1024
	flat_load_dwordx4 v[8:11], v[12:13] offset:2048
	s_nop 0
	flat_load_dwordx4 v[12:15], v[12:13] offset:3072
	v_and_b32_e32 v16, 63, v16
	v_readlane_b32 s6, v240, 9
	v_lshl_add_u64 v[40:41], s[72:73], 0, v[154:155]
	v_lshlrev_b32_e32 v154, 4, v16
	v_readlane_b32 s7, v240, 10
	v_lshlrev_b32_e32 v18, 1, v36
	v_mov_b32_e32 v19, v155
	v_lshl_add_u64 v[44:45], s[6:7], 0, v[154:155]
	v_readlane_b32 s6, v240, 13
	v_lshl_add_u64 v[38:39], v[32:33], 0, v[18:19]
	v_lshl_add_u64 v[42:43], s[94:95], 0, v[18:19]
	s_add_i32 s82, s6, s1
	s_cmp_lg_u32 s56, 0x800
	s_cbranch_scc1 .LBB0_142
	v_readlane_b32 s37, v240, 36
	s_nop 0
	s_cmp_eq_u32 s37, 0
	s_cbranch_scc1 .Lnorm1_bf16
	v_and_b32_e32 v102, 63, v152
	v_lshlrev_b32_e32 v103, 4, v102
	v_lshlrev_b32_e32 v102, 3, v102
	v_readfirstlane_b32 s38, v32
	v_readfirstlane_b32 s39, v33
	v_readlane_b32 s34, v240, 42
	v_readlane_b32 s35, v240, 43
	s_nop 0
	s_lshl_b32 s36, s0, 12
	s_add_u32 s38, s38, s36
	s_addc_u32 s39, s39, 0
	s_lshl_b32 s36, s0, 11
	s_add_u32 s40, s94, s36
	s_addc_u32 s41, s95, 0
	s_add_u32 s42, s34, 0x0
	s_addc_u32 s43, s35, 0
	s_add_u32 s44, s34, 0x1000
	s_addc_u32 s45, s35, 0
	global_load_dwordx4 v[112:115], v103, s[42:43]
	global_load_dwordx4 v[116:119], v103, s[42:43] offset:1024
	global_load_dwordx4 v[120:123], v103, s[42:43] offset:2048
	global_load_dwordx4 v[124:127], v103, s[42:43] offset:3072
	global_load_dwordx4 v[128:131], v103, s[44:45]
	global_load_dwordx4 v[132:135], v103, s[44:45] offset:1024
	global_load_dwordx4 v[136:139], v103, s[44:45] offset:2048
	global_load_dwordx4 v[140:143], v103, s[44:45] offset:3072
	s_add_u32 s42, s42, 0x6000
	s_addc_u32 s43, s43, 0
	s_add_u32 s44, s44, 0x6000
	s_addc_u32 s45, s45, 0
	global_load_dwordx4 v[158:161], v103, s[38:39]
	global_load_dwordx4 v[162:165], v103, s[38:39] offset:1024
	global_load_dwordx4 v[166:169], v103, s[38:39] offset:2048
	global_load_dwordx4 v[170:173], v103, s[38:39] offset:3072
	s_add_u32 s38, s38, 0x800000
	s_addc_u32 s39, s39, 0
	global_load_dwordx4 v[174:177], v103, s[38:39]
	global_load_dwordx4 v[178:181], v103, s[38:39] offset:1024
	global_load_dwordx4 v[182:185], v103, s[38:39] offset:2048
	global_load_dwordx4 v[186:189], v103, s[38:39] offset:3072
	s_add_u32 s38, s38, 0x800000
	s_addc_u32 s39, s39, 0
	global_load_dwordx4 v[198:201], v103, s[38:39]
	global_load_dwordx4 v[202:205], v103, s[38:39] offset:1024
	global_load_dwordx4 v[206:209], v103, s[38:39] offset:2048
	global_load_dwordx4 v[210:213], v103, s[38:39] offset:3072
	s_add_u32 s38, s38, 0x800000
	s_addc_u32 s39, s39, 0
	global_load_dwordx4 v[214:217], v103, s[38:39]
	global_load_dwordx4 v[218:221], v103, s[38:39] offset:1024
	global_load_dwordx4 v[222:225], v103, s[38:39] offset:2048
	global_load_dwordx4 v[226:229], v103, s[38:39] offset:3072
	s_add_u32 s38, s38, 0x800000
	s_addc_u32 s39, s39, 0
	s_waitcnt vmcnt(16)
	v_pk_add_f32 v[128:129], v[128:129], 1.0 op_sel_hi:[1,0]
	v_pk_add_f32 v[130:131], v[130:131], 1.0 op_sel_hi:[1,0]
	v_pk_add_f32 v[132:133], v[132:133], 1.0 op_sel_hi:[1,0]
	v_pk_add_f32 v[134:135], v[134:135], 1.0 op_sel_hi:[1,0]
	v_pk_add_f32 v[136:137], v[136:137], 1.0 op_sel_hi:[1,0]
	v_pk_add_f32 v[138:139], v[138:139], 1.0 op_sel_hi:[1,0]
	v_pk_add_f32 v[140:141], v[140:141], 1.0 op_sel_hi:[1,0]
	v_pk_add_f32 v[142:143], v[142:143], 1.0 op_sel_hi:[1,0]
	s_waitcnt vmcnt(12)
; __device__ __forceinline__ void norm_phase(const void* src_lat, int lat_f32, const float* src_ctx, int nrows, const float* gvec, const float* mods_l, int sh_off, int sc_off, bf16_t* U, const float* part, int nparts, float* ctx_out) {
;     ...
;     for (int row = gw; row < nrows; row += ngw) {
;         const int s = row < MLAT ? (row >> 13) : 4;
;         f32x4 v[4]; float ss = 0.f;
;         if (row < MLAT && !lat_f32) { const bf16_t* src = (const bf16_t*)src_lat + (size_t)row * DM + 4 * lane;
; #pragma unroll
;             for (int j = 0; j < 4; ++j) { const u32x2 w = *(const u32x2*)(src + 256 * j);
;                 v[j] = (f32x4){__uint_as_float(w.x << 16), __uint_as_float(w.x & 0xffff0000u), __uint_as_float(w.y << 16), __uint_as_float(w.y & 0xffff0000u)}; } }
;         else { const float* src = row < MLAT ? (const float*)src_lat + (size_t)row * DM : src_ctx + (size_t)(row - MLAT) * DM;
; #pragma unroll
;             for (int j = 0; j < 4; ++j) v[j] = *(const f32x4*)(src + 4 * lane + 256 * j); }
; #pragma unroll
;         for (int j = 0; j < 4; ++j) { ss += (v[j][0] * v[j][0] + v[j][1] * v[j][1]) + (v[j][2] * v[j][2] + v[j][3] * v[j][3]); }
;         if (nparts != 0 && row >= MLAT) {
;             for (int ch = 0; ch < nparts; ch += 4) {
;                 f32x4 pv[4][4];
; #pragma unroll
;                 for (int c4 = 0; c4 < 4; ++c4) { const float* pr = part + ((size_t)(ch + c4) * MCTX + (row - MLAT)) * DM + 4 * lane;
; #pragma unroll
;                     for (int j = 0; j < 4; ++j) pv[c4][j] = *(const f32x4*)(pr + 256 * j); }
; #pragma unroll
;                 for (int c4 = 0; c4 < 4; ++c4)
; #pragma unroll
;                     for (int j = 0; j < 4; ++j) v[j] = v[j] + pv[c4][j]; }
;             ss = 0.f;
; #pragma unroll
;             for (int j = 0; j < 4; ++j) { *(f32x4*)(ctx_out + (size_t)(row - MLAT) * DM + 4 * lane + 256 * j) = v[j]; ss += (v[j][0] * v[j][0] + v[j][1] * v[j][1]) + (v[j][2] * v[j][2] + v[j][3] * v[j][3]); }
;         }
;         const float rs = rsqrtf(wave_sum64(ss) * (1.0f / DM) + EPS);
;         const float* shp = mods_l + s * 6144 + sh_off + 4 * lane; const float* scp = mods_l + s * 6144 + sc_off + 4 * lane;
;         bf16_t* up = U + (size_t)row * DM + 4 * lane;
; #pragma unroll
;         for (int j = 0; j < 4; ++j) { const f32x4 sh = *(const f32x4*)(shp + 256 * j), sc = *(const f32x4*)(scp + 256 * j);
	v_mul_f32_e32 v96, v159, v159
	v_mul_f32_e32 v97, v161, v161
	v_fmac_f32_e32 v96, v158, v158
	v_fmac_f32_e32 v97, v160, v160
	v_add_f32_e32 v98, v96, v97
	v_mul_f32_e32 v96, v163, v163
	v_mul_f32_e32 v97, v165, v165
	v_fmac_f32_e32 v96, v162, v162
	v_fmac_f32_e32 v97, v164, v164
	v_add_f32_e32 v96, v96, v97
	v_add_f32_e32 v98, v98, v96
	v_mul_f32_e32 v96, v167, v167
	v_mul_f32_e32 v97, v169, v169
	v_fmac_f32_e32 v96, v166, v166
	v_fmac_f32_e32 v97, v168, v168
	v_add_f32_e32 v96, v96, v97
	v_add_f32_e32 v98, v98, v96
	v_mul_f32_e32 v96, v171, v171
	v_mul_f32_e32 v97, v173, v173
	v_fmac_f32_e32 v96, v170, v170
	v_fmac_f32_e32 v97, v172, v172
	v_add_f32_e32 v96, v96, v97
	v_add_f32_e32 v98, v98, v96
	s_nop 1
	v_add_f32_dpp v98, v98, v98 quad_perm:[1,0,3,2] row_mask:0xf bank_mask:0xf bound_ctrl:1
	s_nop 1
	v_add_f32_dpp v98, v98, v98 quad_perm:[2,3,0,1] row_mask:0xf bank_mask:0xf bound_ctrl:1
	s_nop 1
	v_add_f32_dpp v98, v98, v98 row_half_mirror row_mask:0xf bank_mask:0xf bound_ctrl:1
	s_nop 1
	v_add_f32_dpp v98, v98, v98 row_mirror row_mask:0xf bank_mask:0xf bound_ctrl:1
	v_mov_b32_e32 v96, v98
	s_nop 1
	v_permlane16_swap_b32_e32 v98, v96
	v_add_f32_e32 v98, v98, v96
	v_mov_b32_e32 v96, v98
	s_nop 1
	v_permlane32_swap_b32_e32 v98, v96
	v_add_f32_e32 v98, v98, v96
	v_fmamk_f32 v100, v98, 0x3a800000, v153
	v_rsq_f32_e32 v100, v100
	s_nop 0
	v_pk_mul_f32 v[158:159], v[158:159], v[100:101] op_sel_hi:[1,0]
	v_pk_mul_f32 v[160:161], v[160:161], v[100:101] op_sel_hi:[1,0]
	v_pk_mul_f32 v[162:163], v[162:163], v[100:101] op_sel_hi:[1,0]
	v_pk_mul_f32 v[164:165], v[164:165], v[100:101] op_sel_hi:[1,0]
	v_pk_mul_f32 v[166:167], v[166:167], v[100:101] op_sel_hi:[1,0]
	v_pk_mul_f32 v[168:169], v[168:169], v[100:101] op_sel_hi:[1,0]
	v_pk_mul_f32 v[170:171], v[170:171], v[100:101] op_sel_hi:[1,0]
	v_pk_mul_f32 v[172:173], v[172:173], v[100:101] op_sel_hi:[1,0]
	v_pk_mul_f32 v[158:159], v[0:1], v[158:159]
	v_pk_mul_f32 v[160:161], v[2:3], v[160:161]
	v_pk_mul_f32 v[162:163], v[4:5], v[162:163]
	v_pk_mul_f32 v[164:165], v[6:7], v[164:165]
	v_pk_mul_f32 v[166:167], v[8:9], v[166:167]
	v_pk_mul_f32 v[168:169], v[10:11], v[168:169]
	v_pk_mul_f32 v[170:171], v[12:13], v[170:171]
	v_pk_mul_f32 v[172:173], v[14:15], v[172:173]
	v_pk_fma_f32 v[158:159], v[128:129], v[158:159], v[112:113]
	v_pk_fma_f32 v[160:161], v[130:131], v[160:161], v[114:115]
	v_pk_fma_f32 v[162:163], v[132:133], v[162:163], v[116:117]
	v_pk_fma_f32 v[164:165], v[134:135], v[164:165], v[118:119]
	v_pk_fma_f32 v[166:167], v[136:137], v[166:167], v[120:121]
	v_pk_fma_f32 v[168:169], v[138:139], v[168:169], v[122:123]
	v_pk_fma_f32 v[170:171], v[140:141], v[170:171], v[124:125]
	v_pk_fma_f32 v[172:173], v[142:143], v[172:173], v[126:127]
	v_cvt_pk_bf16_f32 v158, v158, v159
	v_cvt_pk_bf16_f32 v159, v160, v161
	v_cvt_pk_bf16_f32 v162, v162, v163
	v_cvt_pk_bf16_f32 v163, v164, v165
	v_cvt_pk_bf16_f32 v166, v166, v167
	v_cvt_pk_bf16_f32 v167, v168, v169
	v_cvt_pk_bf16_f32 v170, v170, v171
	v_cvt_pk_bf16_f32 v171, v172, v173
	global_store_dwordx2 v102, v[158:159], s[40:41]
	global_store_dwordx2 v102, v[162:163], s[40:41] offset:512
	global_store_dwordx2 v102, v[166:167], s[40:41] offset:1024
	global_store_dwordx2 v102, v[170:171], s[40:41] offset:1536
	s_add_u32 s40, s40, 0x400000
	s_addc_u32 s41, s41, 0
	global_load_dwordx4 v[158:161], v103, s[38:39]
	global_load_dwordx4 v[162:165], v103, s[38:39] offset:1024
	global_load_dwordx4 v[166:169], v103, s[38:39] offset:2048
	global_load_dwordx4 v[170:173], v103, s[38:39] offset:3072
	s_add_u32 s38, s38, 0x800000
	s_addc_u32 s39, s39, 0
	global_load_dwordx4 v[48:51], v103, s[42:43]
	global_load_dwordx4 v[52:55], v103, s[42:43] offset:1024
	global_load_dwordx4 v[56:59], v103, s[42:43] offset:2048
	global_load_dwordx4 v[60:63], v103, s[42:43] offset:3072
	global_load_dwordx4 v[64:67], v103, s[44:45]
	global_load_dwordx4 v[68:71], v103, s[44:45] offset:1024
	global_load_dwordx4 v[72:75], v103, s[44:45] offset:2048
	global_load_dwordx4 v[76:79], v103, s[44:45] offset:3072
	s_add_u32 s42, s42, 0x6000
	s_addc_u32 s43, s43, 0
	s_add_u32 s44, s44, 0x6000
	s_addc_u32 s45, s45, 0
	s_waitcnt vmcnt(24)
	v_mul_f32_e32 v96, v175, v175
	v_mul_f32_e32 v97, v177, v177
	v_fmac_f32_e32 v96, v174, v174
	v_fmac_f32_e32 v97, v176, v176
	v_add_f32_e32 v98, v96, v97
	v_mul_f32_e32 v96, v179, v179
	v_mul_f32_e32 v97, v181, v181
	v_fmac_f32_e32 v96, v178, v178
	v_fmac_f32_e32 v97, v180, v180
	v_add_f32_e32 v96, v96, v97
	v_add_f32_e32 v98, v98, v96
	v_mul_f32_e32 v96, v183, v183
	v_mul_f32_e32 v97, v185, v185
	v_fmac_f32_e32 v96, v182, v182
	v_fmac_f32_e32 v97, v184, v184
	v_add_f32_e32 v96, v96, v97
	v_add_f32_e32 v98, v98, v96
	v_mul_f32_e32 v96, v187, v187
	v_mul_f32_e32 v97, v189, v189
	v_fmac_f32_e32 v96, v186, v186
	v_fmac_f32_e32 v97, v188, v188
	v_add_f32_e32 v96, v96, v97
	v_add_f32_e32 v98, v98, v96
	s_nop 1
	v_add_f32_dpp v98, v98, v98 quad_perm:[1,0,3,2] row_mask:0xf bank_mask:0xf bound_ctrl:1
	s_nop 1
	v_add_f32_dpp v98, v98, v98 quad_perm:[2,3,0,1] row_mask:0xf bank_mask:0xf bound_ctrl:1
	s_nop 1
	v_add_f32_dpp v98, v98, v98 row_half_mirror row_mask:0xf bank_mask:0xf bound_ctrl:1
	s_nop 1
	v_add_f32_dpp v98, v98, v98 row_mirror row_mask:0xf bank_mask:0xf bound_ctrl:1
	v_mov_b32_e32 v96, v98
	s_nop 1
	v_permlane16_swap_b32_e32 v98, v96
	v_add_f32_e32 v98, v98, v96
	v_mov_b32_e32 v96, v98
	s_nop 1
	v_permlane32_swap_b32_e32 v98, v96
	v_add_f32_e32 v98, v98, v96
	v_fmamk_f32 v100, v98, 0x3a800000, v153
	v_rsq_f32_e32 v100, v100
	s_nop 0
	v_pk_mul_f32 v[174:175], v[174:175], v[100:101] op_sel_hi:[1,0]
	v_pk_mul_f32 v[176:177], v[176:177], v[100:101] op_sel_hi:[1,0]
; __device__ __forceinline__ void norm_phase(const void* src_lat, int lat_f32, const float* src_ctx, int nrows, const float* gvec, const float* mods_l, int sh_off, int sc_off, bf16_t* U, const float* part, int nparts, float* ctx_out) {
;     ...
;     for (int row = gw; row < nrows; row += ngw) {
;         const int s = row < MLAT ? (row >> 13) : 4;
;         f32x4 v[4]; float ss = 0.f;
;         if (row < MLAT && !lat_f32) { const bf16_t* src = (const bf16_t*)src_lat + (size_t)row * DM + 4 * lane;
; #pragma unroll
;             for (int j = 0; j < 4; ++j) { const u32x2 w = *(const u32x2*)(src + 256 * j);
;                 v[j] = (f32x4){__uint_as_float(w.x << 16), __uint_as_float(w.x & 0xffff0000u), __uint_as_float(w.y << 16), __uint_as_float(w.y & 0xffff0000u)}; } }
;         else { const float* src = row < MLAT ? (const float*)src_lat + (size_t)row * DM : src_ctx + (size_t)(row - MLAT) * DM;
; #pragma unroll
;             for (int j = 0; j < 4; ++j) v[j] = *(const f32x4*)(src + 4 * lane + 256 * j); }
; #pragma unroll
;         for (int j = 0; j < 4; ++j) { ss += (v[j][0] * v[j][0] + v[j][1] * v[j][1]) + (v[j][2] * v[j][2] + v[j][3] * v[j][3]); }
;         if (nparts != 0 && row >= MLAT) {
;             for (int ch = 0; ch < nparts; ch += 4) {
;                 f32x4 pv[4][4];
; #pragma unroll
;                 for (int c4 = 0; c4 < 4; ++c4) { const float* pr = part + ((size_t)(ch + c4) * MCTX + (row - MLAT)) * DM + 4 * lane;
; #pragma unroll
;                     for (int j = 0; j < 4; ++j) pv[c4][j] = *(const f32x4*)(pr + 256 * j); }
; #pragma unroll
;                 for (int c4 = 0; c4 < 4; ++c4)
; #pragma unroll
;                     for (int j = 0; j < 4; ++j) v[j] = v[j] + pv[c4][j]; }
;             ss = 0.f;
; #pragma unroll
;             for (int j = 0; j < 4; ++j) { *(f32x4*)(ctx_out + (size_t)(row - MLAT) * DM + 4 * lane + 256 * j) = v[j]; ss += (v[j][0] * v[j][0] + v[j][1] * v[j][1]) + (v[j][2] * v[j][2] + v[j][3] * v[j][3]); }
;         }
;         const float rs = rsqrtf(wave_sum64(ss) * (1.0f / DM) + EPS);
;         const float* shp = mods_l + s * 6144 + sh_off + 4 * lane; const float* scp = mods_l + s * 6144 + sc_off + 4 * lane;
;         bf16_t* up = U + (size_t)row * DM + 4 * lane;
; #pragma unroll
;         for (int j = 0; j < 4; ++j) { const f32x4 sh = *(const f32x4*)(shp + 256 * j), sc = *(const f32x4*)(scp + 256 * j);
	v_pk_mul_f32 v[178:179], v[178:179], v[100:101] op_sel_hi:[1,0]
	v_pk_mul_f32 v[180:181], v[180:181], v[100:101] op_sel_hi:[1,0]
	v_pk_mul_f32 v[182:183], v[182:183], v[100:101] op_sel_hi:[1,0]
	v_pk_mul_f32 v[184:185], v[184:185], v[100:101] op_sel_hi:[1,0]
	v_pk_mul_f32 v[186:187], v[186:187], v[100:101] op_sel_hi:[1,0]
	v_pk_mul_f32 v[188:189], v[188:189], v[100:101] op_sel_hi:[1,0]
	v_pk_mul_f32 v[174:175], v[0:1], v[174:175]
	v_pk_mul_f32 v[176:177], v[2:3], v[176:177]
	v_pk_mul_f32 v[178:179], v[4:5], v[178:179]
	v_pk_mul_f32 v[180:181], v[6:7], v[180:181]
	v_pk_mul_f32 v[182:183], v[8:9], v[182:183]
	v_pk_mul_f32 v[184:185], v[10:11], v[184:185]
	v_pk_mul_f32 v[186:187], v[12:13], v[186:187]
	v_pk_mul_f32 v[188:189], v[14:15], v[188:189]
	v_pk_fma_f32 v[174:175], v[128:129], v[174:175], v[112:113]
	v_pk_fma_f32 v[176:177], v[130:131], v[176:177], v[114:115]
	v_pk_fma_f32 v[178:179], v[132:133], v[178:179], v[116:117]
	v_pk_fma_f32 v[180:181], v[134:135], v[180:181], v[118:119]
	v_pk_fma_f32 v[182:183], v[136:137], v[182:183], v[120:121]
	v_pk_fma_f32 v[184:185], v[138:139], v[184:185], v[122:123]
	v_pk_fma_f32 v[186:187], v[140:141], v[186:187], v[124:125]
	v_pk_fma_f32 v[188:189], v[142:143], v[188:189], v[126:127]
	v_cvt_pk_bf16_f32 v174, v174, v175
	v_cvt_pk_bf16_f32 v175, v176, v177
	v_cvt_pk_bf16_f32 v178, v178, v179
	v_cvt_pk_bf16_f32 v179, v180, v181
	v_cvt_pk_bf16_f32 v182, v182, v183
	v_cvt_pk_bf16_f32 v183, v184, v185
	v_cvt_pk_bf16_f32 v186, v186, v187
	v_cvt_pk_bf16_f32 v187, v188, v189
	global_store_dwordx2 v102, v[174:175], s[40:41]
	global_store_dwordx2 v102, v[178:179], s[40:41] offset:512
	global_store_dwordx2 v102, v[182:183], s[40:41] offset:1024
	global_store_dwordx2 v102, v[186:187], s[40:41] offset:1536
	s_add_u32 s40, s40, 0x400000
	s_addc_u32 s41, s41, 0
	global_load_dwordx4 v[174:177], v103, s[38:39]
	global_load_dwordx4 v[178:181], v103, s[38:39] offset:1024
	global_load_dwordx4 v[182:185], v103, s[38:39] offset:2048
	global_load_dwordx4 v[186:189], v103, s[38:39] offset:3072
	s_add_u32 s38, s38, 0x800000
	s_addc_u32 s39, s39, 0
	s_waitcnt vmcnt(28)
	v_mul_f32_e32 v96, v199, v199
	v_mul_f32_e32 v97, v201, v201
	v_fmac_f32_e32 v96, v198, v198
	v_fmac_f32_e32 v97, v200, v200
	v_add_f32_e32 v98, v96, v97
	v_mul_f32_e32 v96, v203, v203
	v_mul_f32_e32 v97, v205, v205
	v_fmac_f32_e32 v96, v202, v202
	v_fmac_f32_e32 v97, v204, v204
	v_add_f32_e32 v96, v96, v97
	v_add_f32_e32 v98, v98, v96
	v_mul_f32_e32 v96, v207, v207
	v_mul_f32_e32 v97, v209, v209
	v_fmac_f32_e32 v96, v206, v206
	v_fmac_f32_e32 v97, v208, v208
	v_add_f32_e32 v96, v96, v97
	v_add_f32_e32 v98, v98, v96
	v_mul_f32_e32 v96, v211, v211
	v_mul_f32_e32 v97, v213, v213
	v_fmac_f32_e32 v96, v210, v210
	v_fmac_f32_e32 v97, v212, v212
	v_add_f32_e32 v96, v96, v97
	v_add_f32_e32 v98, v98, v96
	s_nop 1
	v_add_f32_dpp v98, v98, v98 quad_perm:[1,0,3,2] row_mask:0xf bank_mask:0xf bound_ctrl:1
	s_nop 1
	v_add_f32_dpp v98, v98, v98 quad_perm:[2,3,0,1] row_mask:0xf bank_mask:0xf bound_ctrl:1
	s_nop 1
	v_add_f32_dpp v98, v98, v98 row_half_mirror row_mask:0xf bank_mask:0xf bound_ctrl:1
	s_nop 1
	v_add_f32_dpp v98, v98, v98 row_mirror row_mask:0xf bank_mask:0xf bound_ctrl:1
	v_mov_b32_e32 v96, v98
	s_nop 1
	v_permlane16_swap_b32_e32 v98, v96
	v_add_f32_e32 v98, v98, v96
	v_mov_b32_e32 v96, v98
	s_nop 1
	v_permlane32_swap_b32_e32 v98, v96
	v_add_f32_e32 v98, v98, v96
	v_fmamk_f32 v100, v98, 0x3a800000, v153
	v_rsq_f32_e32 v100, v100
	s_nop 0
	v_pk_mul_f32 v[198:199], v[198:199], v[100:101] op_sel_hi:[1,0]
	v_pk_mul_f32 v[200:201], v[200:201], v[100:101] op_sel_hi:[1,0]
	v_pk_mul_f32 v[202:203], v[202:203], v[100:101] op_sel_hi:[1,0]
	v_pk_mul_f32 v[204:205], v[204:205], v[100:101] op_sel_hi:[1,0]
	v_pk_mul_f32 v[206:207], v[206:207], v[100:101] op_sel_hi:[1,0]
	v_pk_mul_f32 v[208:209], v[208:209], v[100:101] op_sel_hi:[1,0]
	v_pk_mul_f32 v[210:211], v[210:211], v[100:101] op_sel_hi:[1,0]
	v_pk_mul_f32 v[212:213], v[212:213], v[100:101] op_sel_hi:[1,0]
	v_pk_mul_f32 v[198:199], v[0:1], v[198:199]
	v_pk_mul_f32 v[200:201], v[2:3], v[200:201]
	v_pk_mul_f32 v[202:203], v[4:5], v[202:203]
	v_pk_mul_f32 v[204:205], v[6:7], v[204:205]
	v_pk_mul_f32 v[206:207], v[8:9], v[206:207]
	v_pk_mul_f32 v[208:209], v[10:11], v[208:209]
	v_pk_mul_f32 v[210:211], v[12:13], v[210:211]
	v_pk_mul_f32 v[212:213], v[14:15], v[212:213]
	v_pk_fma_f32 v[198:199], v[128:129], v[198:199], v[112:113]
	v_pk_fma_f32 v[200:201], v[130:131], v[200:201], v[114:115]
	v_pk_fma_f32 v[202:203], v[132:133], v[202:203], v[116:117]
	v_pk_fma_f32 v[204:205], v[134:135], v[204:205], v[118:119]
	v_pk_fma_f32 v[206:207], v[136:137], v[206:207], v[120:121]
	v_pk_fma_f32 v[208:209], v[138:139], v[208:209], v[122:123]
	v_pk_fma_f32 v[210:211], v[140:141], v[210:211], v[124:125]
	v_pk_fma_f32 v[212:213], v[142:143], v[212:213], v[126:127]
	v_cvt_pk_bf16_f32 v198, v198, v199
	v_cvt_pk_bf16_f32 v199, v200, v201
	v_cvt_pk_bf16_f32 v202, v202, v203
	v_cvt_pk_bf16_f32 v203, v204, v205
	v_cvt_pk_bf16_f32 v206, v206, v207
	v_cvt_pk_bf16_f32 v207, v208, v209
	v_cvt_pk_bf16_f32 v210, v210, v211
	v_cvt_pk_bf16_f32 v211, v212, v213
	global_store_dwordx2 v102, v[198:199], s[40:41]
	global_store_dwordx2 v102, v[202:203], s[40:41] offset:512
	global_store_dwordx2 v102, v[206:207], s[40:41] offset:1024
	global_store_dwordx2 v102, v[210:211], s[40:41] offset:1536
	s_add_u32 s40, s40, 0x400000
	s_addc_u32 s41, s41, 0
	global_load_dwordx4 v[198:201], v103, s[38:39]
	global_load_dwordx4 v[202:205], v103, s[38:39] offset:1024
	global_load_dwordx4 v[206:209], v103, s[38:39] offset:2048
	global_load_dwordx4 v[210:213], v103, s[38:39] offset:3072
	s_add_u32 s38, s38, 0x800000
	s_addc_u32 s39, s39, 0
	s_waitcnt vmcnt(32)
; __device__ __forceinline__ void norm_phase(const void* src_lat, int lat_f32, const float* src_ctx, int nrows, const float* gvec, const float* mods_l, int sh_off, int sc_off, bf16_t* U, const float* part, int nparts, float* ctx_out) {
;     ...
;     for (int row = gw; row < nrows; row += ngw) {
;         const int s = row < MLAT ? (row >> 13) : 4;
;         f32x4 v[4]; float ss = 0.f;
;         if (row < MLAT && !lat_f32) { const bf16_t* src = (const bf16_t*)src_lat + (size_t)row * DM + 4 * lane;
; #pragma unroll
;             for (int j = 0; j < 4; ++j) { const u32x2 w = *(const u32x2*)(src + 256 * j);
;                 v[j] = (f32x4){__uint_as_float(w.x << 16), __uint_as_float(w.x & 0xffff0000u), __uint_as_float(w.y << 16), __uint_as_float(w.y & 0xffff0000u)}; } }
;         else { const float* src = row < MLAT ? (const float*)src_lat + (size_t)row * DM : src_ctx + (size_t)(row - MLAT) * DM;
; #pragma unroll
;             for (int j = 0; j < 4; ++j) v[j] = *(const f32x4*)(src + 4 * lane + 256 * j); }
; #pragma unroll
;         for (int j = 0; j < 4; ++j) { ss += (v[j][0] * v[j][0] + v[j][1] * v[j][1]) + (v[j][2] * v[j][2] + v[j][3] * v[j][3]); }
;         if (nparts != 0 && row >= MLAT) {
;             for (int ch = 0; ch < nparts; ch += 4) {
;                 f32x4 pv[4][4];
; #pragma unroll
;                 for (int c4 = 0; c4 < 4; ++c4) { const float* pr = part + ((size_t)(ch + c4) * MCTX + (row - MLAT)) * DM + 4 * lane;
; #pragma unroll
;                     for (int j = 0; j < 4; ++j) pv[c4][j] = *(const f32x4*)(pr + 256 * j); }
; #pragma unroll
;                 for (int c4 = 0; c4 < 4; ++c4)
; #pragma unroll
;                     for (int j = 0; j < 4; ++j) v[j] = v[j] + pv[c4][j]; }
;             ss = 0.f;
; #pragma unroll
;             for (int j = 0; j < 4; ++j) { *(f32x4*)(ctx_out + (size_t)(row - MLAT) * DM + 4 * lane + 256 * j) = v[j]; ss += (v[j][0] * v[j][0] + v[j][1] * v[j][1]) + (v[j][2] * v[j][2] + v[j][3] * v[j][3]); }
;         }
;         const float rs = rsqrtf(wave_sum64(ss) * (1.0f / DM) + EPS);
;         const float* shp = mods_l + s * 6144 + sh_off + 4 * lane; const float* scp = mods_l + s * 6144 + sc_off + 4 * lane;
;         bf16_t* up = U + (size_t)row * DM + 4 * lane;
; #pragma unroll
;         for (int j = 0; j < 4; ++j) { const f32x4 sh = *(const f32x4*)(shp + 256 * j), sc = *(const f32x4*)(scp + 256 * j);
	v_mul_f32_e32 v96, v215, v215
	v_mul_f32_e32 v97, v217, v217
	v_fmac_f32_e32 v96, v214, v214
	v_fmac_f32_e32 v97, v216, v216
	v_add_f32_e32 v98, v96, v97
	v_mul_f32_e32 v96, v219, v219
	v_mul_f32_e32 v97, v221, v221
	v_fmac_f32_e32 v96, v218, v218
	v_fmac_f32_e32 v97, v220, v220
	v_add_f32_e32 v96, v96, v97
	v_add_f32_e32 v98, v98, v96
	v_mul_f32_e32 v96, v223, v223
	v_mul_f32_e32 v97, v225, v225
	v_fmac_f32_e32 v96, v222, v222
	v_fmac_f32_e32 v97, v224, v224
	v_add_f32_e32 v96, v96, v97
	v_add_f32_e32 v98, v98, v96
	v_mul_f32_e32 v96, v227, v227
	v_mul_f32_e32 v97, v229, v229
	v_fmac_f32_e32 v96, v226, v226
	v_fmac_f32_e32 v97, v228, v228
	v_add_f32_e32 v96, v96, v97
	v_add_f32_e32 v98, v98, v96
	s_nop 1
	v_add_f32_dpp v98, v98, v98 quad_perm:[1,0,3,2] row_mask:0xf bank_mask:0xf bound_ctrl:1
	s_nop 1
	v_add_f32_dpp v98, v98, v98 quad_perm:[2,3,0,1] row_mask:0xf bank_mask:0xf bound_ctrl:1
	s_nop 1
	v_add_f32_dpp v98, v98, v98 row_half_mirror row_mask:0xf bank_mask:0xf bound_ctrl:1
	s_nop 1
	v_add_f32_dpp v98, v98, v98 row_mirror row_mask:0xf bank_mask:0xf bound_ctrl:1
	v_mov_b32_e32 v96, v98
	s_nop 1
	v_permlane16_swap_b32_e32 v98, v96
	v_add_f32_e32 v98, v98, v96
	v_mov_b32_e32 v96, v98
	s_nop 1
	v_permlane32_swap_b32_e32 v98, v96
	v_add_f32_e32 v98, v98, v96
	v_fmamk_f32 v100, v98, 0x3a800000, v153
	v_rsq_f32_e32 v100, v100
	s_nop 0
	v_pk_mul_f32 v[214:215], v[214:215], v[100:101] op_sel_hi:[1,0]
	v_pk_mul_f32 v[216:217], v[216:217], v[100:101] op_sel_hi:[1,0]
	v_pk_mul_f32 v[218:219], v[218:219], v[100:101] op_sel_hi:[1,0]
	v_pk_mul_f32 v[220:221], v[220:221], v[100:101] op_sel_hi:[1,0]
	v_pk_mul_f32 v[222:223], v[222:223], v[100:101] op_sel_hi:[1,0]
	v_pk_mul_f32 v[224:225], v[224:225], v[100:101] op_sel_hi:[1,0]
	v_pk_mul_f32 v[226:227], v[226:227], v[100:101] op_sel_hi:[1,0]
	v_pk_mul_f32 v[228:229], v[228:229], v[100:101] op_sel_hi:[1,0]
	v_pk_mul_f32 v[214:215], v[0:1], v[214:215]
	v_pk_mul_f32 v[216:217], v[2:3], v[216:217]
	v_pk_mul_f32 v[218:219], v[4:5], v[218:219]
	v_pk_mul_f32 v[220:221], v[6:7], v[220:221]
	v_pk_mul_f32 v[222:223], v[8:9], v[222:223]
	v_pk_mul_f32 v[224:225], v[10:11], v[224:225]
	v_pk_mul_f32 v[226:227], v[12:13], v[226:227]
	v_pk_mul_f32 v[228:229], v[14:15], v[228:229]
	v_pk_fma_f32 v[214:215], v[128:129], v[214:215], v[112:113]
	v_pk_fma_f32 v[216:217], v[130:131], v[216:217], v[114:115]
	v_pk_fma_f32 v[218:219], v[132:133], v[218:219], v[116:117]
	v_pk_fma_f32 v[220:221], v[134:135], v[220:221], v[118:119]
	v_pk_fma_f32 v[222:223], v[136:137], v[222:223], v[120:121]
	v_pk_fma_f32 v[224:225], v[138:139], v[224:225], v[122:123]
	v_pk_fma_f32 v[226:227], v[140:141], v[226:227], v[124:125]
	v_pk_fma_f32 v[228:229], v[142:143], v[228:229], v[126:127]
	v_cvt_pk_bf16_f32 v214, v214, v215
	v_cvt_pk_bf16_f32 v215, v216, v217
	v_cvt_pk_bf16_f32 v218, v218, v219
	v_cvt_pk_bf16_f32 v219, v220, v221
	v_cvt_pk_bf16_f32 v222, v222, v223
	v_cvt_pk_bf16_f32 v223, v224, v225
	v_cvt_pk_bf16_f32 v226, v226, v227
	v_cvt_pk_bf16_f32 v227, v228, v229
	global_store_dwordx2 v102, v[214:215], s[40:41]
	global_store_dwordx2 v102, v[218:219], s[40:41] offset:512
	global_store_dwordx2 v102, v[222:223], s[40:41] offset:1024
	global_store_dwordx2 v102, v[226:227], s[40:41] offset:1536
	s_add_u32 s40, s40, 0x400000
	s_addc_u32 s41, s41, 0
	global_load_dwordx4 v[214:217], v103, s[38:39]
	global_load_dwordx4 v[218:221], v103, s[38:39] offset:1024
	global_load_dwordx4 v[222:225], v103, s[38:39] offset:2048
	global_load_dwordx4 v[226:229], v103, s[38:39] offset:3072
	s_add_u32 s38, s38, 0x800000
	s_addc_u32 s39, s39, 0
	s_waitcnt vmcnt(24)
	v_pk_add_f32 v[64:65], v[64:65], 1.0 op_sel_hi:[1,0]
	v_pk_add_f32 v[66:67], v[66:67], 1.0 op_sel_hi:[1,0]
	v_pk_add_f32 v[68:69], v[68:69], 1.0 op_sel_hi:[1,0]
	v_pk_add_f32 v[70:71], v[70:71], 1.0 op_sel_hi:[1,0]
	v_pk_add_f32 v[72:73], v[72:73], 1.0 op_sel_hi:[1,0]
	v_pk_add_f32 v[74:75], v[74:75], 1.0 op_sel_hi:[1,0]
	v_pk_add_f32 v[76:77], v[76:77], 1.0 op_sel_hi:[1,0]
	v_pk_add_f32 v[78:79], v[78:79], 1.0 op_sel_hi:[1,0]
	v_mul_f32_e32 v96, v159, v159
	v_mul_f32_e32 v97, v161, v161
	v_fmac_f32_e32 v96, v158, v158
	v_fmac_f32_e32 v97, v160, v160
	v_add_f32_e32 v98, v96, v97
	v_mul_f32_e32 v96, v163, v163
	v_mul_f32_e32 v97, v165, v165
	v_fmac_f32_e32 v96, v162, v162
	v_fmac_f32_e32 v97, v164, v164
	v_add_f32_e32 v96, v96, v97
	v_add_f32_e32 v98, v98, v96
	v_mul_f32_e32 v96, v167, v167
	v_mul_f32_e32 v97, v169, v169
	v_fmac_f32_e32 v96, v166, v166
	v_fmac_f32_e32 v97, v168, v168
	v_add_f32_e32 v96, v96, v97
	v_add_f32_e32 v98, v98, v96
	v_mul_f32_e32 v96, v171, v171
	v_mul_f32_e32 v97, v173, v173
	v_fmac_f32_e32 v96, v170, v170
	v_fmac_f32_e32 v97, v172, v172
	v_add_f32_e32 v96, v96, v97
	v_add_f32_e32 v98, v98, v96
	s_nop 1
	v_add_f32_dpp v98, v98, v98 quad_perm:[1,0,3,2] row_mask:0xf bank_mask:0xf bound_ctrl:1
	s_nop 1
	v_add_f32_dpp v98, v98, v98 quad_perm:[2,3,0,1] row_mask:0xf bank_mask:0xf bound_ctrl:1
	s_nop 1
	v_add_f32_dpp v98, v98, v98 row_half_mirror row_mask:0xf bank_mask:0xf bound_ctrl:1
	s_nop 1
	v_add_f32_dpp v98, v98, v98 row_mirror row_mask:0xf bank_mask:0xf bound_ctrl:1
	v_mov_b32_e32 v96, v98
	s_nop 1
	v_permlane16_swap_b32_e32 v98, v96
	v_add_f32_e32 v98, v98, v96
	v_mov_b32_e32 v96, v98
	s_nop 1
	v_permlane32_swap_b32_e32 v98, v96
	v_add_f32_e32 v98, v98, v96
	v_fmamk_f32 v100, v98, 0x3a800000, v153
	v_rsq_f32_e32 v100, v100
	s_nop 0
	v_pk_mul_f32 v[158:159], v[158:159], v[100:101] op_sel_hi:[1,0]
	v_pk_mul_f32 v[160:161], v[160:161], v[100:101] op_sel_hi:[1,0]
	v_pk_mul_f32 v[162:163], v[162:163], v[100:101] op_sel_hi:[1,0]
	v_pk_mul_f32 v[164:165], v[164:165], v[100:101] op_sel_hi:[1,0]
; __device__ __forceinline__ void norm_phase(const void* src_lat, int lat_f32, const float* src_ctx, int nrows, const float* gvec, const float* mods_l, int sh_off, int sc_off, bf16_t* U, const float* part, int nparts, float* ctx_out) {
;     ...
;     for (int row = gw; row < nrows; row += ngw) {
;         const int s = row < MLAT ? (row >> 13) : 4;
;         f32x4 v[4]; float ss = 0.f;
;         if (row < MLAT && !lat_f32) { const bf16_t* src = (const bf16_t*)src_lat + (size_t)row * DM + 4 * lane;
; #pragma unroll
;             for (int j = 0; j < 4; ++j) { const u32x2 w = *(const u32x2*)(src + 256 * j);
;                 v[j] = (f32x4){__uint_as_float(w.x << 16), __uint_as_float(w.x & 0xffff0000u), __uint_as_float(w.y << 16), __uint_as_float(w.y & 0xffff0000u)}; } }
;         else { const float* src = row < MLAT ? (const float*)src_lat + (size_t)row * DM : src_ctx + (size_t)(row - MLAT) * DM;
; #pragma unroll
;             for (int j = 0; j < 4; ++j) v[j] = *(const f32x4*)(src + 4 * lane + 256 * j); }
; #pragma unroll
;         for (int j = 0; j < 4; ++j) { ss += (v[j][0] * v[j][0] + v[j][1] * v[j][1]) + (v[j][2] * v[j][2] + v[j][3] * v[j][3]); }
;         if (nparts != 0 && row >= MLAT) {
;             for (int ch = 0; ch < nparts; ch += 4) {
;                 f32x4 pv[4][4];
; #pragma unroll
;                 for (int c4 = 0; c4 < 4; ++c4) { const float* pr = part + ((size_t)(ch + c4) * MCTX + (row - MLAT)) * DM + 4 * lane;
; #pragma unroll
;                     for (int j = 0; j < 4; ++j) pv[c4][j] = *(const f32x4*)(pr + 256 * j); }
; #pragma unroll
;                 for (int c4 = 0; c4 < 4; ++c4)
; #pragma unroll
;                     for (int j = 0; j < 4; ++j) v[j] = v[j] + pv[c4][j]; }
;             ss = 0.f;
; #pragma unroll
;             for (int j = 0; j < 4; ++j) { *(f32x4*)(ctx_out + (size_t)(row - MLAT) * DM + 4 * lane + 256 * j) = v[j]; ss += (v[j][0] * v[j][0] + v[j][1] * v[j][1]) + (v[j][2] * v[j][2] + v[j][3] * v[j][3]); }
;         }
;         const float rs = rsqrtf(wave_sum64(ss) * (1.0f / DM) + EPS);
;         const float* shp = mods_l + s * 6144 + sh_off + 4 * lane; const float* scp = mods_l + s * 6144 + sc_off + 4 * lane;
;         bf16_t* up = U + (size_t)row * DM + 4 * lane;
; #pragma unroll
;         for (int j = 0; j < 4; ++j) { const f32x4 sh = *(const f32x4*)(shp + 256 * j), sc = *(const f32x4*)(scp + 256 * j);
	v_pk_mul_f32 v[166:167], v[166:167], v[100:101] op_sel_hi:[1,0]
	v_pk_mul_f32 v[168:169], v[168:169], v[100:101] op_sel_hi:[1,0]
	v_pk_mul_f32 v[170:171], v[170:171], v[100:101] op_sel_hi:[1,0]
	v_pk_mul_f32 v[172:173], v[172:173], v[100:101] op_sel_hi:[1,0]
	v_pk_mul_f32 v[158:159], v[0:1], v[158:159]
	v_pk_mul_f32 v[160:161], v[2:3], v[160:161]
	v_pk_mul_f32 v[162:163], v[4:5], v[162:163]
	v_pk_mul_f32 v[164:165], v[6:7], v[164:165]
	v_pk_mul_f32 v[166:167], v[8:9], v[166:167]
	v_pk_mul_f32 v[168:169], v[10:11], v[168:169]
	v_pk_mul_f32 v[170:171], v[12:13], v[170:171]
	v_pk_mul_f32 v[172:173], v[14:15], v[172:173]
	v_pk_fma_f32 v[158:159], v[64:65], v[158:159], v[48:49]
	v_pk_fma_f32 v[160:161], v[66:67], v[160:161], v[50:51]
	v_pk_fma_f32 v[162:163], v[68:69], v[162:163], v[52:53]
	v_pk_fma_f32 v[164:165], v[70:71], v[164:165], v[54:55]
	v_pk_fma_f32 v[166:167], v[72:73], v[166:167], v[56:57]
	v_pk_fma_f32 v[168:169], v[74:75], v[168:169], v[58:59]
	v_pk_fma_f32 v[170:171], v[76:77], v[170:171], v[60:61]
	v_pk_fma_f32 v[172:173], v[78:79], v[172:173], v[62:63]
	v_cvt_pk_bf16_f32 v158, v158, v159
	v_cvt_pk_bf16_f32 v159, v160, v161
	v_cvt_pk_bf16_f32 v162, v162, v163
	v_cvt_pk_bf16_f32 v163, v164, v165
	v_cvt_pk_bf16_f32 v166, v166, v167
	v_cvt_pk_bf16_f32 v167, v168, v169
	v_cvt_pk_bf16_f32 v170, v170, v171
	v_cvt_pk_bf16_f32 v171, v172, v173
	global_store_dwordx2 v102, v[158:159], s[40:41]
	global_store_dwordx2 v102, v[162:163], s[40:41] offset:512
	global_store_dwordx2 v102, v[166:167], s[40:41] offset:1024
	global_store_dwordx2 v102, v[170:171], s[40:41] offset:1536
	s_add_u32 s40, s40, 0x400000
	s_addc_u32 s41, s41, 0
	global_load_dwordx4 v[158:161], v103, s[38:39]
	global_load_dwordx4 v[162:165], v103, s[38:39] offset:1024
	global_load_dwordx4 v[166:169], v103, s[38:39] offset:2048
	global_load_dwordx4 v[170:173], v103, s[38:39] offset:3072
	s_add_u32 s38, s38, 0x800000
	s_addc_u32 s39, s39, 0
	global_load_dwordx4 v[112:115], v103, s[42:43]
	global_load_dwordx4 v[116:119], v103, s[42:43] offset:1024
	global_load_dwordx4 v[120:123], v103, s[42:43] offset:2048
	global_load_dwordx4 v[124:127], v103, s[42:43] offset:3072
	global_load_dwordx4 v[128:131], v103, s[44:45]
	global_load_dwordx4 v[132:135], v103, s[44:45] offset:1024
	global_load_dwordx4 v[136:139], v103, s[44:45] offset:2048
	global_load_dwordx4 v[140:143], v103, s[44:45] offset:3072
	s_add_u32 s42, s42, 0x6000
	s_addc_u32 s43, s43, 0
	s_add_u32 s44, s44, 0x6000
	s_addc_u32 s45, s45, 0
	s_waitcnt vmcnt(32)
	v_mul_f32_e32 v96, v175, v175
	v_mul_f32_e32 v97, v177, v177
	v_fmac_f32_e32 v96, v174, v174
	v_fmac_f32_e32 v97, v176, v176
	v_add_f32_e32 v98, v96, v97
	v_mul_f32_e32 v96, v179, v179
	v_mul_f32_e32 v97, v181, v181
	v_fmac_f32_e32 v96, v178, v178
	v_fmac_f32_e32 v97, v180, v180
	v_add_f32_e32 v96, v96, v97
	v_add_f32_e32 v98, v98, v96
	v_mul_f32_e32 v96, v183, v183
	v_mul_f32_e32 v97, v185, v185
	v_fmac_f32_e32 v96, v182, v182
	v_fmac_f32_e32 v97, v184, v184
	v_add_f32_e32 v96, v96, v97
	v_add_f32_e32 v98, v98, v96
	v_mul_f32_e32 v96, v187, v187
	v_mul_f32_e32 v97, v189, v189
	v_fmac_f32_e32 v96, v186, v186
	v_fmac_f32_e32 v97, v188, v188
	v_add_f32_e32 v96, v96, v97
	v_add_f32_e32 v98, v98, v96
	s_nop 1
	v_add_f32_dpp v98, v98, v98 quad_perm:[1,0,3,2] row_mask:0xf bank_mask:0xf bound_ctrl:1
	s_nop 1
	v_add_f32_dpp v98, v98, v98 quad_perm:[2,3,0,1] row_mask:0xf bank_mask:0xf bound_ctrl:1
	s_nop 1
	v_add_f32_dpp v98, v98, v98 row_half_mirror row_mask:0xf bank_mask:0xf bound_ctrl:1
	s_nop 1
	v_add_f32_dpp v98, v98, v98 row_mirror row_mask:0xf bank_mask:0xf bound_ctrl:1
	v_mov_b32_e32 v96, v98
	s_nop 1
	v_permlane16_swap_b32_e32 v98, v96
	v_add_f32_e32 v98, v98, v96
	v_mov_b32_e32 v96, v98
	s_nop 1
	v_permlane32_swap_b32_e32 v98, v96
	v_add_f32_e32 v98, v98, v96
	v_fmamk_f32 v100, v98, 0x3a800000, v153
	v_rsq_f32_e32 v100, v100
	s_nop 0
	v_pk_mul_f32 v[174:175], v[174:175], v[100:101] op_sel_hi:[1,0]
	v_pk_mul_f32 v[176:177], v[176:177], v[100:101] op_sel_hi:[1,0]
	v_pk_mul_f32 v[178:179], v[178:179], v[100:101] op_sel_hi:[1,0]
	v_pk_mul_f32 v[180:181], v[180:181], v[100:101] op_sel_hi:[1,0]
	v_pk_mul_f32 v[182:183], v[182:183], v[100:101] op_sel_hi:[1,0]
	v_pk_mul_f32 v[184:185], v[184:185], v[100:101] op_sel_hi:[1,0]
	v_pk_mul_f32 v[186:187], v[186:187], v[100:101] op_sel_hi:[1,0]
	v_pk_mul_f32 v[188:189], v[188:189], v[100:101] op_sel_hi:[1,0]
	v_pk_mul_f32 v[174:175], v[0:1], v[174:175]
	v_pk_mul_f32 v[176:177], v[2:3], v[176:177]
	v_pk_mul_f32 v[178:179], v[4:5], v[178:179]
	v_pk_mul_f32 v[180:181], v[6:7], v[180:181]
	v_pk_mul_f32 v[182:183], v[8:9], v[182:183]
	v_pk_mul_f32 v[184:185], v[10:11], v[184:185]
	v_pk_mul_f32 v[186:187], v[12:13], v[186:187]
	v_pk_mul_f32 v[188:189], v[14:15], v[188:189]
	v_pk_fma_f32 v[174:175], v[64:65], v[174:175], v[48:49]
	v_pk_fma_f32 v[176:177], v[66:67], v[176:177], v[50:51]
	v_pk_fma_f32 v[178:179], v[68:69], v[178:179], v[52:53]
	v_pk_fma_f32 v[180:181], v[70:71], v[180:181], v[54:55]
	v_pk_fma_f32 v[182:183], v[72:73], v[182:183], v[56:57]
	v_pk_fma_f32 v[184:185], v[74:75], v[184:185], v[58:59]
	v_pk_fma_f32 v[186:187], v[76:77], v[186:187], v[60:61]
	v_pk_fma_f32 v[188:189], v[78:79], v[188:189], v[62:63]
	v_cvt_pk_bf16_f32 v174, v174, v175
	v_cvt_pk_bf16_f32 v175, v176, v177
	v_cvt_pk_bf16_f32 v178, v178, v179
	v_cvt_pk_bf16_f32 v179, v180, v181
	v_cvt_pk_bf16_f32 v182, v182, v183
	v_cvt_pk_bf16_f32 v183, v184, v185
	v_cvt_pk_bf16_f32 v186, v186, v187
	v_cvt_pk_bf16_f32 v187, v188, v189
	global_store_dwordx2 v102, v[174:175], s[40:41]
	global_store_dwordx2 v102, v[178:179], s[40:41] offset:512
	global_store_dwordx2 v102, v[182:183], s[40:41] offset:1024
	global_store_dwordx2 v102, v[186:187], s[40:41] offset:1536
	s_add_u32 s40, s40, 0x400000
	s_addc_u32 s41, s41, 0
	global_load_dwordx4 v[174:177], v103, s[38:39]
	global_load_dwordx4 v[178:181], v103, s[38:39] offset:1024
	global_load_dwordx4 v[182:185], v103, s[38:39] offset:2048
	global_load_dwordx4 v[186:189], v103, s[38:39] offset:3072
	s_add_u32 s38, s38, 0x800000
	s_addc_u32 s39, s39, 0
	s_waitcnt vmcnt(32)
; __device__ __forceinline__ void norm_phase(const void* src_lat, int lat_f32, const float* src_ctx, int nrows, const float* gvec, const float* mods_l, int sh_off, int sc_off, bf16_t* U, const float* part, int nparts, float* ctx_out) {
;     ...
;     for (int row = gw; row < nrows; row += ngw) {
;         const int s = row < MLAT ? (row >> 13) : 4;
;         f32x4 v[4]; float ss = 0.f;
;         if (row < MLAT && !lat_f32) { const bf16_t* src = (const bf16_t*)src_lat + (size_t)row * DM + 4 * lane;
; #pragma unroll
;             for (int j = 0; j < 4; ++j) { const u32x2 w = *(const u32x2*)(src + 256 * j);
;                 v[j] = (f32x4){__uint_as_float(w.x << 16), __uint_as_float(w.x & 0xffff0000u), __uint_as_float(w.y << 16), __uint_as_float(w.y & 0xffff0000u)}; } }
;         else { const float* src = row < MLAT ? (const float*)src_lat + (size_t)row * DM : src_ctx + (size_t)(row - MLAT) * DM;
; #pragma unroll
;             for (int j = 0; j < 4; ++j) v[j] = *(const f32x4*)(src + 4 * lane + 256 * j); }
; #pragma unroll
;         for (int j = 0; j < 4; ++j) { ss += (v[j][0] * v[j][0] + v[j][1] * v[j][1]) + (v[j][2] * v[j][2] + v[j][3] * v[j][3]); }
;         if (nparts != 0 && row >= MLAT) {
;             for (int ch = 0; ch < nparts; ch += 4) {
;                 f32x4 pv[4][4];
; #pragma unroll
;                 for (int c4 = 0; c4 < 4; ++c4) { const float* pr = part + ((size_t)(ch + c4) * MCTX + (row - MLAT)) * DM + 4 * lane;
; #pragma unroll
;                     for (int j = 0; j < 4; ++j) pv[c4][j] = *(const f32x4*)(pr + 256 * j); }
; #pragma unroll
;                 for (int c4 = 0; c4 < 4; ++c4)
; #pragma unroll
;                     for (int j = 0; j < 4; ++j) v[j] = v[j] + pv[c4][j]; }
;             ss = 0.f;
; #pragma unroll
;             for (int j = 0; j < 4; ++j) { *(f32x4*)(ctx_out + (size_t)(row - MLAT) * DM + 4 * lane + 256 * j) = v[j]; ss += (v[j][0] * v[j][0] + v[j][1] * v[j][1]) + (v[j][2] * v[j][2] + v[j][3] * v[j][3]); }
;         }
;         const float rs = rsqrtf(wave_sum64(ss) * (1.0f / DM) + EPS);
;         const float* shp = mods_l + s * 6144 + sh_off + 4 * lane; const float* scp = mods_l + s * 6144 + sc_off + 4 * lane;
;         bf16_t* up = U + (size_t)row * DM + 4 * lane;
; #pragma unroll
;         for (int j = 0; j < 4; ++j) { const f32x4 sh = *(const f32x4*)(shp + 256 * j), sc = *(const f32x4*)(scp + 256 * j);
	v_mul_f32_e32 v96, v199, v199
	v_mul_f32_e32 v97, v201, v201
	v_fmac_f32_e32 v96, v198, v198
	v_fmac_f32_e32 v97, v200, v200
	v_add_f32_e32 v98, v96, v97
	v_mul_f32_e32 v96, v203, v203
	v_mul_f32_e32 v97, v205, v205
	v_fmac_f32_e32 v96, v202, v202
	v_fmac_f32_e32 v97, v204, v204
	v_add_f32_e32 v96, v96, v97
	v_add_f32_e32 v98, v98, v96
	v_mul_f32_e32 v96, v207, v207
	v_mul_f32_e32 v97, v209, v209
	v_fmac_f32_e32 v96, v206, v206
	v_fmac_f32_e32 v97, v208, v208
	v_add_f32_e32 v96, v96, v97
	v_add_f32_e32 v98, v98, v96
	v_mul_f32_e32 v96, v211, v211
	v_mul_f32_e32 v97, v213, v213
	v_fmac_f32_e32 v96, v210, v210
	v_fmac_f32_e32 v97, v212, v212
	v_add_f32_e32 v96, v96, v97
	v_add_f32_e32 v98, v98, v96
	s_nop 1
	v_add_f32_dpp v98, v98, v98 quad_perm:[1,0,3,2] row_mask:0xf bank_mask:0xf bound_ctrl:1
	s_nop 1
	v_add_f32_dpp v98, v98, v98 quad_perm:[2,3,0,1] row_mask:0xf bank_mask:0xf bound_ctrl:1
	s_nop 1
	v_add_f32_dpp v98, v98, v98 row_half_mirror row_mask:0xf bank_mask:0xf bound_ctrl:1
	s_nop 1
	v_add_f32_dpp v98, v98, v98 row_mirror row_mask:0xf bank_mask:0xf bound_ctrl:1
	v_mov_b32_e32 v96, v98
	s_nop 1
	v_permlane16_swap_b32_e32 v98, v96
	v_add_f32_e32 v98, v98, v96
	v_mov_b32_e32 v96, v98
	s_nop 1
	v_permlane32_swap_b32_e32 v98, v96
	v_add_f32_e32 v98, v98, v96
	v_fmamk_f32 v100, v98, 0x3a800000, v153
	v_rsq_f32_e32 v100, v100
	s_nop 0
	v_pk_mul_f32 v[198:199], v[198:199], v[100:101] op_sel_hi:[1,0]
	v_pk_mul_f32 v[200:201], v[200:201], v[100:101] op_sel_hi:[1,0]
	v_pk_mul_f32 v[202:203], v[202:203], v[100:101] op_sel_hi:[1,0]
	v_pk_mul_f32 v[204:205], v[204:205], v[100:101] op_sel_hi:[1,0]
	v_pk_mul_f32 v[206:207], v[206:207], v[100:101] op_sel_hi:[1,0]
	v_pk_mul_f32 v[208:209], v[208:209], v[100:101] op_sel_hi:[1,0]
	v_pk_mul_f32 v[210:211], v[210:211], v[100:101] op_sel_hi:[1,0]
	v_pk_mul_f32 v[212:213], v[212:213], v[100:101] op_sel_hi:[1,0]
	v_pk_mul_f32 v[198:199], v[0:1], v[198:199]
	v_pk_mul_f32 v[200:201], v[2:3], v[200:201]
	v_pk_mul_f32 v[202:203], v[4:5], v[202:203]
	v_pk_mul_f32 v[204:205], v[6:7], v[204:205]
	v_pk_mul_f32 v[206:207], v[8:9], v[206:207]
	v_pk_mul_f32 v[208:209], v[10:11], v[208:209]
	v_pk_mul_f32 v[210:211], v[12:13], v[210:211]
	v_pk_mul_f32 v[212:213], v[14:15], v[212:213]
	v_pk_fma_f32 v[198:199], v[64:65], v[198:199], v[48:49]
	v_pk_fma_f32 v[200:201], v[66:67], v[200:201], v[50:51]
	v_pk_fma_f32 v[202:203], v[68:69], v[202:203], v[52:53]
	v_pk_fma_f32 v[204:205], v[70:71], v[204:205], v[54:55]
	v_pk_fma_f32 v[206:207], v[72:73], v[206:207], v[56:57]
	v_pk_fma_f32 v[208:209], v[74:75], v[208:209], v[58:59]
	v_pk_fma_f32 v[210:211], v[76:77], v[210:211], v[60:61]
	v_pk_fma_f32 v[212:213], v[78:79], v[212:213], v[62:63]
	v_cvt_pk_bf16_f32 v198, v198, v199
	v_cvt_pk_bf16_f32 v199, v200, v201
	v_cvt_pk_bf16_f32 v202, v202, v203
	v_cvt_pk_bf16_f32 v203, v204, v205
	v_cvt_pk_bf16_f32 v206, v206, v207
	v_cvt_pk_bf16_f32 v207, v208, v209
	v_cvt_pk_bf16_f32 v210, v210, v211
	v_cvt_pk_bf16_f32 v211, v212, v213
	global_store_dwordx2 v102, v[198:199], s[40:41]
	global_store_dwordx2 v102, v[202:203], s[40:41] offset:512
	global_store_dwordx2 v102, v[206:207], s[40:41] offset:1024
	global_store_dwordx2 v102, v[210:211], s[40:41] offset:1536
	s_add_u32 s40, s40, 0x400000
	s_addc_u32 s41, s41, 0
	global_load_dwordx4 v[198:201], v103, s[38:39]
	global_load_dwordx4 v[202:205], v103, s[38:39] offset:1024
	global_load_dwordx4 v[206:209], v103, s[38:39] offset:2048
	global_load_dwordx4 v[210:213], v103, s[38:39] offset:3072
	s_add_u32 s38, s38, 0x800000
	s_addc_u32 s39, s39, 0
	s_waitcnt vmcnt(32)
	v_mul_f32_e32 v96, v215, v215
	v_mul_f32_e32 v97, v217, v217
	v_fmac_f32_e32 v96, v214, v214
	v_fmac_f32_e32 v97, v216, v216
	v_add_f32_e32 v98, v96, v97
	v_mul_f32_e32 v96, v219, v219
	v_mul_f32_e32 v97, v221, v221
	v_fmac_f32_e32 v96, v218, v218
	v_fmac_f32_e32 v97, v220, v220
	v_add_f32_e32 v96, v96, v97
	v_add_f32_e32 v98, v98, v96
	v_mul_f32_e32 v96, v223, v223
	v_mul_f32_e32 v97, v225, v225
	v_fmac_f32_e32 v96, v222, v222
	v_fmac_f32_e32 v97, v224, v224
	v_add_f32_e32 v96, v96, v97
	v_add_f32_e32 v98, v98, v96
	v_mul_f32_e32 v96, v227, v227
	v_mul_f32_e32 v97, v229, v229
	v_fmac_f32_e32 v96, v226, v226
	v_fmac_f32_e32 v97, v228, v228
	v_add_f32_e32 v96, v96, v97
	v_add_f32_e32 v98, v98, v96
	s_nop 1
	v_add_f32_dpp v98, v98, v98 quad_perm:[1,0,3,2] row_mask:0xf bank_mask:0xf bound_ctrl:1
	s_nop 1
	v_add_f32_dpp v98, v98, v98 quad_perm:[2,3,0,1] row_mask:0xf bank_mask:0xf bound_ctrl:1
	s_nop 1
	v_add_f32_dpp v98, v98, v98 row_half_mirror row_mask:0xf bank_mask:0xf bound_ctrl:1
	s_nop 1
	v_add_f32_dpp v98, v98, v98 row_mirror row_mask:0xf bank_mask:0xf bound_ctrl:1
	v_mov_b32_e32 v96, v98
	s_nop 1
	v_permlane16_swap_b32_e32 v98, v96
	v_add_f32_e32 v98, v98, v96
	v_mov_b32_e32 v96, v98
	s_nop 1
	v_permlane32_swap_b32_e32 v98, v96
	v_add_f32_e32 v98, v98, v96
	v_fmamk_f32 v100, v98, 0x3a800000, v153
	v_rsq_f32_e32 v100, v100
	s_nop 0
	v_pk_mul_f32 v[214:215], v[214:215], v[100:101] op_sel_hi:[1,0]
	v_pk_mul_f32 v[216:217], v[216:217], v[100:101] op_sel_hi:[1,0]
	v_pk_mul_f32 v[218:219], v[218:219], v[100:101] op_sel_hi:[1,0]
	v_pk_mul_f32 v[220:221], v[220:221], v[100:101] op_sel_hi:[1,0]
	v_pk_mul_f32 v[222:223], v[222:223], v[100:101] op_sel_hi:[1,0]
	v_pk_mul_f32 v[224:225], v[224:225], v[100:101] op_sel_hi:[1,0]
	v_pk_mul_f32 v[226:227], v[226:227], v[100:101] op_sel_hi:[1,0]
	v_pk_mul_f32 v[228:229], v[228:229], v[100:101] op_sel_hi:[1,0]
	v_pk_mul_f32 v[214:215], v[0:1], v[214:215]
	v_pk_mul_f32 v[216:217], v[2:3], v[216:217]
	v_pk_mul_f32 v[218:219], v[4:5], v[218:219]
	v_pk_mul_f32 v[220:221], v[6:7], v[220:221]
; __device__ __forceinline__ void norm_phase(const void* src_lat, int lat_f32, const float* src_ctx, int nrows, const float* gvec, const float* mods_l, int sh_off, int sc_off, bf16_t* U, const float* part, int nparts, float* ctx_out) {
;     ...
;     for (int row = gw; row < nrows; row += ngw) {
;         const int s = row < MLAT ? (row >> 13) : 4;
;         f32x4 v[4]; float ss = 0.f;
;         if (row < MLAT && !lat_f32) { const bf16_t* src = (const bf16_t*)src_lat + (size_t)row * DM + 4 * lane;
; #pragma unroll
;             for (int j = 0; j < 4; ++j) { const u32x2 w = *(const u32x2*)(src + 256 * j);
;                 v[j] = (f32x4){__uint_as_float(w.x << 16), __uint_as_float(w.x & 0xffff0000u), __uint_as_float(w.y << 16), __uint_as_float(w.y & 0xffff0000u)}; } }
;         else { const float* src = row < MLAT ? (const float*)src_lat + (size_t)row * DM : src_ctx + (size_t)(row - MLAT) * DM;
; #pragma unroll
;             for (int j = 0; j < 4; ++j) v[j] = *(const f32x4*)(src + 4 * lane + 256 * j); }
; #pragma unroll
;         for (int j = 0; j < 4; ++j) { ss += (v[j][0] * v[j][0] + v[j][1] * v[j][1]) + (v[j][2] * v[j][2] + v[j][3] * v[j][3]); }
;         if (nparts != 0 && row >= MLAT) {
;             for (int ch = 0; ch < nparts; ch += 4) {
;                 f32x4 pv[4][4];
; #pragma unroll
;                 for (int c4 = 0; c4 < 4; ++c4) { const float* pr = part + ((size_t)(ch + c4) * MCTX + (row - MLAT)) * DM + 4 * lane;
; #pragma unroll
;                     for (int j = 0; j < 4; ++j) pv[c4][j] = *(const f32x4*)(pr + 256 * j); }
; #pragma unroll
;                 for (int c4 = 0; c4 < 4; ++c4)
; #pragma unroll
;                     for (int j = 0; j < 4; ++j) v[j] = v[j] + pv[c4][j]; }
;             ss = 0.f;
; #pragma unroll
;             for (int j = 0; j < 4; ++j) { *(f32x4*)(ctx_out + (size_t)(row - MLAT) * DM + 4 * lane + 256 * j) = v[j]; ss += (v[j][0] * v[j][0] + v[j][1] * v[j][1]) + (v[j][2] * v[j][2] + v[j][3] * v[j][3]); }
;         }
;         const float rs = rsqrtf(wave_sum64(ss) * (1.0f / DM) + EPS);
;         const float* shp = mods_l + s * 6144 + sh_off + 4 * lane; const float* scp = mods_l + s * 6144 + sc_off + 4 * lane;
;         bf16_t* up = U + (size_t)row * DM + 4 * lane;
; #pragma unroll
;         for (int j = 0; j < 4; ++j) { const f32x4 sh = *(const f32x4*)(shp + 256 * j), sc = *(const f32x4*)(scp + 256 * j);
	v_pk_mul_f32 v[222:223], v[8:9], v[222:223]
	v_pk_mul_f32 v[224:225], v[10:11], v[224:225]
	v_pk_mul_f32 v[226:227], v[12:13], v[226:227]
	v_pk_mul_f32 v[228:229], v[14:15], v[228:229]
	v_pk_fma_f32 v[214:215], v[64:65], v[214:215], v[48:49]
	v_pk_fma_f32 v[216:217], v[66:67], v[216:217], v[50:51]
	v_pk_fma_f32 v[218:219], v[68:69], v[218:219], v[52:53]
	v_pk_fma_f32 v[220:221], v[70:71], v[220:221], v[54:55]
	v_pk_fma_f32 v[222:223], v[72:73], v[222:223], v[56:57]
	v_pk_fma_f32 v[224:225], v[74:75], v[224:225], v[58:59]
	v_pk_fma_f32 v[226:227], v[76:77], v[226:227], v[60:61]
	v_pk_fma_f32 v[228:229], v[78:79], v[228:229], v[62:63]
	v_cvt_pk_bf16_f32 v214, v214, v215
	v_cvt_pk_bf16_f32 v215, v216, v217
	v_cvt_pk_bf16_f32 v218, v218, v219
	v_cvt_pk_bf16_f32 v219, v220, v221
	v_cvt_pk_bf16_f32 v222, v222, v223
	v_cvt_pk_bf16_f32 v223, v224, v225
	v_cvt_pk_bf16_f32 v226, v226, v227
	v_cvt_pk_bf16_f32 v227, v228, v229
	global_store_dwordx2 v102, v[214:215], s[40:41]
	global_store_dwordx2 v102, v[218:219], s[40:41] offset:512
	global_store_dwordx2 v102, v[222:223], s[40:41] offset:1024
	global_store_dwordx2 v102, v[226:227], s[40:41] offset:1536
	s_add_u32 s40, s40, 0x400000
	s_addc_u32 s41, s41, 0
	global_load_dwordx4 v[214:217], v103, s[38:39]
	global_load_dwordx4 v[218:221], v103, s[38:39] offset:1024
	global_load_dwordx4 v[222:225], v103, s[38:39] offset:2048
	global_load_dwordx4 v[226:229], v103, s[38:39] offset:3072
	s_add_u32 s38, s38, 0x800000
	s_addc_u32 s39, s39, 0
	s_waitcnt vmcnt(24)
	v_pk_add_f32 v[128:129], v[128:129], 1.0 op_sel_hi:[1,0]
	v_pk_add_f32 v[130:131], v[130:131], 1.0 op_sel_hi:[1,0]
	v_pk_add_f32 v[132:133], v[132:133], 1.0 op_sel_hi:[1,0]
	v_pk_add_f32 v[134:135], v[134:135], 1.0 op_sel_hi:[1,0]
	v_pk_add_f32 v[136:137], v[136:137], 1.0 op_sel_hi:[1,0]
	v_pk_add_f32 v[138:139], v[138:139], 1.0 op_sel_hi:[1,0]
	v_pk_add_f32 v[140:141], v[140:141], 1.0 op_sel_hi:[1,0]
	v_pk_add_f32 v[142:143], v[142:143], 1.0 op_sel_hi:[1,0]
	v_mul_f32_e32 v96, v159, v159
	v_mul_f32_e32 v97, v161, v161
	v_fmac_f32_e32 v96, v158, v158
	v_fmac_f32_e32 v97, v160, v160
	v_add_f32_e32 v98, v96, v97
	v_mul_f32_e32 v96, v163, v163
	v_mul_f32_e32 v97, v165, v165
	v_fmac_f32_e32 v96, v162, v162
	v_fmac_f32_e32 v97, v164, v164
	v_add_f32_e32 v96, v96, v97
	v_add_f32_e32 v98, v98, v96
	v_mul_f32_e32 v96, v167, v167
	v_mul_f32_e32 v97, v169, v169
	v_fmac_f32_e32 v96, v166, v166
	v_fmac_f32_e32 v97, v168, v168
	v_add_f32_e32 v96, v96, v97
	v_add_f32_e32 v98, v98, v96
	v_mul_f32_e32 v96, v171, v171
	v_mul_f32_e32 v97, v173, v173
	v_fmac_f32_e32 v96, v170, v170
	v_fmac_f32_e32 v97, v172, v172
	v_add_f32_e32 v96, v96, v97
	v_add_f32_e32 v98, v98, v96
	s_nop 1
	v_add_f32_dpp v98, v98, v98 quad_perm:[1,0,3,2] row_mask:0xf bank_mask:0xf bound_ctrl:1
	s_nop 1
	v_add_f32_dpp v98, v98, v98 quad_perm:[2,3,0,1] row_mask:0xf bank_mask:0xf bound_ctrl:1
	s_nop 1
	v_add_f32_dpp v98, v98, v98 row_half_mirror row_mask:0xf bank_mask:0xf bound_ctrl:1
	s_nop 1
	v_add_f32_dpp v98, v98, v98 row_mirror row_mask:0xf bank_mask:0xf bound_ctrl:1
	v_mov_b32_e32 v96, v98
	s_nop 1
	v_permlane16_swap_b32_e32 v98, v96
	v_add_f32_e32 v98, v98, v96
	v_mov_b32_e32 v96, v98
	s_nop 1
	v_permlane32_swap_b32_e32 v98, v96
	v_add_f32_e32 v98, v98, v96
	v_fmamk_f32 v100, v98, 0x3a800000, v153
	v_rsq_f32_e32 v100, v100
	s_nop 0
	v_pk_mul_f32 v[158:159], v[158:159], v[100:101] op_sel_hi:[1,0]
	v_pk_mul_f32 v[160:161], v[160:161], v[100:101] op_sel_hi:[1,0]
	v_pk_mul_f32 v[162:163], v[162:163], v[100:101] op_sel_hi:[1,0]
	v_pk_mul_f32 v[164:165], v[164:165], v[100:101] op_sel_hi:[1,0]
	v_pk_mul_f32 v[166:167], v[166:167], v[100:101] op_sel_hi:[1,0]
	v_pk_mul_f32 v[168:169], v[168:169], v[100:101] op_sel_hi:[1,0]
	v_pk_mul_f32 v[170:171], v[170:171], v[100:101] op_sel_hi:[1,0]
	v_pk_mul_f32 v[172:173], v[172:173], v[100:101] op_sel_hi:[1,0]
	v_pk_mul_f32 v[158:159], v[0:1], v[158:159]
	v_pk_mul_f32 v[160:161], v[2:3], v[160:161]
	v_pk_mul_f32 v[162:163], v[4:5], v[162:163]
	v_pk_mul_f32 v[164:165], v[6:7], v[164:165]
	v_pk_mul_f32 v[166:167], v[8:9], v[166:167]
	v_pk_mul_f32 v[168:169], v[10:11], v[168:169]
	v_pk_mul_f32 v[170:171], v[12:13], v[170:171]
	v_pk_mul_f32 v[172:173], v[14:15], v[172:173]
	v_pk_fma_f32 v[158:159], v[128:129], v[158:159], v[112:113]
	v_pk_fma_f32 v[160:161], v[130:131], v[160:161], v[114:115]
	v_pk_fma_f32 v[162:163], v[132:133], v[162:163], v[116:117]
	v_pk_fma_f32 v[164:165], v[134:135], v[164:165], v[118:119]
	v_pk_fma_f32 v[166:167], v[136:137], v[166:167], v[120:121]
	v_pk_fma_f32 v[168:169], v[138:139], v[168:169], v[122:123]
	v_pk_fma_f32 v[170:171], v[140:141], v[170:171], v[124:125]
	v_pk_fma_f32 v[172:173], v[142:143], v[172:173], v[126:127]
	v_cvt_pk_bf16_f32 v158, v158, v159
	v_cvt_pk_bf16_f32 v159, v160, v161
	v_cvt_pk_bf16_f32 v162, v162, v163
	v_cvt_pk_bf16_f32 v163, v164, v165
	v_cvt_pk_bf16_f32 v166, v166, v167
	v_cvt_pk_bf16_f32 v167, v168, v169
	v_cvt_pk_bf16_f32 v170, v170, v171
	v_cvt_pk_bf16_f32 v171, v172, v173
	global_store_dwordx2 v102, v[158:159], s[40:41]
	global_store_dwordx2 v102, v[162:163], s[40:41] offset:512
	global_store_dwordx2 v102, v[166:167], s[40:41] offset:1024
	global_store_dwordx2 v102, v[170:171], s[40:41] offset:1536
	s_add_u32 s40, s40, 0x400000
	s_addc_u32 s41, s41, 0
	global_load_dwordx4 v[158:161], v103, s[38:39]
	global_load_dwordx4 v[162:165], v103, s[38:39] offset:1024
	global_load_dwordx4 v[166:169], v103, s[38:39] offset:2048
	global_load_dwordx4 v[170:173], v103, s[38:39] offset:3072
	s_add_u32 s38, s38, 0x800000
	s_addc_u32 s39, s39, 0
	global_load_dwordx4 v[48:51], v103, s[42:43]
	global_load_dwordx4 v[52:55], v103, s[42:43] offset:1024
	global_load_dwordx4 v[56:59], v103, s[42:43] offset:2048
	global_load_dwordx4 v[60:63], v103, s[42:43] offset:3072
	global_load_dwordx4 v[64:67], v103, s[44:45]
	global_load_dwordx4 v[68:71], v103, s[44:45] offset:1024
	global_load_dwordx4 v[72:75], v103, s[44:45] offset:2048
	global_load_dwordx4 v[76:79], v103, s[44:45] offset:3072
	s_add_u32 s42, s42, 0x6000
	s_addc_u32 s43, s43, 0
	s_add_u32 s44, s44, 0x6000
	s_addc_u32 s45, s45, 0
	s_waitcnt vmcnt(32)
; __device__ __forceinline__ void norm_phase(const void* src_lat, int lat_f32, const float* src_ctx, int nrows, const float* gvec, const float* mods_l, int sh_off, int sc_off, bf16_t* U, const float* part, int nparts, float* ctx_out) {
;     ...
;     for (int row = gw; row < nrows; row += ngw) {
;         const int s = row < MLAT ? (row >> 13) : 4;
;         f32x4 v[4]; float ss = 0.f;
;         if (row < MLAT && !lat_f32) { const bf16_t* src = (const bf16_t*)src_lat + (size_t)row * DM + 4 * lane;
; #pragma unroll
;             for (int j = 0; j < 4; ++j) { const u32x2 w = *(const u32x2*)(src + 256 * j);
;                 v[j] = (f32x4){__uint_as_float(w.x << 16), __uint_as_float(w.x & 0xffff0000u), __uint_as_float(w.y << 16), __uint_as_float(w.y & 0xffff0000u)}; } }
;         else { const float* src = row < MLAT ? (const float*)src_lat + (size_t)row * DM : src_ctx + (size_t)(row - MLAT) * DM;
; #pragma unroll
;             for (int j = 0; j < 4; ++j) v[j] = *(const f32x4*)(src + 4 * lane + 256 * j); }
; #pragma unroll
;         for (int j = 0; j < 4; ++j) { ss += (v[j][0] * v[j][0] + v[j][1] * v[j][1]) + (v[j][2] * v[j][2] + v[j][3] * v[j][3]); }
;         if (nparts != 0 && row >= MLAT) {
;             for (int ch = 0; ch < nparts; ch += 4) {
;                 f32x4 pv[4][4];
; #pragma unroll
;                 for (int c4 = 0; c4 < 4; ++c4) { const float* pr = part + ((size_t)(ch + c4) * MCTX + (row - MLAT)) * DM + 4 * lane;
; #pragma unroll
;                     for (int j = 0; j < 4; ++j) pv[c4][j] = *(const f32x4*)(pr + 256 * j); }
; #pragma unroll
;                 for (int c4 = 0; c4 < 4; ++c4)
; #pragma unroll
;                     for (int j = 0; j < 4; ++j) v[j] = v[j] + pv[c4][j]; }
;             ss = 0.f;
; #pragma unroll
;             for (int j = 0; j < 4; ++j) { *(f32x4*)(ctx_out + (size_t)(row - MLAT) * DM + 4 * lane + 256 * j) = v[j]; ss += (v[j][0] * v[j][0] + v[j][1] * v[j][1]) + (v[j][2] * v[j][2] + v[j][3] * v[j][3]); }
;         }
;         const float rs = rsqrtf(wave_sum64(ss) * (1.0f / DM) + EPS);
;         const float* shp = mods_l + s * 6144 + sh_off + 4 * lane; const float* scp = mods_l + s * 6144 + sc_off + 4 * lane;
;         bf16_t* up = U + (size_t)row * DM + 4 * lane;
; #pragma unroll
;         for (int j = 0; j < 4; ++j) { const f32x4 sh = *(const f32x4*)(shp + 256 * j), sc = *(const f32x4*)(scp + 256 * j);
	v_mul_f32_e32 v96, v175, v175
	v_mul_f32_e32 v97, v177, v177
	v_fmac_f32_e32 v96, v174, v174
	v_fmac_f32_e32 v97, v176, v176
	v_add_f32_e32 v98, v96, v97
	v_mul_f32_e32 v96, v179, v179
	v_mul_f32_e32 v97, v181, v181
	v_fmac_f32_e32 v96, v178, v178
	v_fmac_f32_e32 v97, v180, v180
	v_add_f32_e32 v96, v96, v97
	v_add_f32_e32 v98, v98, v96
	v_mul_f32_e32 v96, v183, v183
	v_mul_f32_e32 v97, v185, v185
	v_fmac_f32_e32 v96, v182, v182
	v_fmac_f32_e32 v97, v184, v184
	v_add_f32_e32 v96, v96, v97
	v_add_f32_e32 v98, v98, v96
	v_mul_f32_e32 v96, v187, v187
	v_mul_f32_e32 v97, v189, v189
	v_fmac_f32_e32 v96, v186, v186
	v_fmac_f32_e32 v97, v188, v188
	v_add_f32_e32 v96, v96, v97
	v_add_f32_e32 v98, v98, v96
	s_nop 1
	v_add_f32_dpp v98, v98, v98 quad_perm:[1,0,3,2] row_mask:0xf bank_mask:0xf bound_ctrl:1
	s_nop 1
	v_add_f32_dpp v98, v98, v98 quad_perm:[2,3,0,1] row_mask:0xf bank_mask:0xf bound_ctrl:1
	s_nop 1
	v_add_f32_dpp v98, v98, v98 row_half_mirror row_mask:0xf bank_mask:0xf bound_ctrl:1
	s_nop 1
	v_add_f32_dpp v98, v98, v98 row_mirror row_mask:0xf bank_mask:0xf bound_ctrl:1
	v_mov_b32_e32 v96, v98
	s_nop 1
	v_permlane16_swap_b32_e32 v98, v96
	v_add_f32_e32 v98, v98, v96
	v_mov_b32_e32 v96, v98
	s_nop 1
	v_permlane32_swap_b32_e32 v98, v96
	v_add_f32_e32 v98, v98, v96
	v_fmamk_f32 v100, v98, 0x3a800000, v153
	v_rsq_f32_e32 v100, v100
	s_nop 0
	v_pk_mul_f32 v[174:175], v[174:175], v[100:101] op_sel_hi:[1,0]
	v_pk_mul_f32 v[176:177], v[176:177], v[100:101] op_sel_hi:[1,0]
	v_pk_mul_f32 v[178:179], v[178:179], v[100:101] op_sel_hi:[1,0]
	v_pk_mul_f32 v[180:181], v[180:181], v[100:101] op_sel_hi:[1,0]
	v_pk_mul_f32 v[182:183], v[182:183], v[100:101] op_sel_hi:[1,0]
	v_pk_mul_f32 v[184:185], v[184:185], v[100:101] op_sel_hi:[1,0]
	v_pk_mul_f32 v[186:187], v[186:187], v[100:101] op_sel_hi:[1,0]
	v_pk_mul_f32 v[188:189], v[188:189], v[100:101] op_sel_hi:[1,0]
	v_pk_mul_f32 v[174:175], v[0:1], v[174:175]
	v_pk_mul_f32 v[176:177], v[2:3], v[176:177]
	v_pk_mul_f32 v[178:179], v[4:5], v[178:179]
	v_pk_mul_f32 v[180:181], v[6:7], v[180:181]
	v_pk_mul_f32 v[182:183], v[8:9], v[182:183]
	v_pk_mul_f32 v[184:185], v[10:11], v[184:185]
	v_pk_mul_f32 v[186:187], v[12:13], v[186:187]
	v_pk_mul_f32 v[188:189], v[14:15], v[188:189]
	v_pk_fma_f32 v[174:175], v[128:129], v[174:175], v[112:113]
	v_pk_fma_f32 v[176:177], v[130:131], v[176:177], v[114:115]
	v_pk_fma_f32 v[178:179], v[132:133], v[178:179], v[116:117]
	v_pk_fma_f32 v[180:181], v[134:135], v[180:181], v[118:119]
	v_pk_fma_f32 v[182:183], v[136:137], v[182:183], v[120:121]
	v_pk_fma_f32 v[184:185], v[138:139], v[184:185], v[122:123]
	v_pk_fma_f32 v[186:187], v[140:141], v[186:187], v[124:125]
	v_pk_fma_f32 v[188:189], v[142:143], v[188:189], v[126:127]
	v_cvt_pk_bf16_f32 v174, v174, v175
	v_cvt_pk_bf16_f32 v175, v176, v177
	v_cvt_pk_bf16_f32 v178, v178, v179
	v_cvt_pk_bf16_f32 v179, v180, v181
	v_cvt_pk_bf16_f32 v182, v182, v183
	v_cvt_pk_bf16_f32 v183, v184, v185
	v_cvt_pk_bf16_f32 v186, v186, v187
	v_cvt_pk_bf16_f32 v187, v188, v189
	global_store_dwordx2 v102, v[174:175], s[40:41]
	global_store_dwordx2 v102, v[178:179], s[40:41] offset:512
	global_store_dwordx2 v102, v[182:183], s[40:41] offset:1024
	global_store_dwordx2 v102, v[186:187], s[40:41] offset:1536
	s_add_u32 s40, s40, 0x400000
	s_addc_u32 s41, s41, 0
	global_load_dwordx4 v[174:177], v103, s[38:39]
	global_load_dwordx4 v[178:181], v103, s[38:39] offset:1024
	global_load_dwordx4 v[182:185], v103, s[38:39] offset:2048
	global_load_dwordx4 v[186:189], v103, s[38:39] offset:3072
	s_add_u32 s38, s38, 0x800000
	s_addc_u32 s39, s39, 0
	s_waitcnt vmcnt(32)
	v_mul_f32_e32 v96, v199, v199
	v_mul_f32_e32 v97, v201, v201
	v_fmac_f32_e32 v96, v198, v198
	v_fmac_f32_e32 v97, v200, v200
	v_add_f32_e32 v98, v96, v97
	v_mul_f32_e32 v96, v203, v203
	v_mul_f32_e32 v97, v205, v205
	v_fmac_f32_e32 v96, v202, v202
	v_fmac_f32_e32 v97, v204, v204
	v_add_f32_e32 v96, v96, v97
	v_add_f32_e32 v98, v98, v96
	v_mul_f32_e32 v96, v207, v207
	v_mul_f32_e32 v97, v209, v209
	v_fmac_f32_e32 v96, v206, v206
	v_fmac_f32_e32 v97, v208, v208
	v_add_f32_e32 v96, v96, v97
	v_add_f32_e32 v98, v98, v96
	v_mul_f32_e32 v96, v211, v211
	v_mul_f32_e32 v97, v213, v213
	v_fmac_f32_e32 v96, v210, v210
	v_fmac_f32_e32 v97, v212, v212
	v_add_f32_e32 v96, v96, v97
	v_add_f32_e32 v98, v98, v96
	s_nop 1
	v_add_f32_dpp v98, v98, v98 quad_perm:[1,0,3,2] row_mask:0xf bank_mask:0xf bound_ctrl:1
	s_nop 1
	v_add_f32_dpp v98, v98, v98 quad_perm:[2,3,0,1] row_mask:0xf bank_mask:0xf bound_ctrl:1
	s_nop 1
	v_add_f32_dpp v98, v98, v98 row_half_mirror row_mask:0xf bank_mask:0xf bound_ctrl:1
	s_nop 1
	v_add_f32_dpp v98, v98, v98 row_mirror row_mask:0xf bank_mask:0xf bound_ctrl:1
	v_mov_b32_e32 v96, v98
	s_nop 1
	v_permlane16_swap_b32_e32 v98, v96
	v_add_f32_e32 v98, v98, v96
	v_mov_b32_e32 v96, v98
	s_nop 1
	v_permlane32_swap_b32_e32 v98, v96
	v_add_f32_e32 v98, v98, v96
	v_fmamk_f32 v100, v98, 0x3a800000, v153
	v_rsq_f32_e32 v100, v100
	s_nop 0
	v_pk_mul_f32 v[198:199], v[198:199], v[100:101] op_sel_hi:[1,0]
	v_pk_mul_f32 v[200:201], v[200:201], v[100:101] op_sel_hi:[1,0]
	v_pk_mul_f32 v[202:203], v[202:203], v[100:101] op_sel_hi:[1,0]
	v_pk_mul_f32 v[204:205], v[204:205], v[100:101] op_sel_hi:[1,0]
	v_pk_mul_f32 v[206:207], v[206:207], v[100:101] op_sel_hi:[1,0]
	v_pk_mul_f32 v[208:209], v[208:209], v[100:101] op_sel_hi:[1,0]
	v_pk_mul_f32 v[210:211], v[210:211], v[100:101] op_sel_hi:[1,0]
	v_pk_mul_f32 v[212:213], v[212:213], v[100:101] op_sel_hi:[1,0]
	v_pk_mul_f32 v[198:199], v[0:1], v[198:199]
	v_pk_mul_f32 v[200:201], v[2:3], v[200:201]
	v_pk_mul_f32 v[202:203], v[4:5], v[202:203]
; __device__ __forceinline__ void norm_phase(const void* src_lat, int lat_f32, const float* src_ctx, int nrows, const float* gvec, const float* mods_l, int sh_off, int sc_off, bf16_t* U, const float* part, int nparts, float* ctx_out) {
;     ...
;     for (int row = gw; row < nrows; row += ngw) {
;         const int s = row < MLAT ? (row >> 13) : 4;
;         f32x4 v[4]; float ss = 0.f;
;         if (row < MLAT && !lat_f32) { const bf16_t* src = (const bf16_t*)src_lat + (size_t)row * DM + 4 * lane;
; #pragma unroll
;             for (int j = 0; j < 4; ++j) { const u32x2 w = *(const u32x2*)(src + 256 * j);
;                 v[j] = (f32x4){__uint_as_float(w.x << 16), __uint_as_float(w.x & 0xffff0000u), __uint_as_float(w.y << 16), __uint_as_float(w.y & 0xffff0000u)}; } }
;         else { const float* src = row < MLAT ? (const float*)src_lat + (size_t)row * DM : src_ctx + (size_t)(row - MLAT) * DM;
; #pragma unroll
;             for (int j = 0; j < 4; ++j) v[j] = *(const f32x4*)(src + 4 * lane + 256 * j); }
; #pragma unroll
;         for (int j = 0; j < 4; ++j) { ss += (v[j][0] * v[j][0] + v[j][1] * v[j][1]) + (v[j][2] * v[j][2] + v[j][3] * v[j][3]); }
;         if (nparts != 0 && row >= MLAT) {
;             for (int ch = 0; ch < nparts; ch += 4) {
;                 f32x4 pv[4][4];
; #pragma unroll
;                 for (int c4 = 0; c4 < 4; ++c4) { const float* pr = part + ((size_t)(ch + c4) * MCTX + (row - MLAT)) * DM + 4 * lane;
; #pragma unroll
;                     for (int j = 0; j < 4; ++j) pv[c4][j] = *(const f32x4*)(pr + 256 * j); }
; #pragma unroll
;                 for (int c4 = 0; c4 < 4; ++c4)
; #pragma unroll
;                     for (int j = 0; j < 4; ++j) v[j] = v[j] + pv[c4][j]; }
;             ss = 0.f;
; #pragma unroll
;             for (int j = 0; j < 4; ++j) { *(f32x4*)(ctx_out + (size_t)(row - MLAT) * DM + 4 * lane + 256 * j) = v[j]; ss += (v[j][0] * v[j][0] + v[j][1] * v[j][1]) + (v[j][2] * v[j][2] + v[j][3] * v[j][3]); }
;         }
;         const float rs = rsqrtf(wave_sum64(ss) * (1.0f / DM) + EPS);
;         const float* shp = mods_l + s * 6144 + sh_off + 4 * lane; const float* scp = mods_l + s * 6144 + sc_off + 4 * lane;
;         bf16_t* up = U + (size_t)row * DM + 4 * lane;
; #pragma unroll
;         for (int j = 0; j < 4; ++j) { const f32x4 sh = *(const f32x4*)(shp + 256 * j), sc = *(const f32x4*)(scp + 256 * j);
	v_pk_mul_f32 v[204:205], v[6:7], v[204:205]
	v_pk_mul_f32 v[206:207], v[8:9], v[206:207]
	v_pk_mul_f32 v[208:209], v[10:11], v[208:209]
	v_pk_mul_f32 v[210:211], v[12:13], v[210:211]
	v_pk_mul_f32 v[212:213], v[14:15], v[212:213]
	v_pk_fma_f32 v[198:199], v[128:129], v[198:199], v[112:113]
	v_pk_fma_f32 v[200:201], v[130:131], v[200:201], v[114:115]
	v_pk_fma_f32 v[202:203], v[132:133], v[202:203], v[116:117]
	v_pk_fma_f32 v[204:205], v[134:135], v[204:205], v[118:119]
	v_pk_fma_f32 v[206:207], v[136:137], v[206:207], v[120:121]
	v_pk_fma_f32 v[208:209], v[138:139], v[208:209], v[122:123]
	v_pk_fma_f32 v[210:211], v[140:141], v[210:211], v[124:125]
	v_pk_fma_f32 v[212:213], v[142:143], v[212:213], v[126:127]
	v_cvt_pk_bf16_f32 v198, v198, v199
	v_cvt_pk_bf16_f32 v199, v200, v201
	v_cvt_pk_bf16_f32 v202, v202, v203
	v_cvt_pk_bf16_f32 v203, v204, v205
	v_cvt_pk_bf16_f32 v206, v206, v207
	v_cvt_pk_bf16_f32 v207, v208, v209
	v_cvt_pk_bf16_f32 v210, v210, v211
	v_cvt_pk_bf16_f32 v211, v212, v213
	global_store_dwordx2 v102, v[198:199], s[40:41]
	global_store_dwordx2 v102, v[202:203], s[40:41] offset:512
	global_store_dwordx2 v102, v[206:207], s[40:41] offset:1024
	global_store_dwordx2 v102, v[210:211], s[40:41] offset:1536
	s_add_u32 s40, s40, 0x400000
	s_addc_u32 s41, s41, 0
	global_load_dwordx4 v[198:201], v103, s[38:39]
	global_load_dwordx4 v[202:205], v103, s[38:39] offset:1024
	global_load_dwordx4 v[206:209], v103, s[38:39] offset:2048
	global_load_dwordx4 v[210:213], v103, s[38:39] offset:3072
	s_add_u32 s38, s38, 0x800000
	s_addc_u32 s39, s39, 0
	s_waitcnt vmcnt(32)
	v_mul_f32_e32 v96, v215, v215
	v_mul_f32_e32 v97, v217, v217
	v_fmac_f32_e32 v96, v214, v214
	v_fmac_f32_e32 v97, v216, v216
	v_add_f32_e32 v98, v96, v97
	v_mul_f32_e32 v96, v219, v219
	v_mul_f32_e32 v97, v221, v221
	v_fmac_f32_e32 v96, v218, v218
	v_fmac_f32_e32 v97, v220, v220
	v_add_f32_e32 v96, v96, v97
	v_add_f32_e32 v98, v98, v96
	v_mul_f32_e32 v96, v223, v223
	v_mul_f32_e32 v97, v225, v225
	v_fmac_f32_e32 v96, v222, v222
	v_fmac_f32_e32 v97, v224, v224
	v_add_f32_e32 v96, v96, v97
	v_add_f32_e32 v98, v98, v96
	v_mul_f32_e32 v96, v227, v227
	v_mul_f32_e32 v97, v229, v229
	v_fmac_f32_e32 v96, v226, v226
	v_fmac_f32_e32 v97, v228, v228
	v_add_f32_e32 v96, v96, v97
	v_add_f32_e32 v98, v98, v96
	s_nop 1
	v_add_f32_dpp v98, v98, v98 quad_perm:[1,0,3,2] row_mask:0xf bank_mask:0xf bound_ctrl:1
	s_nop 1
	v_add_f32_dpp v98, v98, v98 quad_perm:[2,3,0,1] row_mask:0xf bank_mask:0xf bound_ctrl:1
	s_nop 1
	v_add_f32_dpp v98, v98, v98 row_half_mirror row_mask:0xf bank_mask:0xf bound_ctrl:1
	s_nop 1
	v_add_f32_dpp v98, v98, v98 row_mirror row_mask:0xf bank_mask:0xf bound_ctrl:1
	v_mov_b32_e32 v96, v98
	s_nop 1
	v_permlane16_swap_b32_e32 v98, v96
	v_add_f32_e32 v98, v98, v96
	v_mov_b32_e32 v96, v98
	s_nop 1
	v_permlane32_swap_b32_e32 v98, v96
	v_add_f32_e32 v98, v98, v96
	v_fmamk_f32 v100, v98, 0x3a800000, v153
	v_rsq_f32_e32 v100, v100
	s_nop 0
	v_pk_mul_f32 v[214:215], v[214:215], v[100:101] op_sel_hi:[1,0]
	v_pk_mul_f32 v[216:217], v[216:217], v[100:101] op_sel_hi:[1,0]
	v_pk_mul_f32 v[218:219], v[218:219], v[100:101] op_sel_hi:[1,0]
	v_pk_mul_f32 v[220:221], v[220:221], v[100:101] op_sel_hi:[1,0]
	v_pk_mul_f32 v[222:223], v[222:223], v[100:101] op_sel_hi:[1,0]
	v_pk_mul_f32 v[224:225], v[224:225], v[100:101] op_sel_hi:[1,0]
	v_pk_mul_f32 v[226:227], v[226:227], v[100:101] op_sel_hi:[1,0]
	v_pk_mul_f32 v[228:229], v[228:229], v[100:101] op_sel_hi:[1,0]
	v_pk_mul_f32 v[214:215], v[0:1], v[214:215]
	v_pk_mul_f32 v[216:217], v[2:3], v[216:217]
	v_pk_mul_f32 v[218:219], v[4:5], v[218:219]
	v_pk_mul_f32 v[220:221], v[6:7], v[220:221]
	v_pk_mul_f32 v[222:223], v[8:9], v[222:223]
	v_pk_mul_f32 v[224:225], v[10:11], v[224:225]
	v_pk_mul_f32 v[226:227], v[12:13], v[226:227]
	v_pk_mul_f32 v[228:229], v[14:15], v[228:229]
	v_pk_fma_f32 v[214:215], v[128:129], v[214:215], v[112:113]
	v_pk_fma_f32 v[216:217], v[130:131], v[216:217], v[114:115]
	v_pk_fma_f32 v[218:219], v[132:133], v[218:219], v[116:117]
	v_pk_fma_f32 v[220:221], v[134:135], v[220:221], v[118:119]
	v_pk_fma_f32 v[222:223], v[136:137], v[222:223], v[120:121]
	v_pk_fma_f32 v[224:225], v[138:139], v[224:225], v[122:123]
	v_pk_fma_f32 v[226:227], v[140:141], v[226:227], v[124:125]
	v_pk_fma_f32 v[228:229], v[142:143], v[228:229], v[126:127]
	v_cvt_pk_bf16_f32 v214, v214, v215
	v_cvt_pk_bf16_f32 v215, v216, v217
	v_cvt_pk_bf16_f32 v218, v218, v219
	v_cvt_pk_bf16_f32 v219, v220, v221
	v_cvt_pk_bf16_f32 v222, v222, v223
	v_cvt_pk_bf16_f32 v223, v224, v225
	v_cvt_pk_bf16_f32 v226, v226, v227
	v_cvt_pk_bf16_f32 v227, v228, v229
	global_store_dwordx2 v102, v[214:215], s[40:41]
	global_store_dwordx2 v102, v[218:219], s[40:41] offset:512
	global_store_dwordx2 v102, v[222:223], s[40:41] offset:1024
	global_store_dwordx2 v102, v[226:227], s[40:41] offset:1536
	s_add_u32 s40, s40, 0x400000
	s_addc_u32 s41, s41, 0
	global_load_dwordx4 v[214:217], v103, s[38:39]
	global_load_dwordx4 v[218:221], v103, s[38:39] offset:1024
	global_load_dwordx4 v[222:225], v103, s[38:39] offset:2048
	global_load_dwordx4 v[226:229], v103, s[38:39] offset:3072
	s_add_u32 s38, s38, 0x800000
	s_addc_u32 s39, s39, 0
	s_waitcnt vmcnt(24)
; __device__ __forceinline__ void norm_phase(const void* src_lat, int lat_f32, const float* src_ctx, int nrows, const float* gvec, const float* mods_l, int sh_off, int sc_off, bf16_t* U, const float* part, int nparts, float* ctx_out) {
;     ...
;     for (int row = gw; row < nrows; row += ngw) {
;         const int s = row < MLAT ? (row >> 13) : 4;
;         f32x4 v[4]; float ss = 0.f;
;         if (row < MLAT && !lat_f32) { const bf16_t* src = (const bf16_t*)src_lat + (size_t)row * DM + 4 * lane;
; #pragma unroll
;             for (int j = 0; j < 4; ++j) { const u32x2 w = *(const u32x2*)(src + 256 * j);
;                 v[j] = (f32x4){__uint_as_float(w.x << 16), __uint_as_float(w.x & 0xffff0000u), __uint_as_float(w.y << 16), __uint_as_float(w.y & 0xffff0000u)}; } }
;         else { const float* src = row < MLAT ? (const float*)src_lat + (size_t)row * DM : src_ctx + (size_t)(row - MLAT) * DM;
; #pragma unroll
;             for (int j = 0; j < 4; ++j) v[j] = *(const f32x4*)(src + 4 * lane + 256 * j); }
; #pragma unroll
;         for (int j = 0; j < 4; ++j) { ss += (v[j][0] * v[j][0] + v[j][1] * v[j][1]) + (v[j][2] * v[j][2] + v[j][3] * v[j][3]); }
;         if (nparts != 0 && row >= MLAT) {
;             for (int ch = 0; ch < nparts; ch += 4) {
;                 f32x4 pv[4][4];
; #pragma unroll
;                 for (int c4 = 0; c4 < 4; ++c4) { const float* pr = part + ((size_t)(ch + c4) * MCTX + (row - MLAT)) * DM + 4 * lane;
; #pragma unroll
;                     for (int j = 0; j < 4; ++j) pv[c4][j] = *(const f32x4*)(pr + 256 * j); }
; #pragma unroll
;                 for (int c4 = 0; c4 < 4; ++c4)
; #pragma unroll
;                     for (int j = 0; j < 4; ++j) v[j] = v[j] + pv[c4][j]; }
;             ss = 0.f;
; #pragma unroll
;             for (int j = 0; j < 4; ++j) { *(f32x4*)(ctx_out + (size_t)(row - MLAT) * DM + 4 * lane + 256 * j) = v[j]; ss += (v[j][0] * v[j][0] + v[j][1] * v[j][1]) + (v[j][2] * v[j][2] + v[j][3] * v[j][3]); }
;         }
;         const float rs = rsqrtf(wave_sum64(ss) * (1.0f / DM) + EPS);
;         const float* shp = mods_l + s * 6144 + sh_off + 4 * lane; const float* scp = mods_l + s * 6144 + sc_off + 4 * lane;
;         bf16_t* up = U + (size_t)row * DM + 4 * lane;
; #pragma unroll
;         for (int j = 0; j < 4; ++j) { const f32x4 sh = *(const f32x4*)(shp + 256 * j), sc = *(const f32x4*)(scp + 256 * j);
	v_pk_add_f32 v[64:65], v[64:65], 1.0 op_sel_hi:[1,0]
	v_pk_add_f32 v[66:67], v[66:67], 1.0 op_sel_hi:[1,0]
	v_pk_add_f32 v[68:69], v[68:69], 1.0 op_sel_hi:[1,0]
	v_pk_add_f32 v[70:71], v[70:71], 1.0 op_sel_hi:[1,0]
	v_pk_add_f32 v[72:73], v[72:73], 1.0 op_sel_hi:[1,0]
	v_pk_add_f32 v[74:75], v[74:75], 1.0 op_sel_hi:[1,0]
	v_pk_add_f32 v[76:77], v[76:77], 1.0 op_sel_hi:[1,0]
	v_pk_add_f32 v[78:79], v[78:79], 1.0 op_sel_hi:[1,0]
	v_mul_f32_e32 v96, v159, v159
	v_mul_f32_e32 v97, v161, v161
	v_fmac_f32_e32 v96, v158, v158
	v_fmac_f32_e32 v97, v160, v160
	v_add_f32_e32 v98, v96, v97
	v_mul_f32_e32 v96, v163, v163
	v_mul_f32_e32 v97, v165, v165
	v_fmac_f32_e32 v96, v162, v162
	v_fmac_f32_e32 v97, v164, v164
	v_add_f32_e32 v96, v96, v97
	v_add_f32_e32 v98, v98, v96
	v_mul_f32_e32 v96, v167, v167
	v_mul_f32_e32 v97, v169, v169
	v_fmac_f32_e32 v96, v166, v166
	v_fmac_f32_e32 v97, v168, v168
	v_add_f32_e32 v96, v96, v97
	v_add_f32_e32 v98, v98, v96
	v_mul_f32_e32 v96, v171, v171
	v_mul_f32_e32 v97, v173, v173
	v_fmac_f32_e32 v96, v170, v170
	v_fmac_f32_e32 v97, v172, v172
	v_add_f32_e32 v96, v96, v97
	v_add_f32_e32 v98, v98, v96
	s_nop 1
	v_add_f32_dpp v98, v98, v98 quad_perm:[1,0,3,2] row_mask:0xf bank_mask:0xf bound_ctrl:1
	s_nop 1
	v_add_f32_dpp v98, v98, v98 quad_perm:[2,3,0,1] row_mask:0xf bank_mask:0xf bound_ctrl:1
	s_nop 1
	v_add_f32_dpp v98, v98, v98 row_half_mirror row_mask:0xf bank_mask:0xf bound_ctrl:1
	s_nop 1
	v_add_f32_dpp v98, v98, v98 row_mirror row_mask:0xf bank_mask:0xf bound_ctrl:1
	v_mov_b32_e32 v96, v98
	s_nop 1
	v_permlane16_swap_b32_e32 v98, v96
	v_add_f32_e32 v98, v98, v96
	v_mov_b32_e32 v96, v98
	s_nop 1
	v_permlane32_swap_b32_e32 v98, v96
	v_add_f32_e32 v98, v98, v96
	v_fmamk_f32 v100, v98, 0x3a800000, v153
	v_rsq_f32_e32 v100, v100
	s_nop 0
	v_pk_mul_f32 v[158:159], v[158:159], v[100:101] op_sel_hi:[1,0]
	v_pk_mul_f32 v[160:161], v[160:161], v[100:101] op_sel_hi:[1,0]
	v_pk_mul_f32 v[162:163], v[162:163], v[100:101] op_sel_hi:[1,0]
	v_pk_mul_f32 v[164:165], v[164:165], v[100:101] op_sel_hi:[1,0]
	v_pk_mul_f32 v[166:167], v[166:167], v[100:101] op_sel_hi:[1,0]
	v_pk_mul_f32 v[168:169], v[168:169], v[100:101] op_sel_hi:[1,0]
	v_pk_mul_f32 v[170:171], v[170:171], v[100:101] op_sel_hi:[1,0]
	v_pk_mul_f32 v[172:173], v[172:173], v[100:101] op_sel_hi:[1,0]
	v_pk_mul_f32 v[158:159], v[0:1], v[158:159]
	v_pk_mul_f32 v[160:161], v[2:3], v[160:161]
	v_pk_mul_f32 v[162:163], v[4:5], v[162:163]
	v_pk_mul_f32 v[164:165], v[6:7], v[164:165]
	v_pk_mul_f32 v[166:167], v[8:9], v[166:167]
	v_pk_mul_f32 v[168:169], v[10:11], v[168:169]
	v_pk_mul_f32 v[170:171], v[12:13], v[170:171]
	v_pk_mul_f32 v[172:173], v[14:15], v[172:173]
	v_pk_fma_f32 v[158:159], v[64:65], v[158:159], v[48:49]
	v_pk_fma_f32 v[160:161], v[66:67], v[160:161], v[50:51]
	v_pk_fma_f32 v[162:163], v[68:69], v[162:163], v[52:53]
	v_pk_fma_f32 v[164:165], v[70:71], v[164:165], v[54:55]
	v_pk_fma_f32 v[166:167], v[72:73], v[166:167], v[56:57]
	v_pk_fma_f32 v[168:169], v[74:75], v[168:169], v[58:59]
	v_pk_fma_f32 v[170:171], v[76:77], v[170:171], v[60:61]
	v_pk_fma_f32 v[172:173], v[78:79], v[172:173], v[62:63]
	v_cvt_pk_bf16_f32 v158, v158, v159
	v_cvt_pk_bf16_f32 v159, v160, v161
	v_cvt_pk_bf16_f32 v162, v162, v163
	v_cvt_pk_bf16_f32 v163, v164, v165
	v_cvt_pk_bf16_f32 v166, v166, v167
	v_cvt_pk_bf16_f32 v167, v168, v169
	v_cvt_pk_bf16_f32 v170, v170, v171
	v_cvt_pk_bf16_f32 v171, v172, v173
	global_store_dwordx2 v102, v[158:159], s[40:41]
	global_store_dwordx2 v102, v[162:163], s[40:41] offset:512
	global_store_dwordx2 v102, v[166:167], s[40:41] offset:1024
	global_store_dwordx2 v102, v[170:171], s[40:41] offset:1536
	s_add_u32 s40, s40, 0x400000
	s_addc_u32 s41, s41, 0
	s_waitcnt vmcnt(20)
	v_mul_f32_e32 v96, v175, v175
	v_mul_f32_e32 v97, v177, v177
	v_fmac_f32_e32 v96, v174, v174
	v_fmac_f32_e32 v97, v176, v176
	v_add_f32_e32 v98, v96, v97
	v_mul_f32_e32 v96, v179, v179
	v_mul_f32_e32 v97, v181, v181
	v_fmac_f32_e32 v96, v178, v178
	v_fmac_f32_e32 v97, v180, v180
	v_add_f32_e32 v96, v96, v97
	v_add_f32_e32 v98, v98, v96
	v_mul_f32_e32 v96, v183, v183
	v_mul_f32_e32 v97, v185, v185
	v_fmac_f32_e32 v96, v182, v182
	v_fmac_f32_e32 v97, v184, v184
	v_add_f32_e32 v96, v96, v97
	v_add_f32_e32 v98, v98, v96
	v_mul_f32_e32 v96, v187, v187
	v_mul_f32_e32 v97, v189, v189
	v_fmac_f32_e32 v96, v186, v186
	v_fmac_f32_e32 v97, v188, v188
	v_add_f32_e32 v96, v96, v97
	v_add_f32_e32 v98, v98, v96
	s_nop 1
	v_add_f32_dpp v98, v98, v98 quad_perm:[1,0,3,2] row_mask:0xf bank_mask:0xf bound_ctrl:1
	s_nop 1
	v_add_f32_dpp v98, v98, v98 quad_perm:[2,3,0,1] row_mask:0xf bank_mask:0xf bound_ctrl:1
	s_nop 1
	v_add_f32_dpp v98, v98, v98 row_half_mirror row_mask:0xf bank_mask:0xf bound_ctrl:1
	s_nop 1
	v_add_f32_dpp v98, v98, v98 row_mirror row_mask:0xf bank_mask:0xf bound_ctrl:1
	v_mov_b32_e32 v96, v98
	s_nop 1
	v_permlane16_swap_b32_e32 v98, v96
	v_add_f32_e32 v98, v98, v96
	v_mov_b32_e32 v96, v98
	s_nop 1
	v_permlane32_swap_b32_e32 v98, v96
	v_add_f32_e32 v98, v98, v96
	v_fmamk_f32 v100, v98, 0x3a800000, v153
	v_rsq_f32_e32 v100, v100
	s_nop 0
	v_pk_mul_f32 v[174:175], v[174:175], v[100:101] op_sel_hi:[1,0]
	v_pk_mul_f32 v[176:177], v[176:177], v[100:101] op_sel_hi:[1,0]
	v_pk_mul_f32 v[178:179], v[178:179], v[100:101] op_sel_hi:[1,0]
	v_pk_mul_f32 v[180:181], v[180:181], v[100:101] op_sel_hi:[1,0]
	v_pk_mul_f32 v[182:183], v[182:183], v[100:101] op_sel_hi:[1,0]
	v_pk_mul_f32 v[184:185], v[184:185], v[100:101] op_sel_hi:[1,0]
	v_pk_mul_f32 v[186:187], v[186:187], v[100:101] op_sel_hi:[1,0]
	v_pk_mul_f32 v[188:189], v[188:189], v[100:101] op_sel_hi:[1,0]
	v_pk_mul_f32 v[174:175], v[0:1], v[174:175]
	v_pk_mul_f32 v[176:177], v[2:3], v[176:177]
	v_pk_mul_f32 v[178:179], v[4:5], v[178:179]
	v_pk_mul_f32 v[180:181], v[6:7], v[180:181]
	v_pk_mul_f32 v[182:183], v[8:9], v[182:183]
	v_pk_mul_f32 v[184:185], v[10:11], v[184:185]
	v_pk_mul_f32 v[186:187], v[12:13], v[186:187]
	v_pk_mul_f32 v[188:189], v[14:15], v[188:189]
	v_pk_fma_f32 v[174:175], v[64:65], v[174:175], v[48:49]
	v_pk_fma_f32 v[176:177], v[66:67], v[176:177], v[50:51]
	v_pk_fma_f32 v[178:179], v[68:69], v[178:179], v[52:53]
	v_pk_fma_f32 v[180:181], v[70:71], v[180:181], v[54:55]
	v_pk_fma_f32 v[182:183], v[72:73], v[182:183], v[56:57]
	v_pk_fma_f32 v[184:185], v[74:75], v[184:185], v[58:59]
	v_pk_fma_f32 v[186:187], v[76:77], v[186:187], v[60:61]
	v_pk_fma_f32 v[188:189], v[78:79], v[188:189], v[62:63]
	v_cvt_pk_bf16_f32 v174, v174, v175
	v_cvt_pk_bf16_f32 v175, v176, v177
	v_cvt_pk_bf16_f32 v178, v178, v179
	v_cvt_pk_bf16_f32 v179, v180, v181
	v_cvt_pk_bf16_f32 v182, v182, v183
	v_cvt_pk_bf16_f32 v183, v184, v185
	v_cvt_pk_bf16_f32 v186, v186, v187
	v_cvt_pk_bf16_f32 v187, v188, v189
	global_store_dwordx2 v102, v[174:175], s[40:41]
	global_store_dwordx2 v102, v[178:179], s[40:41] offset:512
	global_store_dwordx2 v102, v[182:183], s[40:41] offset:1024
	global_store_dwordx2 v102, v[186:187], s[40:41] offset:1536
	s_add_u32 s40, s40, 0x400000
	s_addc_u32 s41, s41, 0
	s_waitcnt vmcnt(16)
; __device__ __forceinline__ void norm_phase(const void* src_lat, int lat_f32, const float* src_ctx, int nrows, const float* gvec, const float* mods_l, int sh_off, int sc_off, bf16_t* U, const float* part, int nparts, float* ctx_out) {
;     ...
;     for (int row = gw; row < nrows; row += ngw) {
;         const int s = row < MLAT ? (row >> 13) : 4;
;         f32x4 v[4]; float ss = 0.f;
;         if (row < MLAT && !lat_f32) { const bf16_t* src = (const bf16_t*)src_lat + (size_t)row * DM + 4 * lane;
; #pragma unroll
;             for (int j = 0; j < 4; ++j) { const u32x2 w = *(const u32x2*)(src + 256 * j);
;                 v[j] = (f32x4){__uint_as_float(w.x << 16), __uint_as_float(w.x & 0xffff0000u), __uint_as_float(w.y << 16), __uint_as_float(w.y & 0xffff0000u)}; } }
;         else { const float* src = row < MLAT ? (const float*)src_lat + (size_t)row * DM : src_ctx + (size_t)(row - MLAT) * DM;
; #pragma unroll
;             for (int j = 0; j < 4; ++j) v[j] = *(const f32x4*)(src + 4 * lane + 256 * j); }
; #pragma unroll
;         for (int j = 0; j < 4; ++j) { ss += (v[j][0] * v[j][0] + v[j][1] * v[j][1]) + (v[j][2] * v[j][2] + v[j][3] * v[j][3]); }
;         if (nparts != 0 && row >= MLAT) {
;             for (int ch = 0; ch < nparts; ch += 4) {
;                 f32x4 pv[4][4];
; #pragma unroll
;                 for (int c4 = 0; c4 < 4; ++c4) { const float* pr = part + ((size_t)(ch + c4) * MCTX + (row - MLAT)) * DM + 4 * lane;
; #pragma unroll
;                     for (int j = 0; j < 4; ++j) pv[c4][j] = *(const f32x4*)(pr + 256 * j); }
; #pragma unroll
;                 for (int c4 = 0; c4 < 4; ++c4)
; #pragma unroll
;                     for (int j = 0; j < 4; ++j) v[j] = v[j] + pv[c4][j]; }
;             ss = 0.f;
; #pragma unroll
;             for (int j = 0; j < 4; ++j) { *(f32x4*)(ctx_out + (size_t)(row - MLAT) * DM + 4 * lane + 256 * j) = v[j]; ss += (v[j][0] * v[j][0] + v[j][1] * v[j][1]) + (v[j][2] * v[j][2] + v[j][3] * v[j][3]); }
;         }
;         const float rs = rsqrtf(wave_sum64(ss) * (1.0f / DM) + EPS);
;         const float* shp = mods_l + s * 6144 + sh_off + 4 * lane; const float* scp = mods_l + s * 6144 + sc_off + 4 * lane;
;         bf16_t* up = U + (size_t)row * DM + 4 * lane;
; #pragma unroll
;         for (int j = 0; j < 4; ++j) { const f32x4 sh = *(const f32x4*)(shp + 256 * j), sc = *(const f32x4*)(scp + 256 * j);
	v_mul_f32_e32 v96, v199, v199
	v_mul_f32_e32 v97, v201, v201
	v_fmac_f32_e32 v96, v198, v198
	v_fmac_f32_e32 v97, v200, v200
	v_add_f32_e32 v98, v96, v97
	v_mul_f32_e32 v96, v203, v203
	v_mul_f32_e32 v97, v205, v205
	v_fmac_f32_e32 v96, v202, v202
	v_fmac_f32_e32 v97, v204, v204
	v_add_f32_e32 v96, v96, v97
	v_add_f32_e32 v98, v98, v96
	v_mul_f32_e32 v96, v207, v207
	v_mul_f32_e32 v97, v209, v209
	v_fmac_f32_e32 v96, v206, v206
	v_fmac_f32_e32 v97, v208, v208
	v_add_f32_e32 v96, v96, v97
	v_add_f32_e32 v98, v98, v96
	v_mul_f32_e32 v96, v211, v211
	v_mul_f32_e32 v97, v213, v213
	v_fmac_f32_e32 v96, v210, v210
	v_fmac_f32_e32 v97, v212, v212
	v_add_f32_e32 v96, v96, v97
	v_add_f32_e32 v98, v98, v96
	s_nop 1
	v_add_f32_dpp v98, v98, v98 quad_perm:[1,0,3,2] row_mask:0xf bank_mask:0xf bound_ctrl:1
	s_nop 1
	v_add_f32_dpp v98, v98, v98 quad_perm:[2,3,0,1] row_mask:0xf bank_mask:0xf bound_ctrl:1
	s_nop 1
	v_add_f32_dpp v98, v98, v98 row_half_mirror row_mask:0xf bank_mask:0xf bound_ctrl:1
	s_nop 1
	v_add_f32_dpp v98, v98, v98 row_mirror row_mask:0xf bank_mask:0xf bound_ctrl:1
	v_mov_b32_e32 v96, v98
	s_nop 1
	v_permlane16_swap_b32_e32 v98, v96
	v_add_f32_e32 v98, v98, v96
	v_mov_b32_e32 v96, v98
	s_nop 1
	v_permlane32_swap_b32_e32 v98, v96
	v_add_f32_e32 v98, v98, v96
	v_fmamk_f32 v100, v98, 0x3a800000, v153
	v_rsq_f32_e32 v100, v100
	s_nop 0
	v_pk_mul_f32 v[198:199], v[198:199], v[100:101] op_sel_hi:[1,0]
	v_pk_mul_f32 v[200:201], v[200:201], v[100:101] op_sel_hi:[1,0]
	v_pk_mul_f32 v[202:203], v[202:203], v[100:101] op_sel_hi:[1,0]
	v_pk_mul_f32 v[204:205], v[204:205], v[100:101] op_sel_hi:[1,0]
	v_pk_mul_f32 v[206:207], v[206:207], v[100:101] op_sel_hi:[1,0]
	v_pk_mul_f32 v[208:209], v[208:209], v[100:101] op_sel_hi:[1,0]
	v_pk_mul_f32 v[210:211], v[210:211], v[100:101] op_sel_hi:[1,0]
	v_pk_mul_f32 v[212:213], v[212:213], v[100:101] op_sel_hi:[1,0]
	v_pk_mul_f32 v[198:199], v[0:1], v[198:199]
	v_pk_mul_f32 v[200:201], v[2:3], v[200:201]
	v_pk_mul_f32 v[202:203], v[4:5], v[202:203]
	v_pk_mul_f32 v[204:205], v[6:7], v[204:205]
	v_pk_mul_f32 v[206:207], v[8:9], v[206:207]
	v_pk_mul_f32 v[208:209], v[10:11], v[208:209]
	v_pk_mul_f32 v[210:211], v[12:13], v[210:211]
	v_pk_mul_f32 v[212:213], v[14:15], v[212:213]
	v_pk_fma_f32 v[198:199], v[64:65], v[198:199], v[48:49]
	v_pk_fma_f32 v[200:201], v[66:67], v[200:201], v[50:51]
	v_pk_fma_f32 v[202:203], v[68:69], v[202:203], v[52:53]
	v_pk_fma_f32 v[204:205], v[70:71], v[204:205], v[54:55]
	v_pk_fma_f32 v[206:207], v[72:73], v[206:207], v[56:57]
	v_pk_fma_f32 v[208:209], v[74:75], v[208:209], v[58:59]
	v_pk_fma_f32 v[210:211], v[76:77], v[210:211], v[60:61]
	v_pk_fma_f32 v[212:213], v[78:79], v[212:213], v[62:63]
	v_cvt_pk_bf16_f32 v198, v198, v199
	v_cvt_pk_bf16_f32 v199, v200, v201
	v_cvt_pk_bf16_f32 v202, v202, v203
	v_cvt_pk_bf16_f32 v203, v204, v205
	v_cvt_pk_bf16_f32 v206, v206, v207
	v_cvt_pk_bf16_f32 v207, v208, v209
	v_cvt_pk_bf16_f32 v210, v210, v211
	v_cvt_pk_bf16_f32 v211, v212, v213
	global_store_dwordx2 v102, v[198:199], s[40:41]
	global_store_dwordx2 v102, v[202:203], s[40:41] offset:512
	global_store_dwordx2 v102, v[206:207], s[40:41] offset:1024
	global_store_dwordx2 v102, v[210:211], s[40:41] offset:1536
	s_add_u32 s40, s40, 0x400000
	s_addc_u32 s41, s41, 0
	s_waitcnt vmcnt(12)
	v_mul_f32_e32 v96, v215, v215
	v_mul_f32_e32 v97, v217, v217
	v_fmac_f32_e32 v96, v214, v214
	v_fmac_f32_e32 v97, v216, v216
	v_add_f32_e32 v98, v96, v97
	v_mul_f32_e32 v96, v219, v219
	v_mul_f32_e32 v97, v221, v221
	v_fmac_f32_e32 v96, v218, v218
	v_fmac_f32_e32 v97, v220, v220
	v_add_f32_e32 v96, v96, v97
	v_add_f32_e32 v98, v98, v96
	v_mul_f32_e32 v96, v223, v223
	v_mul_f32_e32 v97, v225, v225
	v_fmac_f32_e32 v96, v222, v222
	v_fmac_f32_e32 v97, v224, v224
	v_add_f32_e32 v96, v96, v97
	v_add_f32_e32 v98, v98, v96
	v_mul_f32_e32 v96, v227, v227
	v_mul_f32_e32 v97, v229, v229
	v_fmac_f32_e32 v96, v226, v226
	v_fmac_f32_e32 v97, v228, v228
	v_add_f32_e32 v96, v96, v97
	v_add_f32_e32 v98, v98, v96
	s_nop 1
	v_add_f32_dpp v98, v98, v98 quad_perm:[1,0,3,2] row_mask:0xf bank_mask:0xf bound_ctrl:1
	s_nop 1
	v_add_f32_dpp v98, v98, v98 quad_perm:[2,3,0,1] row_mask:0xf bank_mask:0xf bound_ctrl:1
	s_nop 1
	v_add_f32_dpp v98, v98, v98 row_half_mirror row_mask:0xf bank_mask:0xf bound_ctrl:1
	s_nop 1
	v_add_f32_dpp v98, v98, v98 row_mirror row_mask:0xf bank_mask:0xf bound_ctrl:1
	v_mov_b32_e32 v96, v98
	s_nop 1
	v_permlane16_swap_b32_e32 v98, v96
	v_add_f32_e32 v98, v98, v96
	v_mov_b32_e32 v96, v98
	s_nop 1
	v_permlane32_swap_b32_e32 v98, v96
	v_add_f32_e32 v98, v98, v96
	v_fmamk_f32 v100, v98, 0x3a800000, v153
	v_rsq_f32_e32 v100, v100
	s_nop 0
	v_pk_mul_f32 v[214:215], v[214:215], v[100:101] op_sel_hi:[1,0]
	v_pk_mul_f32 v[216:217], v[216:217], v[100:101] op_sel_hi:[1,0]
	v_pk_mul_f32 v[218:219], v[218:219], v[100:101] op_sel_hi:[1,0]
	v_pk_mul_f32 v[220:221], v[220:221], v[100:101] op_sel_hi:[1,0]
	v_pk_mul_f32 v[222:223], v[222:223], v[100:101] op_sel_hi:[1,0]
	v_pk_mul_f32 v[224:225], v[224:225], v[100:101] op_sel_hi:[1,0]
	v_pk_mul_f32 v[226:227], v[226:227], v[100:101] op_sel_hi:[1,0]
	v_pk_mul_f32 v[228:229], v[228:229], v[100:101] op_sel_hi:[1,0]
	v_pk_mul_f32 v[214:215], v[0:1], v[214:215]
	v_pk_mul_f32 v[216:217], v[2:3], v[216:217]
	v_pk_mul_f32 v[218:219], v[4:5], v[218:219]
	v_pk_mul_f32 v[220:221], v[6:7], v[220:221]
	v_pk_mul_f32 v[222:223], v[8:9], v[222:223]
	v_pk_mul_f32 v[224:225], v[10:11], v[224:225]
	v_pk_mul_f32 v[226:227], v[12:13], v[226:227]
	v_pk_mul_f32 v[228:229], v[14:15], v[228:229]
	v_pk_fma_f32 v[214:215], v[64:65], v[214:215], v[48:49]
	v_pk_fma_f32 v[216:217], v[66:67], v[216:217], v[50:51]
	v_pk_fma_f32 v[218:219], v[68:69], v[218:219], v[52:53]
	v_pk_fma_f32 v[220:221], v[70:71], v[220:221], v[54:55]
	v_pk_fma_f32 v[222:223], v[72:73], v[222:223], v[56:57]
	v_pk_fma_f32 v[224:225], v[74:75], v[224:225], v[58:59]
	v_pk_fma_f32 v[226:227], v[76:77], v[226:227], v[60:61]
	v_pk_fma_f32 v[228:229], v[78:79], v[228:229], v[62:63]
	v_cvt_pk_bf16_f32 v214, v214, v215
	v_cvt_pk_bf16_f32 v215, v216, v217
	v_cvt_pk_bf16_f32 v218, v218, v219
	v_cvt_pk_bf16_f32 v219, v220, v221
	v_cvt_pk_bf16_f32 v222, v222, v223
	v_cvt_pk_bf16_f32 v223, v224, v225
	v_cvt_pk_bf16_f32 v226, v226, v227
	v_cvt_pk_bf16_f32 v227, v228, v229
	global_store_dwordx2 v102, v[214:215], s[40:41]
	global_store_dwordx2 v102, v[218:219], s[40:41] offset:512
	global_store_dwordx2 v102, v[222:223], s[40:41] offset:1024
	global_store_dwordx2 v102, v[226:227], s[40:41] offset:1536
	s_add_u32 s40, s40, 0x400000
	s_addc_u32 s41, s41, 0
	s_add_i32 s0, s0, 0x8000
	s_add_i32 s82, s82, 0x8000
	s_cmp_lt_i32 s0, 0x8400
	s_cbranch_scc1 .LBB0_142
	s_branch .LBB0_150

; #define LAS __attribute__((address_space(3)))
; __device__ __forceinline__ void swa_phase(LAS unsigned char* lds, const bf16_t* Q, const bf16_t* K, const bf16_t* V, bf16_t* Ob, const float* sink, float negb) {
;     int tid_ = threadIdx.x; asm volatile("" : "+v"(tid_));
;     const int tid = tid_, lane = tid & 63, w = __builtin_amdgcn_readfirstlane(tid >> 6), l15 = lane & 15, g = lane >> 4;
;     for (int it = 0;; ++it) {
;         const int item = item_of(it, SW_ITEMS, SW_ITEMS); if (item < 0) break;
;         const int b = item >> 8, kvh = (item >> 6) & 3, tb = item & 63;
;         const size_t ctx0 = (size_t)(MLAT + b * NCTX), lat0 = (size_t)(b * SEQ);
;         const int i_lo = tb == 0 ? 2 : 0, i_hi = tb == 63 ? 4 : 6;
;         const int NT = 4 + (i_hi - i_lo);
;         const DmaLane dl = dma_lane(256, kvh * 64, w, lane);
;     ...
;         dma_tile<1>(lds, K, V, SW_ROW0(0), 256, dl, w);
;         dma_tile<1>(lds + SW_BUF, K, V, SW_ROW0(1), 256, dl, w);
;         dma_tile<1>(lds + 2 * SW_BUF, K, V, SW_ROW0(2), 256, dl, w);
;         const int tq = 128 * tb + 16 * w;
; __global__ void __launch_bounds__(512, 2) fwd_megakernel(Args a) {
;     ...
;         else att::swa_phase(lds, WSP(bf16_t, WS_Q), WSP(bf16_t, WS_K), WSP(bf16_t, WS_V), WSP(bf16_t, WS_O), A->swa_sink, -WSP(const float, WS_BND)[1]);
.LBB0_340:
	s_or_b64 exec, exec, s[0:1]
	v_readlane_b32 s6, v240, 38
	v_readlane_b32 s7, v240, 39
	s_mov_b64 s[0:1], -1
	s_and_b64 vcc, exec, s[6:7]
	s_waitcnt lgkmcnt(0)
	s_barrier
	s_cbranch_vccz .LBB0_359
	v_readlane_b32 s0, v241, 45
	v_readlane_b32 s1, v241, 46
	v_readlane_b32 s98, v240, 60
	v_readlane_b32 s99, v240, 61
	v_mov_b32_e32 v120, s98
	v_mov_b32_e32 v121, s99
	v_mov_b32_e32 v4, v152
	s_mov_b32 s41, 0
	s_nop 1
	global_load_dword v186, v155, s[0:1]
	s_waitcnt vmcnt(0)
	v_xor_b32_e32 v0, 0x80000000, v186
	v_bfe_u32 v1, v4, 3, 3
	v_readfirstlane_b32 s0, v4
	v_xor_b32_e32 v3, v1, v4
	v_and_b32_e32 v7, 1, v4
	s_ashr_i32 s0, s0, 6
	v_and_or_b32 v3, v3, 6, v7
	v_lshlrev_b32_e32 v7, 9, v1
	v_bitop3_b32 v2, v1, v4, 7 bitop3:0x78
	v_lshl_or_b32 v188, s0, 12, v7
	s_lshl_b32 s38, s0, 10
	s_lshl_b32 s39, s0, 4
	v_readlane_b32 s0, v241, 37
	v_bfe_u32 v5, v4, 4, 2
	v_lshlrev_b32_e32 v189, 4, v2
	v_lshlrev_b32_e32 v190, 4, v3
	v_and_b32_e32 v2, 48, v4
	v_mov_b32_e32 v3, v155
	v_readlane_b32 s1, v241, 38
	v_and_b32_e32 v6, 7, v4
	v_bfe_u32 v8, v4, 3, 1
	v_lshl_add_u64 v[122:123], s[0:1], 0, v[2:3]
	v_bitop3_b32 v2, v5, v4, 7 bitop3:0x78
	v_lshlrev_b32_e32 v192, 4, v2
	v_bitop3_b32 v2, v5, v6, 4 bitop3:0x36
	v_and_or_b32 v9, v1, 2, v8
	v_lshlrev_b32_e32 v154, 3, v5
	v_lshlrev_b32_e32 v193, 4, v2
	v_lshlrev_b32_e32 v6, 9, v5
	v_lshlrev_b32_e32 v2, 5, v4
	v_lshlrev_b32_e32 v199, 5, v9
	v_bfe_u32 v9, v4, 2, 2
	v_lshlrev_b32_e32 v5, 2, v5
	v_and_b32_e32 v7, 0x180, v2
	v_lshlrev_b32_e32 v2, 3, v4
	v_or_b32_e32 v9, v5, v9
	v_and_b32_e32 v198, 24, v2
	v_xor_b32_e32 v202, 0x60, v199
	v_lshlrev_b32_e32 v203, 7, v9
	v_add_u32_e32 v9, 0, v6
	v_or_b32_e32 v6, v6, v7
	v_xor_b32_e32 v201, 64, v199
	v_add3_u32 v204, v9, v7, v198
	v_or3_b32 v7, v6, v202, v198
	v_and_b32_e32 v187, 15, v4
	v_xor_b32_e32 v200, 32, v199
	v_add_u32_e32 v205, 0, v7
	v_or3_b32 v7, v6, v201, v198
	v_lshlrev_b32_e32 v4, 2, v4
	v_readlane_b32 s0, v241, 43
	v_add_u32_e32 v206, 0, v7
	v_or3_b32 v7, v6, v200, v198
	v_and_or_b32 v4, v4, 64, v6
	v_lshlrev_b32_e32 v6, 5, v8
	v_lshlrev_b32_e32 v191, 7, v187
	v_readlane_b32 s1, v241, 44
	v_or3_b32 v4, v4, v6, v198
	v_add_u32_e32 v208, 0, v4
	v_lshl_add_u64 v[124:125], s[0:1], 0, v[154:155]
	v_or_b32_e32 v4, v191, v193
	s_add_i32 s0, 0, 0x4000
	v_add_u32_e32 v209, s0, v4
	v_or_b32_e32 v4, v191, v192
	v_add_u32_e32 v210, s0, v4
	v_sub_u32_e32 v4, v5, v187
	v_mov_b32_e32 v1, v0
	v_mov_b32_e32 v2, v0
	v_mov_b32_e32 v3, v0
	v_add_u32_e32 v154, 0, v191
	v_add_u32_e32 v207, 0, v7
	s_add_i32 s40, s38, 0
	v_subrev_u32_e32 v211, s39, v4
	s_branch .LBB0_343

; #define LAS __attribute__((address_space(3)))
; __device__ __forceinline__ void na_phase(LAS unsigned char* lds, const bf16_t* Q, const bf16_t* K, const bf16_t* V, bf16_t* Ob, const float* rpb, float negb) {
;     int tid_ = threadIdx.x; asm volatile("" : "+v"(tid_));
;     const int tid = tid_, lane = tid & 63, w = __builtin_amdgcn_readfirstlane(tid >> 6), l15 = lane & 15, g = lane >> 4;
;     LAS float* tab = (LAS float*)(lds + NA_TAB);
;     for (int it = 0;; ++it) {
;         const int item = item_of(it, NA_ITEMS_LAT, NA_ITEMS); if (item < 0) break;
;         const bool isctx = item >= NA_ITEMS_LAT;
;         int b, hp, rq;
;         if (!isctx) { b = item >> 8; hp = (item >> 5) & 7; rq = item & 31; } else { const int j = item - NA_ITEMS_LAT; b = j >> 3; hp = j & 7; rq = 0; }
;         const int hh = w >> 2, head = 2 * hp + hh;
;         const size_t ctx0 = (size_t)(MLAT + b * NCTX), lat0 = (size_t)(b * SEQ);
;         const int kr_lo = min(max(4 * rq - 4, 0), 120), kr_hi = min(max(4 * rq - 1, 0), 120) + 8;
;         const int NT = 4 + (isctx ? 0 : kr_hi - kr_lo);
;         const DmaLane dl = dma_lane(DM, hp * 128, w, lane);
;     ...
;         dma_tile<2>(lds, K, V, NA_ROW0(0), DM, dl, w);
;         dma_tile<2>(lds + NA_BUF, K, V, NA_ROW0(1), DM, dl, w);
;         dma_tile<2>(lds + 2 * NA_BUF, K, V, NA_ROW0(2), DM, dl, w);
;         for (int i = tid; i < 2 * 465; i += 512) { const int h2 = i / 465, e = i - h2 * 465; tab[h2 * 512 + e] = rpb[(2 * hp + h2) * 465 + e] * LOG2E; }
;         const int r = 4 * rq + (w & 3);
;         const size_t qrow0 = isctx ? (size_t)(MLAT + b * NCTX + (w & 3) * 64) : (size_t)(b * SEQ + r * 64);
;         bf16x8 qf[4][2];
; #pragma unroll
;         for (int grp = 0; grp < 4; ++grp)
; #pragma unroll
;             for (int ds = 0; ds < 2; ++ds) qf[grp][ds] = *(const bf16x8*)(Q + (qrow0 + 16 * grp + l15) * DM + head * 64 + 32 * ds + 8 * g);
;         f32x4 O[4][4]; float ls[4];
; #pragma unroll
;         for (int grp = 0; grp < 4; ++grp) { ls[grp] = 0.f;
; #pragma unroll
;             for (int db = 0; db < 4; ++db) O[grp][db] = (f32x4){0.f, 0.f, 0.f, 0.f}; }
;         const int r0w = min(max(r - 4, 0), 120);
.LBB0_359:
	s_and_b64 vcc, exec, s[0:1]
	s_cbranch_vccz .LBB0_450
	v_readlane_b32 s0, v241, 50
	v_readlane_b32 s1, v241, 51
	v_readlane_b32 s98, v240, 58
	v_readlane_b32 s99, v240, 59
	v_mov_b32_e32 v108, s98
	v_mov_b32_e32 v109, s99
	v_mov_b32_e32 v198, v152
	v_mov_b32_e32 v111, v155
	s_mov_b32 s92, 0
	s_nop 0
	global_load_dword v0, v155, s[0:1]
	s_waitcnt vmcnt(0)
	v_xor_b32_e32 v0, 0x80000000, v0
	v_bfe_u32 v1, v198, 3, 3
	v_xor_b32_e32 v5, v1, v198
	v_and_b32_e32 v6, 1, v198
	v_bfe_u32 v7, v198, 3, 1
	v_bfe_u32 v4, v198, 4, 2
	v_and_b32_e32 v2, 7, v198
	v_bitop3_b32 v3, v1, v198, 7 bitop3:0x78
	v_and_or_b32 v5, v5, 6, v6
	v_and_or_b32 v8, v1, 2, v7
	v_readfirstlane_b32 s0, v198
	v_lshlrev_b32_e32 v201, 4, v3
	v_lshlrev_b32_e32 v202, 4, v5
	v_lshlrev_b32_e32 v154, 3, v4
	v_bitop3_b32 v3, v4, v198, 7 bitop3:0x78
	v_bitop3_b32 v2, v4, v2, 4 bitop3:0x36
	v_lshlrev_b32_e32 v5, 9, v4
	v_lshlrev_b32_e32 v206, 5, v8
	v_bfe_u32 v8, v198, 2, 2
	v_lshlrev_b32_e32 v4, 2, v4
	s_ashr_i32 s1, s0, 6
	v_and_b32_e32 v199, 15, v198
	s_ashr_i32 s6, s0, 8
	s_movk_i32 s0, 0x3a2
	v_or_b32_e32 v8, v4, v8
	v_cmp_gt_i32_e64 s[8:9], s0, v198
	v_lshlrev_b32_e32 v210, 7, v8
	v_sub_u32_e64 v8, v199, 8 clamp
	v_writelane_b32 v240, s8, 46
	s_and_b32 s2, s1, 3
	v_sub_u32_e32 v8, v4, v8
	v_lshlrev_b32_e32 v6, 11, v1
	v_writelane_b32 v240, s9, 47
	s_lshl_b32 s0, s2, 6
	v_add_u32_e32 v10, 1, v8
	v_lshl_or_b32 v200, s1, 14, v6
	s_lshl_b32 s63, s1, 10
	v_writelane_b32 v240, s0, 48
	v_readlane_b32 s0, v241, 37
	v_cmp_gt_u32_e64 s[10:11], 16, v10
	v_add_u32_e32 v10, 2, v8
	v_and_b32_e32 v110, 48, v198
	v_readlane_b32 s1, v241, 38
	v_cmp_gt_u32_e64 s[12:13], 16, v10
	v_add_u32_e32 v10, 3, v8
	v_lshl_add_u64 v[112:113], s[0:1], 0, v[110:111]
	s_lshl_b32 s0, s6, 13
	v_writelane_b32 v240, s6, 49
	s_lshl_b32 s1, s6, 11
	v_cmp_gt_u32_e64 s[14:15], 16, v10
	s_movk_i32 s6, 0xffef
	v_add_u32_e32 v10, 17, v8
	v_sub_u32_e32 v9, v4, v199
	v_cmp_gt_u32_e64 s[8:9], 16, v8
	v_cmp_lt_u32_e64 s[16:17], s6, v8
	v_cmp_gt_u32_e64 s[18:19], 16, v10
	v_add_u32_e32 v10, 18, v8
	v_add_u32_e32 v8, 19, v8
	v_cmp_gt_u32_e64 s[22:23], 16, v8
	v_add_u32_e32 v8, 1, v9
	v_cmp_gt_u32_e64 s[26:27], 16, v8
	v_add_u32_e32 v8, 2, v9
	v_cmp_gt_u32_e64 s[28:29], 16, v8
	v_add_u32_e32 v8, 3, v9
	v_cmp_gt_u32_e64 s[30:31], 16, v8
	v_add_u32_e32 v8, 17, v9
	v_cmp_gt_u32_e64 s[36:37], 16, v8
	v_add_u32_e32 v8, 18, v9
	v_cmp_gt_u32_e64 s[38:39], 16, v8
	v_add_u32_e32 v8, 19, v9
	v_cmp_gt_u32_e64 s[40:41], 16, v8
	v_and_or_b32 v8, v198, 63, 48
	v_cmp_gt_u32_e64 s[24:25], 16, v9
	v_cmp_lt_u32_e64 s[34:35], s6, v9
	v_add_u32_e32 v9, -8, v8
	v_min_u32_e32 v9, 48, v9
	v_sub_u32_e32 v4, v4, v9
	v_and_b32_e32 v9, -16, v4
	s_movk_i32 s6, 0xffe0
	v_cmp_gt_u32_e64 s[20:21], 16, v10
	v_cmp_eq_u32_e64 s[42:43], s6, v9
	v_add_u32_e32 v10, 33, v4
	s_movk_i32 s6, 0xffd0
	v_lshlrev_b32_e32 v204, 4, v2
	v_lshlrev_b32_e32 v2, 5, v198
	v_cmp_gt_u32_e64 s[44:45], 16, v10
	v_add_u32_e32 v10, 34, v4
	v_cmp_eq_u32_e64 s[50:51], s6, v9
	v_add_u32_e32 v9, 49, v4
	v_and_b32_e32 v6, 0x180, v2
	v_lshlrev_b32_e32 v2, 3, v198
	v_cmp_gt_u32_e64 s[46:47], 16, v10
	v_add_u32_e32 v10, 35, v4
	v_cmp_gt_u32_e64 s[52:53], 16, v9
	v_add_u32_e32 v9, 50, v4
	v_add_u32_e32 v4, 51, v4
	s_add_i32 s65, s0, 0
	v_lshlrev_b32_e32 v111, 7, v199
	v_and_b32_e32 v205, 24, v2
	v_cmp_gt_u32_e64 s[56:57], 16, v4
	v_readlane_b32 s6, v241, 43
	v_add_u32_e32 v4, s65, v5
	v_lshlrev_b32_e32 v203, 4, v3
	v_readlane_b32 s7, v241, 44
	v_add3_u32 v212, v4, v6, v205
	v_or_b32_e32 v4, s0, v111
	v_cmp_gt_u32_e64 s[54:55], 16, v9
	v_lshl_add_u64 v[114:115], s[6:7], 0, v[154:155]
	v_or_b32_e32 v9, v4, v204
	s_add_i32 s6, 0, 0x8000
	v_or_b32_e32 v4, v4, v203
	v_add_u32_e32 v214, s6, v4
	v_or3_b32 v4, s0, v5, v6
	v_lshlrev_b32_e32 v5, 2, v198
	v_and_or_b32 v5, v5, 64, v4
	v_lshlrev_b32_e32 v6, 5, v7
	v_xor_b32_e32 v209, 0x60, v206
	v_or3_b32 v5, v5, v6, v205
	v_xor_b32_e32 v207, 32, v206
	v_xor_b32_e32 v208, 64, v206
	v_add_u32_e32 v215, 0, v5
	v_or3_b32 v5, v4, v209, v205
	v_add_u32_e32 v216, 0, v5
	v_or3_b32 v5, v4, v208, v205
	v_or3_b32 v4, v4, v207, v205
	v_add_u32_e32 v218, 0, v4
	v_lshlrev_b32_e32 v4, 2, v8
	v_sub_u32_e32 v4, s1, v4
	v_add_u32_e32 v219, 0, v4
	v_lshlrev_b32_e32 v4, 2, v199
	v_sub_u32_e32 v4, s1, v4
	v_mov_b32_e32 v1, v0
	v_mov_b32_e32 v2, v0
	v_mov_b32_e32 v3, v0
	v_cmp_gt_u32_e64 s[48:49], 16, v10
	v_add_u32_e32 v211, s65, v111
	v_add_u32_e32 v213, s6, v9
	v_add_u32_e32 v217, 0, v5
	s_add_i32 s69, s63, 0
	v_add_u32_e32 v220, 0, v4
	s_branch .LBB0_362

;     __device__ void init(int N, int K, int S_, int G_, int c_, bool rev = false) { lat.init(MLAT, N, G_, c_); S = S_; ntc = S_ ? K / 64 / S_ : 0; nr = (rev && lat.nwg % G_ == 0) ? lat.nwg / G_ : 0; }
; __global__ void __launch_bounds__(512, 2) fwd_megakernel(Args a) {
;     ...
;             pg8::Gemm g{WSP(bf16_t, WS_O), WSP(const bf16_t, l == 0 ? WS_WO0 : WS_WO1), M, DM, DM, 2}; SplitOrder S; S.init(DM, DM, l == 0 ? 4 : 0, gridDim.x, blockIdx.x);
;             EpiRes E{l == 0 ? (const void*)A->x : (const void*)WSP(bf16_t, WS_HB), WSP(float, WS_HC), WSP(bf16_t, WS_HB), WSP(float, WS_HC), WSP(float, WS_MODS) + l * 5 * 6144 + 2048, WSP(float, WS_PART), l == 0, 0};
;             pg8::gemm_phase<EpiRes, SplitOrder, true, true>(lds, g, S, E);
.LBB0_502:
	s_or_b64 exec, exec, s[0:1]
	v_readlane_b32 s0, v240, 40
	v_readlane_b32 s1, v240, 41
	s_and_b64 vcc, exec, s[0:1]
	v_mov_b64_e32 v[158:159], s[70:71]
	s_waitcnt lgkmcnt(0)
	s_barrier
	s_cbranch_vccnz .LBB0_504
	v_readlane_b32 s98, v240, 50
	v_readlane_b32 s99, v240, 51
	v_mov_b32_e32 v158, s98
	v_mov_b32_e32 v159, s99

; __device__ __forceinline__ void norm_phase(const void* src_lat, int lat_f32, const float* src_ctx, int nrows, const float* gvec, const float* mods_l, int sh_off, int sc_off, bf16_t* U, const float* part, int nparts, float* ctx_out) {
;     int tid_ = threadIdx.x; asm volatile("" : "+v"(tid_));
;     const int lane = tid_ & 63, w = __builtin_amdgcn_readfirstlane(tid_ >> 6);
;     const int gw = blockIdx.x * 8 + w, ngw = gridDim.x * 8;
;     f32x4 gv[4];
; #pragma unroll
;     for (int j = 0; j < 4; ++j) gv[j] = *(const f32x4*)(gvec + 4 * lane + 256 * j);
;     for (int row = gw; row < nrows; row += ngw) {
;         const int s = row < MLAT ? (row >> 13) : 4;
;         f32x4 v[4]; float ss = 0.f;
;         if (row < MLAT && !lat_f32) { const bf16_t* src = (const bf16_t*)src_lat + (size_t)row * DM + 4 * lane;
; #pragma unroll
;             for (int j = 0; j < 4; ++j) { const u32x2 w = *(const u32x2*)(src + 256 * j);
;                 v[j] = (f32x4){__uint_as_float(w.x << 16), __uint_as_float(w.x & 0xffff0000u), __uint_as_float(w.y << 16), __uint_as_float(w.y & 0xffff0000u)}; } }
;         else { const float* src = row < MLAT ? (const float*)src_lat + (size_t)row * DM : src_ctx + (size_t)(row - MLAT) * DM;
; #pragma unroll
;             for (int j = 0; j < 4; ++j) v[j] = *(const f32x4*)(src + 4 * lane + 256 * j); }
; #pragma unroll
;         for (int j = 0; j < 4; ++j) { ss += (v[j][0] * v[j][0] + v[j][1] * v[j][1]) + (v[j][2] * v[j][2] + v[j][3] * v[j][3]); }
;         if (nparts != 0 && row >= MLAT) {
;             for (int ch = 0; ch < nparts; ch += 4) {
;                 f32x4 pv[4][4];
; #pragma unroll
;                 for (int c4 = 0; c4 < 4; ++c4) { const float* pr = part + ((size_t)(ch + c4) * MCTX + (row - MLAT)) * DM + 4 * lane;
; #pragma unroll
;                     for (int j = 0; j < 4; ++j) pv[c4][j] = *(const f32x4*)(pr + 256 * j); }
; #pragma unroll
;                 for (int c4 = 0; c4 < 4; ++c4)
; #pragma unroll
;                     for (int j = 0; j < 4; ++j) v[j] = v[j] + pv[c4][j]; }
;             ss = 0.f;
; #pragma unroll
; __global__ void __launch_bounds__(512, 2) fwd_megakernel(Args a) {
;     ...
;         norm_phase(WSP(bf16_t, WS_HB), 0, l == 0 ? A->ctx : WSP(float, WS_HC), M, A->g_mlp + l * DM, WSP(float, WS_MODS) + l * 5 * 6144, 3072, 4096, WSP(bf16_t, WS_U), WSP(const float, WS_PART), l == 0 ? 4 : 0, WSP(float, WS_HC));
.LBB0_726:
	s_or_b64 exec, exec, s[0:1]
	v_readlane_b32 s0, v240, 40
	v_readlane_b32 s1, v240, 41
	s_and_b64 vcc, exec, s[0:1]
	v_mov_b64_e32 v[16:17], s[72:73]
	s_waitcnt lgkmcnt(0)
	s_barrier
	s_cbranch_vccnz .LBB0_728
	v_readlane_b32 s98, v240, 52
	v_readlane_b32 s99, v240, 53
	v_mov_b32_e32 v16, s98
	v_mov_b32_e32 v17, s99
.LBB0_728:
	v_readlane_b32 s98, v240, 56
	v_readlane_b32 s99, v240, 57
	v_mov_b32_e32 v0, s98
	v_mov_b32_e32 v1, s99
	v_readlane_b32 s0, v240, 36
	v_readlane_b32 s1, v240, 37
	s_and_b64 s[0:1], exec, s[0:1]
	s_mov_b32 s0, 0x8400
	v_mov_b32_e32 v18, v152
	s_cselect_b32 s26, s0, 0x8000
	v_readlane_b32 s1, v241, 4
	v_readfirstlane_b32 s0, v18
	s_ashr_i32 s0, s0, 6
	s_add_i32 s0, s0, s1
	s_cmp_ge_i32 s0, s26
	s_cbranch_scc1 .LBB0_738
	v_readlane_b32 s8, v240, 44
	v_readlane_b32 s9, v240, 45
	v_lshlrev_b32_e32 v2, 2, v18
	s_lshl_b64 s[8:9], s[8:9], 2
	v_and_b32_e32 v20, 0xfc, v2
	s_waitcnt vmcnt(0)
	v_lshl_add_u64 v[0:1], v[0:1], 0, s[8:9]
	v_lshlrev_b32_e32 v154, 2, v20
	v_lshl_add_u64 v[12:13], v[0:1], 0, v[154:155]
	flat_load_dwordx4 v[0:3], v[12:13]
	flat_load_dwordx4 v[4:7], v[12:13] offset:1024
	flat_load_dwordx4 v[8:11], v[12:13] offset:2048
	s_nop 0
	flat_load_dwordx4 v[12:15], v[12:13] offset:3072
	v_readlane_b32 s8, v241, 7
	v_readlane_b32 s9, v241, 8
	s_ashr_i32 s1, s0, 31
	v_lshl_add_u64 v[36:37], v[16:17], 0, v[154:155]
	v_lshl_add_u64 v[32:33], s[8:9], 0, v[154:155]
	s_lshl_b64 s[8:9], s[0:1], 11
	v_and_b32_e32 v16, 63, v18
	s_add_u32 s8, s70, s8
	v_lshl_add_u64 v[34:35], s[72:73], 0, v[154:155]
	v_lshlrev_b32_e32 v154, 3, v16
	s_addc_u32 s9, s71, s9
	v_lshl_add_u64 v[38:39], s[8:9], 0, v[154:155]
	v_lshlrev_b32_e32 v154, 2, v20
	s_cmp_lg_u32 s56, 0x800
	s_cbranch_scc1 .LBB0_732
	v_and_b32_e32 v100, 63, v152
	v_lshlrev_b32_e32 v101, 4, v100
	v_lshlrev_b32_e32 v100, 3, v100
	v_readlane_b32 s34, v240, 42
	v_readlane_b32 s35, v240, 43
	s_lshl_b32 s36, s0, 11
	s_nop 0
	s_add_u32 s38, s70, s36
	s_addc_u32 s39, s71, 0
	s_add_u32 s40, s38, 0xe7600000
	s_addc_u32 s41, s39, -1
	s_add_u32 s42, s34, 0x3000
	s_addc_u32 s43, s35, 0
	s_add_u32 s44, s34, 0x4000
	s_addc_u32 s45, s35, 0
	global_load_dwordx4 v[198:201], v101, s[42:43]
	global_load_dwordx4 v[202:205], v101, s[42:43] offset:1024
	global_load_dwordx4 v[206:209], v101, s[42:43] offset:2048
	global_load_dwordx4 v[210:213], v101, s[42:43] offset:3072
	global_load_dwordx4 v[214:217], v101, s[44:45]
	global_load_dwordx4 v[218:221], v101, s[44:45] offset:1024
	global_load_dwordx4 v[222:225], v101, s[44:45] offset:2048
	global_load_dwordx4 v[226:229], v101, s[44:45] offset:3072
	s_add_u32 s42, s42, 0x6000
	s_addc_u32 s43, s43, 0
	s_add_u32 s44, s44, 0x6000
	s_addc_u32 s45, s45, 0
	global_load_dwordx2 v[104:105], v100, s[38:39]
	global_load_dwordx2 v[106:107], v100, s[38:39] offset:512
	global_load_dwordx2 v[108:109], v100, s[38:39] offset:1024
	global_load_dwordx2 v[110:111], v100, s[38:39] offset:1536
	s_add_u32 s38, s38, 0x400000
	s_addc_u32 s39, s39, 0
	global_load_dwordx2 v[112:113], v100, s[38:39]
	global_load_dwordx2 v[114:115], v100, s[38:39] offset:512
	global_load_dwordx2 v[116:117], v100, s[38:39] offset:1024
	global_load_dwordx2 v[118:119], v100, s[38:39] offset:1536
	s_add_u32 s38, s38, 0x400000
	s_addc_u32 s39, s39, 0
	global_load_dwordx2 v[120:121], v100, s[38:39]
	global_load_dwordx2 v[122:123], v100, s[38:39] offset:512
	global_load_dwordx2 v[124:125], v100, s[38:39] offset:1024
	global_load_dwordx2 v[126:127], v100, s[38:39] offset:1536
	s_add_u32 s38, s38, 0x400000
	s_addc_u32 s39, s39, 0
	global_load_dwordx2 v[128:129], v100, s[38:39]
	global_load_dwordx2 v[130:131], v100, s[38:39] offset:512
	global_load_dwordx2 v[132:133], v100, s[38:39] offset:1024
	global_load_dwordx2 v[134:135], v100, s[38:39] offset:1536
	s_add_u32 s38, s38, 0x400000
	s_addc_u32 s39, s39, 0
	s_waitcnt vmcnt(16)
	v_pk_add_f32 v[214:215], v[214:215], 1.0 op_sel_hi:[1,0]
	v_pk_add_f32 v[216:217], v[216:217], 1.0 op_sel_hi:[1,0]
	v_pk_add_f32 v[218:219], v[218:219], 1.0 op_sel_hi:[1,0]
	v_pk_add_f32 v[220:221], v[220:221], 1.0 op_sel_hi:[1,0]
	v_pk_add_f32 v[222:223], v[222:223], 1.0 op_sel_hi:[1,0]
	v_pk_add_f32 v[224:225], v[224:225], 1.0 op_sel_hi:[1,0]
	v_pk_add_f32 v[226:227], v[226:227], 1.0 op_sel_hi:[1,0]
	v_pk_add_f32 v[228:229], v[228:229], 1.0 op_sel_hi:[1,0]
	s_waitcnt vmcnt(12)
; __device__ __forceinline__ void norm_phase(const void* src_lat, int lat_f32, const float* src_ctx, int nrows, const float* gvec, const float* mods_l, int sh_off, int sc_off, bf16_t* U, const float* part, int nparts, float* ctx_out) {
;     ...
;     for (int row = gw; row < nrows; row += ngw) {
;         const int s = row < MLAT ? (row >> 13) : 4;
;         f32x4 v[4]; float ss = 0.f;
;         if (row < MLAT && !lat_f32) { const bf16_t* src = (const bf16_t*)src_lat + (size_t)row * DM + 4 * lane;
; #pragma unroll
;             for (int j = 0; j < 4; ++j) { const u32x2 w = *(const u32x2*)(src + 256 * j);
;                 v[j] = (f32x4){__uint_as_float(w.x << 16), __uint_as_float(w.x & 0xffff0000u), __uint_as_float(w.y << 16), __uint_as_float(w.y & 0xffff0000u)}; } }
;         else { const float* src = row < MLAT ? (const float*)src_lat + (size_t)row * DM : src_ctx + (size_t)(row - MLAT) * DM;
; #pragma unroll
;             for (int j = 0; j < 4; ++j) v[j] = *(const f32x4*)(src + 4 * lane + 256 * j); }
; #pragma unroll
;         for (int j = 0; j < 4; ++j) { ss += (v[j][0] * v[j][0] + v[j][1] * v[j][1]) + (v[j][2] * v[j][2] + v[j][3] * v[j][3]); }
;         if (nparts != 0 && row >= MLAT) {
;             for (int ch = 0; ch < nparts; ch += 4) {
;                 f32x4 pv[4][4];
; #pragma unroll
;                 for (int c4 = 0; c4 < 4; ++c4) { const float* pr = part + ((size_t)(ch + c4) * MCTX + (row - MLAT)) * DM + 4 * lane;
; #pragma unroll
;                     for (int j = 0; j < 4; ++j) pv[c4][j] = *(const f32x4*)(pr + 256 * j); }
; #pragma unroll
;                 for (int c4 = 0; c4 < 4; ++c4)
; #pragma unroll
;                     for (int j = 0; j < 4; ++j) v[j] = v[j] + pv[c4][j]; }
;             ss = 0.f;
; #pragma unroll
;             for (int j = 0; j < 4; ++j) { *(f32x4*)(ctx_out + (size_t)(row - MLAT) * DM + 4 * lane + 256 * j) = v[j]; ss += (v[j][0] * v[j][0] + v[j][1] * v[j][1]) + (v[j][2] * v[j][2] + v[j][3] * v[j][3]); }
;         }
;         const float rs = rsqrtf(wave_sum64(ss) * (1.0f / DM) + EPS);
;         const float* shp = mods_l + s * 6144 + sh_off + 4 * lane; const float* scp = mods_l + s * 6144 + sc_off + 4 * lane;
;         bf16_t* up = U + (size_t)row * DM + 4 * lane;
; #pragma unroll
;         for (int j = 0; j < 4; ++j) { const f32x4 sh = *(const f32x4*)(shp + 256 * j), sc = *(const f32x4*)(scp + 256 * j);
	v_lshlrev_b32_e32 v40, 16, v104
	v_and_b32_e32 v41, 0xffff0000, v104
	v_lshlrev_b32_e32 v42, 16, v105
	v_and_b32_e32 v43, 0xffff0000, v105
	v_lshlrev_b32_e32 v44, 16, v106
	v_and_b32_e32 v45, 0xffff0000, v106
	v_lshlrev_b32_e32 v46, 16, v107
	v_and_b32_e32 v47, 0xffff0000, v107
	v_lshlrev_b32_e32 v48, 16, v108
	v_and_b32_e32 v49, 0xffff0000, v108
	v_lshlrev_b32_e32 v50, 16, v109
	v_and_b32_e32 v51, 0xffff0000, v109
	v_lshlrev_b32_e32 v52, 16, v110
	v_and_b32_e32 v53, 0xffff0000, v110
	v_lshlrev_b32_e32 v54, 16, v111
	v_and_b32_e32 v55, 0xffff0000, v111
	v_mul_f32_e32 v56, v41, v41
	v_mul_f32_e32 v57, v43, v43
	v_fmac_f32_e32 v56, v40, v40
	v_fmac_f32_e32 v57, v42, v42
	v_add_f32_e32 v58, v56, v57
	v_mul_f32_e32 v56, v45, v45
	v_mul_f32_e32 v57, v47, v47
	v_fmac_f32_e32 v56, v44, v44
	v_fmac_f32_e32 v57, v46, v46
	v_add_f32_e32 v56, v56, v57
	v_add_f32_e32 v58, v58, v56
	v_mul_f32_e32 v56, v49, v49
	v_mul_f32_e32 v57, v51, v51
	v_fmac_f32_e32 v56, v48, v48
	v_fmac_f32_e32 v57, v50, v50
	v_add_f32_e32 v56, v56, v57
	v_add_f32_e32 v58, v58, v56
	v_mul_f32_e32 v56, v53, v53
	v_mul_f32_e32 v57, v55, v55
	v_fmac_f32_e32 v56, v52, v52
	v_fmac_f32_e32 v57, v54, v54
	v_add_f32_e32 v56, v56, v57
	v_add_f32_e32 v58, v58, v56
	s_nop 1
	v_add_f32_dpp v58, v58, v58 quad_perm:[1,0,3,2] row_mask:0xf bank_mask:0xf bound_ctrl:1
	s_nop 1
	v_add_f32_dpp v58, v58, v58 quad_perm:[2,3,0,1] row_mask:0xf bank_mask:0xf bound_ctrl:1
	s_nop 1
	v_add_f32_dpp v58, v58, v58 row_half_mirror row_mask:0xf bank_mask:0xf bound_ctrl:1
	s_nop 1
	v_add_f32_dpp v58, v58, v58 row_mirror row_mask:0xf bank_mask:0xf bound_ctrl:1
	v_mov_b32_e32 v56, v58
	s_nop 1
	v_permlane16_swap_b32_e32 v58, v56
	v_add_f32_e32 v58, v58, v56
	v_mov_b32_e32 v56, v58
	s_nop 1
	v_permlane32_swap_b32_e32 v58, v56
	v_add_f32_e32 v58, v58, v56
	v_fmamk_f32 v60, v58, 0x3a800000, v153
	v_rsq_f32_e32 v60, v60
	s_nop 0
	v_pk_mul_f32 v[40:41], v[40:41], v[60:61] op_sel_hi:[1,0]
	v_pk_mul_f32 v[42:43], v[42:43], v[60:61] op_sel_hi:[1,0]
	v_pk_mul_f32 v[44:45], v[44:45], v[60:61] op_sel_hi:[1,0]
	v_pk_mul_f32 v[46:47], v[46:47], v[60:61] op_sel_hi:[1,0]
	v_pk_mul_f32 v[48:49], v[48:49], v[60:61] op_sel_hi:[1,0]
	v_pk_mul_f32 v[50:51], v[50:51], v[60:61] op_sel_hi:[1,0]
	v_pk_mul_f32 v[52:53], v[52:53], v[60:61] op_sel_hi:[1,0]
	v_pk_mul_f32 v[54:55], v[54:55], v[60:61] op_sel_hi:[1,0]
	v_pk_mul_f32 v[40:41], v[0:1], v[40:41]
	v_pk_mul_f32 v[42:43], v[2:3], v[42:43]
	v_pk_mul_f32 v[44:45], v[4:5], v[44:45]
	v_pk_mul_f32 v[46:47], v[6:7], v[46:47]
	v_pk_mul_f32 v[48:49], v[8:9], v[48:49]
	v_pk_mul_f32 v[50:51], v[10:11], v[50:51]
	v_pk_mul_f32 v[52:53], v[12:13], v[52:53]
	v_pk_mul_f32 v[54:55], v[14:15], v[54:55]
	v_pk_fma_f32 v[40:41], v[214:215], v[40:41], v[198:199]
	v_pk_fma_f32 v[42:43], v[216:217], v[42:43], v[200:201]
	v_pk_fma_f32 v[44:45], v[218:219], v[44:45], v[202:203]
	v_pk_fma_f32 v[46:47], v[220:221], v[46:47], v[204:205]
	v_pk_fma_f32 v[48:49], v[222:223], v[48:49], v[206:207]
	v_pk_fma_f32 v[50:51], v[224:225], v[50:51], v[208:209]
	v_pk_fma_f32 v[52:53], v[226:227], v[52:53], v[210:211]
	v_pk_fma_f32 v[54:55], v[228:229], v[54:55], v[212:213]
	v_cvt_pk_bf16_f32 v40, v40, v41
	v_cvt_pk_bf16_f32 v41, v42, v43
	v_cvt_pk_bf16_f32 v44, v44, v45
	v_cvt_pk_bf16_f32 v45, v46, v47
	v_cvt_pk_bf16_f32 v48, v48, v49
	v_cvt_pk_bf16_f32 v49, v50, v51
	v_cvt_pk_bf16_f32 v52, v52, v53
	v_cvt_pk_bf16_f32 v53, v54, v55
	global_store_dwordx2 v100, v[40:41], s[40:41]
	global_store_dwordx2 v100, v[44:45], s[40:41] offset:512
	global_store_dwordx2 v100, v[48:49], s[40:41] offset:1024
	global_store_dwordx2 v100, v[52:53], s[40:41] offset:1536
	s_add_u32 s40, s40, 0x400000
	s_addc_u32 s41, s41, 0
	global_load_dwordx2 v[104:105], v100, s[38:39]
	global_load_dwordx2 v[106:107], v100, s[38:39] offset:512
	global_load_dwordx2 v[108:109], v100, s[38:39] offset:1024
	global_load_dwordx2 v[110:111], v100, s[38:39] offset:1536
	s_add_u32 s38, s38, 0x400000
	s_addc_u32 s39, s39, 0
	global_load_dwordx4 v[68:71], v101, s[42:43]
	global_load_dwordx4 v[72:75], v101, s[42:43] offset:1024
	global_load_dwordx4 v[76:79], v101, s[42:43] offset:2048
	global_load_dwordx4 v[80:83], v101, s[42:43] offset:3072
	global_load_dwordx4 v[84:87], v101, s[44:45]
	global_load_dwordx4 v[88:91], v101, s[44:45] offset:1024
	global_load_dwordx4 v[92:95], v101, s[44:45] offset:2048
	global_load_dwordx4 v[96:99], v101, s[44:45] offset:3072
	s_add_u32 s42, s42, 0x6000
	s_addc_u32 s43, s43, 0
	s_add_u32 s44, s44, 0x6000
	s_addc_u32 s45, s45, 0
	s_waitcnt vmcnt(24)
; __device__ __forceinline__ void norm_phase(const void* src_lat, int lat_f32, const float* src_ctx, int nrows, const float* gvec, const float* mods_l, int sh_off, int sc_off, bf16_t* U, const float* part, int nparts, float* ctx_out) {
;     ...
;     for (int row = gw; row < nrows; row += ngw) {
;         const int s = row < MLAT ? (row >> 13) : 4;
;         f32x4 v[4]; float ss = 0.f;
;         if (row < MLAT && !lat_f32) { const bf16_t* src = (const bf16_t*)src_lat + (size_t)row * DM + 4 * lane;
; #pragma unroll
;             for (int j = 0; j < 4; ++j) { const u32x2 w = *(const u32x2*)(src + 256 * j);
;                 v[j] = (f32x4){__uint_as_float(w.x << 16), __uint_as_float(w.x & 0xffff0000u), __uint_as_float(w.y << 16), __uint_as_float(w.y & 0xffff0000u)}; } }
;         else { const float* src = row < MLAT ? (const float*)src_lat + (size_t)row * DM : src_ctx + (size_t)(row - MLAT) * DM;
; #pragma unroll
;             for (int j = 0; j < 4; ++j) v[j] = *(const f32x4*)(src + 4 * lane + 256 * j); }
; #pragma unroll
;         for (int j = 0; j < 4; ++j) { ss += (v[j][0] * v[j][0] + v[j][1] * v[j][1]) + (v[j][2] * v[j][2] + v[j][3] * v[j][3]); }
;         if (nparts != 0 && row >= MLAT) {
;             for (int ch = 0; ch < nparts; ch += 4) {
;                 f32x4 pv[4][4];
; #pragma unroll
;                 for (int c4 = 0; c4 < 4; ++c4) { const float* pr = part + ((size_t)(ch + c4) * MCTX + (row - MLAT)) * DM + 4 * lane;
; #pragma unroll
;                     for (int j = 0; j < 4; ++j) pv[c4][j] = *(const f32x4*)(pr + 256 * j); }
; #pragma unroll
;                 for (int c4 = 0; c4 < 4; ++c4)
; #pragma unroll
;                     for (int j = 0; j < 4; ++j) v[j] = v[j] + pv[c4][j]; }
;             ss = 0.f;
; #pragma unroll
;             for (int j = 0; j < 4; ++j) { *(f32x4*)(ctx_out + (size_t)(row - MLAT) * DM + 4 * lane + 256 * j) = v[j]; ss += (v[j][0] * v[j][0] + v[j][1] * v[j][1]) + (v[j][2] * v[j][2] + v[j][3] * v[j][3]); }
;         }
;         const float rs = rsqrtf(wave_sum64(ss) * (1.0f / DM) + EPS);
;         const float* shp = mods_l + s * 6144 + sh_off + 4 * lane; const float* scp = mods_l + s * 6144 + sc_off + 4 * lane;
;         bf16_t* up = U + (size_t)row * DM + 4 * lane;
; #pragma unroll
;         for (int j = 0; j < 4; ++j) { const f32x4 sh = *(const f32x4*)(shp + 256 * j), sc = *(const f32x4*)(scp + 256 * j);
	v_lshlrev_b32_e32 v40, 16, v112
	v_and_b32_e32 v41, 0xffff0000, v112
	v_lshlrev_b32_e32 v42, 16, v113
	v_and_b32_e32 v43, 0xffff0000, v113
	v_lshlrev_b32_e32 v44, 16, v114
	v_and_b32_e32 v45, 0xffff0000, v114
	v_lshlrev_b32_e32 v46, 16, v115
	v_and_b32_e32 v47, 0xffff0000, v115
	v_lshlrev_b32_e32 v48, 16, v116
	v_and_b32_e32 v49, 0xffff0000, v116
	v_lshlrev_b32_e32 v50, 16, v117
	v_and_b32_e32 v51, 0xffff0000, v117
	v_lshlrev_b32_e32 v52, 16, v118
	v_and_b32_e32 v53, 0xffff0000, v118
	v_lshlrev_b32_e32 v54, 16, v119
	v_and_b32_e32 v55, 0xffff0000, v119
	v_mul_f32_e32 v56, v41, v41
	v_mul_f32_e32 v57, v43, v43
	v_fmac_f32_e32 v56, v40, v40
	v_fmac_f32_e32 v57, v42, v42
	v_add_f32_e32 v58, v56, v57
	v_mul_f32_e32 v56, v45, v45
	v_mul_f32_e32 v57, v47, v47
	v_fmac_f32_e32 v56, v44, v44
	v_fmac_f32_e32 v57, v46, v46
	v_add_f32_e32 v56, v56, v57
	v_add_f32_e32 v58, v58, v56
	v_mul_f32_e32 v56, v49, v49
	v_mul_f32_e32 v57, v51, v51
	v_fmac_f32_e32 v56, v48, v48
	v_fmac_f32_e32 v57, v50, v50
	v_add_f32_e32 v56, v56, v57
	v_add_f32_e32 v58, v58, v56
	v_mul_f32_e32 v56, v53, v53
	v_mul_f32_e32 v57, v55, v55
	v_fmac_f32_e32 v56, v52, v52
	v_fmac_f32_e32 v57, v54, v54
	v_add_f32_e32 v56, v56, v57
	v_add_f32_e32 v58, v58, v56
	s_nop 1
	v_add_f32_dpp v58, v58, v58 quad_perm:[1,0,3,2] row_mask:0xf bank_mask:0xf bound_ctrl:1
	s_nop 1
	v_add_f32_dpp v58, v58, v58 quad_perm:[2,3,0,1] row_mask:0xf bank_mask:0xf bound_ctrl:1
	s_nop 1
	v_add_f32_dpp v58, v58, v58 row_half_mirror row_mask:0xf bank_mask:0xf bound_ctrl:1
	s_nop 1
	v_add_f32_dpp v58, v58, v58 row_mirror row_mask:0xf bank_mask:0xf bound_ctrl:1
	v_mov_b32_e32 v56, v58
	s_nop 1
	v_permlane16_swap_b32_e32 v58, v56
	v_add_f32_e32 v58, v58, v56
	v_mov_b32_e32 v56, v58
	s_nop 1
	v_permlane32_swap_b32_e32 v58, v56
	v_add_f32_e32 v58, v58, v56
	v_fmamk_f32 v60, v58, 0x3a800000, v153
	v_rsq_f32_e32 v60, v60
	s_nop 0
	v_pk_mul_f32 v[40:41], v[40:41], v[60:61] op_sel_hi:[1,0]
	v_pk_mul_f32 v[42:43], v[42:43], v[60:61] op_sel_hi:[1,0]
	v_pk_mul_f32 v[44:45], v[44:45], v[60:61] op_sel_hi:[1,0]
	v_pk_mul_f32 v[46:47], v[46:47], v[60:61] op_sel_hi:[1,0]
	v_pk_mul_f32 v[48:49], v[48:49], v[60:61] op_sel_hi:[1,0]
	v_pk_mul_f32 v[50:51], v[50:51], v[60:61] op_sel_hi:[1,0]
	v_pk_mul_f32 v[52:53], v[52:53], v[60:61] op_sel_hi:[1,0]
	v_pk_mul_f32 v[54:55], v[54:55], v[60:61] op_sel_hi:[1,0]
	v_pk_mul_f32 v[40:41], v[0:1], v[40:41]
	v_pk_mul_f32 v[42:43], v[2:3], v[42:43]
	v_pk_mul_f32 v[44:45], v[4:5], v[44:45]
	v_pk_mul_f32 v[46:47], v[6:7], v[46:47]
	v_pk_mul_f32 v[48:49], v[8:9], v[48:49]
	v_pk_mul_f32 v[50:51], v[10:11], v[50:51]
	v_pk_mul_f32 v[52:53], v[12:13], v[52:53]
	v_pk_mul_f32 v[54:55], v[14:15], v[54:55]
	v_pk_fma_f32 v[40:41], v[214:215], v[40:41], v[198:199]
	v_pk_fma_f32 v[42:43], v[216:217], v[42:43], v[200:201]
	v_pk_fma_f32 v[44:45], v[218:219], v[44:45], v[202:203]
	v_pk_fma_f32 v[46:47], v[220:221], v[46:47], v[204:205]
	v_pk_fma_f32 v[48:49], v[222:223], v[48:49], v[206:207]
	v_pk_fma_f32 v[50:51], v[224:225], v[50:51], v[208:209]
	v_pk_fma_f32 v[52:53], v[226:227], v[52:53], v[210:211]
	v_pk_fma_f32 v[54:55], v[228:229], v[54:55], v[212:213]
	v_cvt_pk_bf16_f32 v40, v40, v41
	v_cvt_pk_bf16_f32 v41, v42, v43
	v_cvt_pk_bf16_f32 v44, v44, v45
	v_cvt_pk_bf16_f32 v45, v46, v47
	v_cvt_pk_bf16_f32 v48, v48, v49
	v_cvt_pk_bf16_f32 v49, v50, v51
	v_cvt_pk_bf16_f32 v52, v52, v53
	v_cvt_pk_bf16_f32 v53, v54, v55
	global_store_dwordx2 v100, v[40:41], s[40:41]
	global_store_dwordx2 v100, v[44:45], s[40:41] offset:512
	global_store_dwordx2 v100, v[48:49], s[40:41] offset:1024
	global_store_dwordx2 v100, v[52:53], s[40:41] offset:1536
	s_add_u32 s40, s40, 0x400000
	s_addc_u32 s41, s41, 0
	global_load_dwordx2 v[112:113], v100, s[38:39]
	global_load_dwordx2 v[114:115], v100, s[38:39] offset:512
	global_load_dwordx2 v[116:117], v100, s[38:39] offset:1024
	global_load_dwordx2 v[118:119], v100, s[38:39] offset:1536
	s_add_u32 s38, s38, 0x400000
	s_addc_u32 s39, s39, 0
	s_waitcnt vmcnt(28)
	v_lshlrev_b32_e32 v40, 16, v120
	v_and_b32_e32 v41, 0xffff0000, v120
	v_lshlrev_b32_e32 v42, 16, v121
	v_and_b32_e32 v43, 0xffff0000, v121
	v_lshlrev_b32_e32 v44, 16, v122
	v_and_b32_e32 v45, 0xffff0000, v122
	v_lshlrev_b32_e32 v46, 16, v123
	v_and_b32_e32 v47, 0xffff0000, v123
	v_lshlrev_b32_e32 v48, 16, v124
	v_and_b32_e32 v49, 0xffff0000, v124
	v_lshlrev_b32_e32 v50, 16, v125
	v_and_b32_e32 v51, 0xffff0000, v125
	v_lshlrev_b32_e32 v52, 16, v126
	v_and_b32_e32 v53, 0xffff0000, v126
	v_lshlrev_b32_e32 v54, 16, v127
	v_and_b32_e32 v55, 0xffff0000, v127
	v_mul_f32_e32 v56, v41, v41
	v_mul_f32_e32 v57, v43, v43
	v_fmac_f32_e32 v56, v40, v40
	v_fmac_f32_e32 v57, v42, v42
	v_add_f32_e32 v58, v56, v57
	v_mul_f32_e32 v56, v45, v45
	v_mul_f32_e32 v57, v47, v47
	v_fmac_f32_e32 v56, v44, v44
	v_fmac_f32_e32 v57, v46, v46
	v_add_f32_e32 v56, v56, v57
	v_add_f32_e32 v58, v58, v56
	v_mul_f32_e32 v56, v49, v49
	v_mul_f32_e32 v57, v51, v51
	v_fmac_f32_e32 v56, v48, v48
	v_fmac_f32_e32 v57, v50, v50
	v_add_f32_e32 v56, v56, v57
	v_add_f32_e32 v58, v58, v56
	v_mul_f32_e32 v56, v53, v53
	v_mul_f32_e32 v57, v55, v55
	v_fmac_f32_e32 v56, v52, v52
	v_fmac_f32_e32 v57, v54, v54
	v_add_f32_e32 v56, v56, v57
	v_add_f32_e32 v58, v58, v56
	s_nop 1
	v_add_f32_dpp v58, v58, v58 quad_perm:[1,0,3,2] row_mask:0xf bank_mask:0xf bound_ctrl:1
	s_nop 1
	v_add_f32_dpp v58, v58, v58 quad_perm:[2,3,0,1] row_mask:0xf bank_mask:0xf bound_ctrl:1
	s_nop 1
	v_add_f32_dpp v58, v58, v58 row_half_mirror row_mask:0xf bank_mask:0xf bound_ctrl:1
	s_nop 1
	v_add_f32_dpp v58, v58, v58 row_mirror row_mask:0xf bank_mask:0xf bound_ctrl:1
	v_mov_b32_e32 v56, v58
	s_nop 1
; __device__ __forceinline__ void norm_phase(const void* src_lat, int lat_f32, const float* src_ctx, int nrows, const float* gvec, const float* mods_l, int sh_off, int sc_off, bf16_t* U, const float* part, int nparts, float* ctx_out) {
;     ...
;     for (int row = gw; row < nrows; row += ngw) {
;         const int s = row < MLAT ? (row >> 13) : 4;
;         f32x4 v[4]; float ss = 0.f;
;         if (row < MLAT && !lat_f32) { const bf16_t* src = (const bf16_t*)src_lat + (size_t)row * DM + 4 * lane;
; #pragma unroll
;             for (int j = 0; j < 4; ++j) { const u32x2 w = *(const u32x2*)(src + 256 * j);
;                 v[j] = (f32x4){__uint_as_float(w.x << 16), __uint_as_float(w.x & 0xffff0000u), __uint_as_float(w.y << 16), __uint_as_float(w.y & 0xffff0000u)}; } }
;         else { const float* src = row < MLAT ? (const float*)src_lat + (size_t)row * DM : src_ctx + (size_t)(row - MLAT) * DM;
; #pragma unroll
;             for (int j = 0; j < 4; ++j) v[j] = *(const f32x4*)(src + 4 * lane + 256 * j); }
; #pragma unroll
;         for (int j = 0; j < 4; ++j) { ss += (v[j][0] * v[j][0] + v[j][1] * v[j][1]) + (v[j][2] * v[j][2] + v[j][3] * v[j][3]); }
;         if (nparts != 0 && row >= MLAT) {
;             for (int ch = 0; ch < nparts; ch += 4) {
;                 f32x4 pv[4][4];
; #pragma unroll
;                 for (int c4 = 0; c4 < 4; ++c4) { const float* pr = part + ((size_t)(ch + c4) * MCTX + (row - MLAT)) * DM + 4 * lane;
; #pragma unroll
;                     for (int j = 0; j < 4; ++j) pv[c4][j] = *(const f32x4*)(pr + 256 * j); }
; #pragma unroll
;                 for (int c4 = 0; c4 < 4; ++c4)
; #pragma unroll
;                     for (int j = 0; j < 4; ++j) v[j] = v[j] + pv[c4][j]; }
;             ss = 0.f;
; #pragma unroll
;             for (int j = 0; j < 4; ++j) { *(f32x4*)(ctx_out + (size_t)(row - MLAT) * DM + 4 * lane + 256 * j) = v[j]; ss += (v[j][0] * v[j][0] + v[j][1] * v[j][1]) + (v[j][2] * v[j][2] + v[j][3] * v[j][3]); }
;         }
;         const float rs = rsqrtf(wave_sum64(ss) * (1.0f / DM) + EPS);
;         const float* shp = mods_l + s * 6144 + sh_off + 4 * lane; const float* scp = mods_l + s * 6144 + sc_off + 4 * lane;
;         bf16_t* up = U + (size_t)row * DM + 4 * lane;
; #pragma unroll
;         for (int j = 0; j < 4; ++j) { const f32x4 sh = *(const f32x4*)(shp + 256 * j), sc = *(const f32x4*)(scp + 256 * j);
	v_permlane16_swap_b32_e32 v58, v56
	v_add_f32_e32 v58, v58, v56
	v_mov_b32_e32 v56, v58
	s_nop 1
	v_permlane32_swap_b32_e32 v58, v56
	v_add_f32_e32 v58, v58, v56
	v_fmamk_f32 v60, v58, 0x3a800000, v153
	v_rsq_f32_e32 v60, v60
	s_nop 0
	v_pk_mul_f32 v[40:41], v[40:41], v[60:61] op_sel_hi:[1,0]
	v_pk_mul_f32 v[42:43], v[42:43], v[60:61] op_sel_hi:[1,0]
	v_pk_mul_f32 v[44:45], v[44:45], v[60:61] op_sel_hi:[1,0]
	v_pk_mul_f32 v[46:47], v[46:47], v[60:61] op_sel_hi:[1,0]
	v_pk_mul_f32 v[48:49], v[48:49], v[60:61] op_sel_hi:[1,0]
	v_pk_mul_f32 v[50:51], v[50:51], v[60:61] op_sel_hi:[1,0]
	v_pk_mul_f32 v[52:53], v[52:53], v[60:61] op_sel_hi:[1,0]
	v_pk_mul_f32 v[54:55], v[54:55], v[60:61] op_sel_hi:[1,0]
	v_pk_mul_f32 v[40:41], v[0:1], v[40:41]
	v_pk_mul_f32 v[42:43], v[2:3], v[42:43]
	v_pk_mul_f32 v[44:45], v[4:5], v[44:45]
	v_pk_mul_f32 v[46:47], v[6:7], v[46:47]
	v_pk_mul_f32 v[48:49], v[8:9], v[48:49]
	v_pk_mul_f32 v[50:51], v[10:11], v[50:51]
	v_pk_mul_f32 v[52:53], v[12:13], v[52:53]
	v_pk_mul_f32 v[54:55], v[14:15], v[54:55]
	v_pk_fma_f32 v[40:41], v[214:215], v[40:41], v[198:199]
	v_pk_fma_f32 v[42:43], v[216:217], v[42:43], v[200:201]
	v_pk_fma_f32 v[44:45], v[218:219], v[44:45], v[202:203]
	v_pk_fma_f32 v[46:47], v[220:221], v[46:47], v[204:205]
	v_pk_fma_f32 v[48:49], v[222:223], v[48:49], v[206:207]
	v_pk_fma_f32 v[50:51], v[224:225], v[50:51], v[208:209]
	v_pk_fma_f32 v[52:53], v[226:227], v[52:53], v[210:211]
	v_pk_fma_f32 v[54:55], v[228:229], v[54:55], v[212:213]
	v_cvt_pk_bf16_f32 v40, v40, v41
	v_cvt_pk_bf16_f32 v41, v42, v43
	v_cvt_pk_bf16_f32 v44, v44, v45
	v_cvt_pk_bf16_f32 v45, v46, v47
	v_cvt_pk_bf16_f32 v48, v48, v49
	v_cvt_pk_bf16_f32 v49, v50, v51
	v_cvt_pk_bf16_f32 v52, v52, v53
	v_cvt_pk_bf16_f32 v53, v54, v55
	global_store_dwordx2 v100, v[40:41], s[40:41]
	global_store_dwordx2 v100, v[44:45], s[40:41] offset:512
	global_store_dwordx2 v100, v[48:49], s[40:41] offset:1024
	global_store_dwordx2 v100, v[52:53], s[40:41] offset:1536
	s_add_u32 s40, s40, 0x400000
	s_addc_u32 s41, s41, 0
	global_load_dwordx2 v[120:121], v100, s[38:39]
	global_load_dwordx2 v[122:123], v100, s[38:39] offset:512
	global_load_dwordx2 v[124:125], v100, s[38:39] offset:1024
	global_load_dwordx2 v[126:127], v100, s[38:39] offset:1536
	s_add_u32 s38, s38, 0x400000
	s_addc_u32 s39, s39, 0
	s_waitcnt vmcnt(32)
	v_lshlrev_b32_e32 v40, 16, v128
	v_and_b32_e32 v41, 0xffff0000, v128
	v_lshlrev_b32_e32 v42, 16, v129
	v_and_b32_e32 v43, 0xffff0000, v129
	v_lshlrev_b32_e32 v44, 16, v130
	v_and_b32_e32 v45, 0xffff0000, v130
	v_lshlrev_b32_e32 v46, 16, v131
	v_and_b32_e32 v47, 0xffff0000, v131
	v_lshlrev_b32_e32 v48, 16, v132
	v_and_b32_e32 v49, 0xffff0000, v132
	v_lshlrev_b32_e32 v50, 16, v133
	v_and_b32_e32 v51, 0xffff0000, v133
	v_lshlrev_b32_e32 v52, 16, v134
	v_and_b32_e32 v53, 0xffff0000, v134
	v_lshlrev_b32_e32 v54, 16, v135
	v_and_b32_e32 v55, 0xffff0000, v135
	v_mul_f32_e32 v56, v41, v41
	v_mul_f32_e32 v57, v43, v43
	v_fmac_f32_e32 v56, v40, v40
	v_fmac_f32_e32 v57, v42, v42
	v_add_f32_e32 v58, v56, v57
	v_mul_f32_e32 v56, v45, v45
	v_mul_f32_e32 v57, v47, v47
	v_fmac_f32_e32 v56, v44, v44
	v_fmac_f32_e32 v57, v46, v46
	v_add_f32_e32 v56, v56, v57
	v_add_f32_e32 v58, v58, v56
	v_mul_f32_e32 v56, v49, v49
	v_mul_f32_e32 v57, v51, v51
	v_fmac_f32_e32 v56, v48, v48
	v_fmac_f32_e32 v57, v50, v50
	v_add_f32_e32 v56, v56, v57
	v_add_f32_e32 v58, v58, v56
	v_mul_f32_e32 v56, v53, v53
	v_mul_f32_e32 v57, v55, v55
	v_fmac_f32_e32 v56, v52, v52
	v_fmac_f32_e32 v57, v54, v54
	v_add_f32_e32 v56, v56, v57
	v_add_f32_e32 v58, v58, v56
	s_nop 1
	v_add_f32_dpp v58, v58, v58 quad_perm:[1,0,3,2] row_mask:0xf bank_mask:0xf bound_ctrl:1
	s_nop 1
	v_add_f32_dpp v58, v58, v58 quad_perm:[2,3,0,1] row_mask:0xf bank_mask:0xf bound_ctrl:1
	s_nop 1
	v_add_f32_dpp v58, v58, v58 row_half_mirror row_mask:0xf bank_mask:0xf bound_ctrl:1
	s_nop 1
	v_add_f32_dpp v58, v58, v58 row_mirror row_mask:0xf bank_mask:0xf bound_ctrl:1
	v_mov_b32_e32 v56, v58
	s_nop 1
	v_permlane16_swap_b32_e32 v58, v56
	v_add_f32_e32 v58, v58, v56
	v_mov_b32_e32 v56, v58
	s_nop 1
	v_permlane32_swap_b32_e32 v58, v56
	v_add_f32_e32 v58, v58, v56
	v_fmamk_f32 v60, v58, 0x3a800000, v153
	v_rsq_f32_e32 v60, v60
	s_nop 0
	v_pk_mul_f32 v[40:41], v[40:41], v[60:61] op_sel_hi:[1,0]
	v_pk_mul_f32 v[42:43], v[42:43], v[60:61] op_sel_hi:[1,0]
	v_pk_mul_f32 v[44:45], v[44:45], v[60:61] op_sel_hi:[1,0]
	v_pk_mul_f32 v[46:47], v[46:47], v[60:61] op_sel_hi:[1,0]
	v_pk_mul_f32 v[48:49], v[48:49], v[60:61] op_sel_hi:[1,0]
	v_pk_mul_f32 v[50:51], v[50:51], v[60:61] op_sel_hi:[1,0]
	v_pk_mul_f32 v[52:53], v[52:53], v[60:61] op_sel_hi:[1,0]
	v_pk_mul_f32 v[54:55], v[54:55], v[60:61] op_sel_hi:[1,0]
	v_pk_mul_f32 v[40:41], v[0:1], v[40:41]
	v_pk_mul_f32 v[42:43], v[2:3], v[42:43]
	v_pk_mul_f32 v[44:45], v[4:5], v[44:45]
	v_pk_mul_f32 v[46:47], v[6:7], v[46:47]
	v_pk_mul_f32 v[48:49], v[8:9], v[48:49]
	v_pk_mul_f32 v[50:51], v[10:11], v[50:51]
	v_pk_mul_f32 v[52:53], v[12:13], v[52:53]
	v_pk_mul_f32 v[54:55], v[14:15], v[54:55]
	v_pk_fma_f32 v[40:41], v[214:215], v[40:41], v[198:199]
	v_pk_fma_f32 v[42:43], v[216:217], v[42:43], v[200:201]
	v_pk_fma_f32 v[44:45], v[218:219], v[44:45], v[202:203]
	v_pk_fma_f32 v[46:47], v[220:221], v[46:47], v[204:205]
	v_pk_fma_f32 v[48:49], v[222:223], v[48:49], v[206:207]
	v_pk_fma_f32 v[50:51], v[224:225], v[50:51], v[208:209]
	v_pk_fma_f32 v[52:53], v[226:227], v[52:53], v[210:211]
	v_pk_fma_f32 v[54:55], v[228:229], v[54:55], v[212:213]
	v_cvt_pk_bf16_f32 v40, v40, v41
	v_cvt_pk_bf16_f32 v41, v42, v43
	v_cvt_pk_bf16_f32 v44, v44, v45
	v_cvt_pk_bf16_f32 v45, v46, v47
	v_cvt_pk_bf16_f32 v48, v48, v49
	v_cvt_pk_bf16_f32 v49, v50, v51
	v_cvt_pk_bf16_f32 v52, v52, v53
	v_cvt_pk_bf16_f32 v53, v54, v55
	global_store_dwordx2 v100, v[40:41], s[40:41]
	global_store_dwordx2 v100, v[44:45], s[40:41] offset:512
	global_store_dwordx2 v100, v[48:49], s[40:41] offset:1024
	global_store_dwordx2 v100, v[52:53], s[40:41] offset:1536
	s_add_u32 s40, s40, 0x400000
	s_addc_u32 s41, s41, 0
	global_load_dwordx2 v[128:129], v100, s[38:39]
	global_load_dwordx2 v[130:131], v100, s[38:39] offset:512
	global_load_dwordx2 v[132:133], v100, s[38:39] offset:1024
	global_load_dwordx2 v[134:135], v100, s[38:39] offset:1536
	s_add_u32 s38, s38, 0x400000
	s_addc_u32 s39, s39, 0
	s_waitcnt vmcnt(24)
; __device__ __forceinline__ void norm_phase(const void* src_lat, int lat_f32, const float* src_ctx, int nrows, const float* gvec, const float* mods_l, int sh_off, int sc_off, bf16_t* U, const float* part, int nparts, float* ctx_out) {
;     ...
;     for (int row = gw; row < nrows; row += ngw) {
;         const int s = row < MLAT ? (row >> 13) : 4;
;         f32x4 v[4]; float ss = 0.f;
;         if (row < MLAT && !lat_f32) { const bf16_t* src = (const bf16_t*)src_lat + (size_t)row * DM + 4 * lane;
; #pragma unroll
;             for (int j = 0; j < 4; ++j) { const u32x2 w = *(const u32x2*)(src + 256 * j);
;                 v[j] = (f32x4){__uint_as_float(w.x << 16), __uint_as_float(w.x & 0xffff0000u), __uint_as_float(w.y << 16), __uint_as_float(w.y & 0xffff0000u)}; } }
;         else { const float* src = row < MLAT ? (const float*)src_lat + (size_t)row * DM : src_ctx + (size_t)(row - MLAT) * DM;
; #pragma unroll
;             for (int j = 0; j < 4; ++j) v[j] = *(const f32x4*)(src + 4 * lane + 256 * j); }
; #pragma unroll
;         for (int j = 0; j < 4; ++j) { ss += (v[j][0] * v[j][0] + v[j][1] * v[j][1]) + (v[j][2] * v[j][2] + v[j][3] * v[j][3]); }
;         if (nparts != 0 && row >= MLAT) {
;             for (int ch = 0; ch < nparts; ch += 4) {
;                 f32x4 pv[4][4];
; #pragma unroll
;                 for (int c4 = 0; c4 < 4; ++c4) { const float* pr = part + ((size_t)(ch + c4) * MCTX + (row - MLAT)) * DM + 4 * lane;
; #pragma unroll
;                     for (int j = 0; j < 4; ++j) pv[c4][j] = *(const f32x4*)(pr + 256 * j); }
; #pragma unroll
;                 for (int c4 = 0; c4 < 4; ++c4)
; #pragma unroll
;                     for (int j = 0; j < 4; ++j) v[j] = v[j] + pv[c4][j]; }
;             ss = 0.f;
; #pragma unroll
;             for (int j = 0; j < 4; ++j) { *(f32x4*)(ctx_out + (size_t)(row - MLAT) * DM + 4 * lane + 256 * j) = v[j]; ss += (v[j][0] * v[j][0] + v[j][1] * v[j][1]) + (v[j][2] * v[j][2] + v[j][3] * v[j][3]); }
;         }
;         const float rs = rsqrtf(wave_sum64(ss) * (1.0f / DM) + EPS);
;         const float* shp = mods_l + s * 6144 + sh_off + 4 * lane; const float* scp = mods_l + s * 6144 + sc_off + 4 * lane;
;         bf16_t* up = U + (size_t)row * DM + 4 * lane;
; #pragma unroll
;         for (int j = 0; j < 4; ++j) { const f32x4 sh = *(const f32x4*)(shp + 256 * j), sc = *(const f32x4*)(scp + 256 * j);
	v_pk_add_f32 v[84:85], v[84:85], 1.0 op_sel_hi:[1,0]
	v_pk_add_f32 v[86:87], v[86:87], 1.0 op_sel_hi:[1,0]
	v_pk_add_f32 v[88:89], v[88:89], 1.0 op_sel_hi:[1,0]
	v_pk_add_f32 v[90:91], v[90:91], 1.0 op_sel_hi:[1,0]
	v_pk_add_f32 v[92:93], v[92:93], 1.0 op_sel_hi:[1,0]
	v_pk_add_f32 v[94:95], v[94:95], 1.0 op_sel_hi:[1,0]
	v_pk_add_f32 v[96:97], v[96:97], 1.0 op_sel_hi:[1,0]
	v_pk_add_f32 v[98:99], v[98:99], 1.0 op_sel_hi:[1,0]
	v_lshlrev_b32_e32 v40, 16, v104
	v_and_b32_e32 v41, 0xffff0000, v104
	v_lshlrev_b32_e32 v42, 16, v105
	v_and_b32_e32 v43, 0xffff0000, v105
	v_lshlrev_b32_e32 v44, 16, v106
	v_and_b32_e32 v45, 0xffff0000, v106
	v_lshlrev_b32_e32 v46, 16, v107
	v_and_b32_e32 v47, 0xffff0000, v107
	v_lshlrev_b32_e32 v48, 16, v108
	v_and_b32_e32 v49, 0xffff0000, v108
	v_lshlrev_b32_e32 v50, 16, v109
	v_and_b32_e32 v51, 0xffff0000, v109
	v_lshlrev_b32_e32 v52, 16, v110
	v_and_b32_e32 v53, 0xffff0000, v110
	v_lshlrev_b32_e32 v54, 16, v111
	v_and_b32_e32 v55, 0xffff0000, v111
	v_mul_f32_e32 v56, v41, v41
	v_mul_f32_e32 v57, v43, v43
	v_fmac_f32_e32 v56, v40, v40
	v_fmac_f32_e32 v57, v42, v42
	v_add_f32_e32 v58, v56, v57
	v_mul_f32_e32 v56, v45, v45
	v_mul_f32_e32 v57, v47, v47
	v_fmac_f32_e32 v56, v44, v44
	v_fmac_f32_e32 v57, v46, v46
	v_add_f32_e32 v56, v56, v57
	v_add_f32_e32 v58, v58, v56
	v_mul_f32_e32 v56, v49, v49
	v_mul_f32_e32 v57, v51, v51
	v_fmac_f32_e32 v56, v48, v48
	v_fmac_f32_e32 v57, v50, v50
	v_add_f32_e32 v56, v56, v57
	v_add_f32_e32 v58, v58, v56
	v_mul_f32_e32 v56, v53, v53
	v_mul_f32_e32 v57, v55, v55
	v_fmac_f32_e32 v56, v52, v52
	v_fmac_f32_e32 v57, v54, v54
	v_add_f32_e32 v56, v56, v57
	v_add_f32_e32 v58, v58, v56
	s_nop 1
	v_add_f32_dpp v58, v58, v58 quad_perm:[1,0,3,2] row_mask:0xf bank_mask:0xf bound_ctrl:1
	s_nop 1
	v_add_f32_dpp v58, v58, v58 quad_perm:[2,3,0,1] row_mask:0xf bank_mask:0xf bound_ctrl:1
	s_nop 1
	v_add_f32_dpp v58, v58, v58 row_half_mirror row_mask:0xf bank_mask:0xf bound_ctrl:1
	s_nop 1
	v_add_f32_dpp v58, v58, v58 row_mirror row_mask:0xf bank_mask:0xf bound_ctrl:1
	v_mov_b32_e32 v56, v58
	s_nop 1
	v_permlane16_swap_b32_e32 v58, v56
	v_add_f32_e32 v58, v58, v56
	v_mov_b32_e32 v56, v58
	s_nop 1
	v_permlane32_swap_b32_e32 v58, v56
	v_add_f32_e32 v58, v58, v56
	v_fmamk_f32 v60, v58, 0x3a800000, v153
	v_rsq_f32_e32 v60, v60
	s_nop 0
	v_pk_mul_f32 v[40:41], v[40:41], v[60:61] op_sel_hi:[1,0]
	v_pk_mul_f32 v[42:43], v[42:43], v[60:61] op_sel_hi:[1,0]
	v_pk_mul_f32 v[44:45], v[44:45], v[60:61] op_sel_hi:[1,0]
	v_pk_mul_f32 v[46:47], v[46:47], v[60:61] op_sel_hi:[1,0]
	v_pk_mul_f32 v[48:49], v[48:49], v[60:61] op_sel_hi:[1,0]
	v_pk_mul_f32 v[50:51], v[50:51], v[60:61] op_sel_hi:[1,0]
	v_pk_mul_f32 v[52:53], v[52:53], v[60:61] op_sel_hi:[1,0]
	v_pk_mul_f32 v[54:55], v[54:55], v[60:61] op_sel_hi:[1,0]
	v_pk_mul_f32 v[40:41], v[0:1], v[40:41]
	v_pk_mul_f32 v[42:43], v[2:3], v[42:43]
	v_pk_mul_f32 v[44:45], v[4:5], v[44:45]
	v_pk_mul_f32 v[46:47], v[6:7], v[46:47]
	v_pk_mul_f32 v[48:49], v[8:9], v[48:49]
	v_pk_mul_f32 v[50:51], v[10:11], v[50:51]
	v_pk_mul_f32 v[52:53], v[12:13], v[52:53]
	v_pk_mul_f32 v[54:55], v[14:15], v[54:55]
	v_pk_fma_f32 v[40:41], v[84:85], v[40:41], v[68:69]
	v_pk_fma_f32 v[42:43], v[86:87], v[42:43], v[70:71]
	v_pk_fma_f32 v[44:45], v[88:89], v[44:45], v[72:73]
	v_pk_fma_f32 v[46:47], v[90:91], v[46:47], v[74:75]
	v_pk_fma_f32 v[48:49], v[92:93], v[48:49], v[76:77]
	v_pk_fma_f32 v[50:51], v[94:95], v[50:51], v[78:79]
	v_pk_fma_f32 v[52:53], v[96:97], v[52:53], v[80:81]
	v_pk_fma_f32 v[54:55], v[98:99], v[54:55], v[82:83]
	v_cvt_pk_bf16_f32 v40, v40, v41
	v_cvt_pk_bf16_f32 v41, v42, v43
	v_cvt_pk_bf16_f32 v44, v44, v45
	v_cvt_pk_bf16_f32 v45, v46, v47
	v_cvt_pk_bf16_f32 v48, v48, v49
	v_cvt_pk_bf16_f32 v49, v50, v51
	v_cvt_pk_bf16_f32 v52, v52, v53
	v_cvt_pk_bf16_f32 v53, v54, v55
	global_store_dwordx2 v100, v[40:41], s[40:41]
	global_store_dwordx2 v100, v[44:45], s[40:41] offset:512
	global_store_dwordx2 v100, v[48:49], s[40:41] offset:1024
	global_store_dwordx2 v100, v[52:53], s[40:41] offset:1536
	s_add_u32 s40, s40, 0x400000
	s_addc_u32 s41, s41, 0
	global_load_dwordx2 v[104:105], v100, s[38:39]
	global_load_dwordx2 v[106:107], v100, s[38:39] offset:512
	global_load_dwordx2 v[108:109], v100, s[38:39] offset:1024
	global_load_dwordx2 v[110:111], v100, s[38:39] offset:1536
	s_add_u32 s38, s38, 0x400000
	s_addc_u32 s39, s39, 0
	global_load_dwordx4 v[198:201], v101, s[42:43]
	global_load_dwordx4 v[202:205], v101, s[42:43] offset:1024
	global_load_dwordx4 v[206:209], v101, s[42:43] offset:2048
	global_load_dwordx4 v[210:213], v101, s[42:43] offset:3072
	global_load_dwordx4 v[214:217], v101, s[44:45]
	global_load_dwordx4 v[218:221], v101, s[44:45] offset:1024
	global_load_dwordx4 v[222:225], v101, s[44:45] offset:2048
	global_load_dwordx4 v[226:229], v101, s[44:45] offset:3072
	s_add_u32 s42, s42, 0x6000
	s_addc_u32 s43, s43, 0
	s_add_u32 s44, s44, 0x6000
	s_addc_u32 s45, s45, 0
	s_waitcnt vmcnt(32)
; __device__ __forceinline__ void norm_phase(const void* src_lat, int lat_f32, const float* src_ctx, int nrows, const float* gvec, const float* mods_l, int sh_off, int sc_off, bf16_t* U, const float* part, int nparts, float* ctx_out) {
;     ...
;     for (int row = gw; row < nrows; row += ngw) {
;         const int s = row < MLAT ? (row >> 13) : 4;
;         f32x4 v[4]; float ss = 0.f;
;         if (row < MLAT && !lat_f32) { const bf16_t* src = (const bf16_t*)src_lat + (size_t)row * DM + 4 * lane;
; #pragma unroll
;             for (int j = 0; j < 4; ++j) { const u32x2 w = *(const u32x2*)(src + 256 * j);
;                 v[j] = (f32x4){__uint_as_float(w.x << 16), __uint_as_float(w.x & 0xffff0000u), __uint_as_float(w.y << 16), __uint_as_float(w.y & 0xffff0000u)}; } }
;         else { const float* src = row < MLAT ? (const float*)src_lat + (size_t)row * DM : src_ctx + (size_t)(row - MLAT) * DM;
; #pragma unroll
;             for (int j = 0; j < 4; ++j) v[j] = *(const f32x4*)(src + 4 * lane + 256 * j); }
; #pragma unroll
;         for (int j = 0; j < 4; ++j) { ss += (v[j][0] * v[j][0] + v[j][1] * v[j][1]) + (v[j][2] * v[j][2] + v[j][3] * v[j][3]); }
;         if (nparts != 0 && row >= MLAT) {
;             for (int ch = 0; ch < nparts; ch += 4) {
;                 f32x4 pv[4][4];
; #pragma unroll
;                 for (int c4 = 0; c4 < 4; ++c4) { const float* pr = part + ((size_t)(ch + c4) * MCTX + (row - MLAT)) * DM + 4 * lane;
; #pragma unroll
;                     for (int j = 0; j < 4; ++j) pv[c4][j] = *(const f32x4*)(pr + 256 * j); }
; #pragma unroll
;                 for (int c4 = 0; c4 < 4; ++c4)
; #pragma unroll
;                     for (int j = 0; j < 4; ++j) v[j] = v[j] + pv[c4][j]; }
;             ss = 0.f;
; #pragma unroll
;             for (int j = 0; j < 4; ++j) { *(f32x4*)(ctx_out + (size_t)(row - MLAT) * DM + 4 * lane + 256 * j) = v[j]; ss += (v[j][0] * v[j][0] + v[j][1] * v[j][1]) + (v[j][2] * v[j][2] + v[j][3] * v[j][3]); }
;         }
;         const float rs = rsqrtf(wave_sum64(ss) * (1.0f / DM) + EPS);
;         const float* shp = mods_l + s * 6144 + sh_off + 4 * lane; const float* scp = mods_l + s * 6144 + sc_off + 4 * lane;
;         bf16_t* up = U + (size_t)row * DM + 4 * lane;
; #pragma unroll
;         for (int j = 0; j < 4; ++j) { const f32x4 sh = *(const f32x4*)(shp + 256 * j), sc = *(const f32x4*)(scp + 256 * j);
	v_lshlrev_b32_e32 v40, 16, v112
	v_and_b32_e32 v41, 0xffff0000, v112
	v_lshlrev_b32_e32 v42, 16, v113
	v_and_b32_e32 v43, 0xffff0000, v113
	v_lshlrev_b32_e32 v44, 16, v114
	v_and_b32_e32 v45, 0xffff0000, v114
	v_lshlrev_b32_e32 v46, 16, v115
	v_and_b32_e32 v47, 0xffff0000, v115
	v_lshlrev_b32_e32 v48, 16, v116
	v_and_b32_e32 v49, 0xffff0000, v116
	v_lshlrev_b32_e32 v50, 16, v117
	v_and_b32_e32 v51, 0xffff0000, v117
	v_lshlrev_b32_e32 v52, 16, v118
	v_and_b32_e32 v53, 0xffff0000, v118
	v_lshlrev_b32_e32 v54, 16, v119
	v_and_b32_e32 v55, 0xffff0000, v119
	v_mul_f32_e32 v56, v41, v41
	v_mul_f32_e32 v57, v43, v43
	v_fmac_f32_e32 v56, v40, v40
	v_fmac_f32_e32 v57, v42, v42
	v_add_f32_e32 v58, v56, v57
	v_mul_f32_e32 v56, v45, v45
	v_mul_f32_e32 v57, v47, v47
	v_fmac_f32_e32 v56, v44, v44
	v_fmac_f32_e32 v57, v46, v46
	v_add_f32_e32 v56, v56, v57
	v_add_f32_e32 v58, v58, v56
	v_mul_f32_e32 v56, v49, v49
	v_mul_f32_e32 v57, v51, v51
	v_fmac_f32_e32 v56, v48, v48
	v_fmac_f32_e32 v57, v50, v50
	v_add_f32_e32 v56, v56, v57
	v_add_f32_e32 v58, v58, v56
	v_mul_f32_e32 v56, v53, v53
	v_mul_f32_e32 v57, v55, v55
	v_fmac_f32_e32 v56, v52, v52
	v_fmac_f32_e32 v57, v54, v54
	v_add_f32_e32 v56, v56, v57
	v_add_f32_e32 v58, v58, v56
	s_nop 1
	v_add_f32_dpp v58, v58, v58 quad_perm:[1,0,3,2] row_mask:0xf bank_mask:0xf bound_ctrl:1
	s_nop 1
	v_add_f32_dpp v58, v58, v58 quad_perm:[2,3,0,1] row_mask:0xf bank_mask:0xf bound_ctrl:1
	s_nop 1
	v_add_f32_dpp v58, v58, v58 row_half_mirror row_mask:0xf bank_mask:0xf bound_ctrl:1
	s_nop 1
	v_add_f32_dpp v58, v58, v58 row_mirror row_mask:0xf bank_mask:0xf bound_ctrl:1
	v_mov_b32_e32 v56, v58
	s_nop 1
	v_permlane16_swap_b32_e32 v58, v56
	v_add_f32_e32 v58, v58, v56
	v_mov_b32_e32 v56, v58
	s_nop 1
	v_permlane32_swap_b32_e32 v58, v56
	v_add_f32_e32 v58, v58, v56
	v_fmamk_f32 v60, v58, 0x3a800000, v153
	v_rsq_f32_e32 v60, v60
	s_nop 0
	v_pk_mul_f32 v[40:41], v[40:41], v[60:61] op_sel_hi:[1,0]
	v_pk_mul_f32 v[42:43], v[42:43], v[60:61] op_sel_hi:[1,0]
	v_pk_mul_f32 v[44:45], v[44:45], v[60:61] op_sel_hi:[1,0]
	v_pk_mul_f32 v[46:47], v[46:47], v[60:61] op_sel_hi:[1,0]
	v_pk_mul_f32 v[48:49], v[48:49], v[60:61] op_sel_hi:[1,0]
	v_pk_mul_f32 v[50:51], v[50:51], v[60:61] op_sel_hi:[1,0]
	v_pk_mul_f32 v[52:53], v[52:53], v[60:61] op_sel_hi:[1,0]
	v_pk_mul_f32 v[54:55], v[54:55], v[60:61] op_sel_hi:[1,0]
	v_pk_mul_f32 v[40:41], v[0:1], v[40:41]
	v_pk_mul_f32 v[42:43], v[2:3], v[42:43]
	v_pk_mul_f32 v[44:45], v[4:5], v[44:45]
	v_pk_mul_f32 v[46:47], v[6:7], v[46:47]
	v_pk_mul_f32 v[48:49], v[8:9], v[48:49]
	v_pk_mul_f32 v[50:51], v[10:11], v[50:51]
	v_pk_mul_f32 v[52:53], v[12:13], v[52:53]
	v_pk_mul_f32 v[54:55], v[14:15], v[54:55]
	v_pk_fma_f32 v[40:41], v[84:85], v[40:41], v[68:69]
	v_pk_fma_f32 v[42:43], v[86:87], v[42:43], v[70:71]
	v_pk_fma_f32 v[44:45], v[88:89], v[44:45], v[72:73]
	v_pk_fma_f32 v[46:47], v[90:91], v[46:47], v[74:75]
	v_pk_fma_f32 v[48:49], v[92:93], v[48:49], v[76:77]
	v_pk_fma_f32 v[50:51], v[94:95], v[50:51], v[78:79]
	v_pk_fma_f32 v[52:53], v[96:97], v[52:53], v[80:81]
	v_pk_fma_f32 v[54:55], v[98:99], v[54:55], v[82:83]
	v_cvt_pk_bf16_f32 v40, v40, v41
	v_cvt_pk_bf16_f32 v41, v42, v43
	v_cvt_pk_bf16_f32 v44, v44, v45
	v_cvt_pk_bf16_f32 v45, v46, v47
	v_cvt_pk_bf16_f32 v48, v48, v49
	v_cvt_pk_bf16_f32 v49, v50, v51
	v_cvt_pk_bf16_f32 v52, v52, v53
	v_cvt_pk_bf16_f32 v53, v54, v55
	global_store_dwordx2 v100, v[40:41], s[40:41]
	global_store_dwordx2 v100, v[44:45], s[40:41] offset:512
	global_store_dwordx2 v100, v[48:49], s[40:41] offset:1024
	global_store_dwordx2 v100, v[52:53], s[40:41] offset:1536
	s_add_u32 s40, s40, 0x400000
	s_addc_u32 s41, s41, 0
	global_load_dwordx2 v[112:113], v100, s[38:39]
	global_load_dwordx2 v[114:115], v100, s[38:39] offset:512
	global_load_dwordx2 v[116:117], v100, s[38:39] offset:1024
	global_load_dwordx2 v[118:119], v100, s[38:39] offset:1536
	s_add_u32 s38, s38, 0x400000
	s_addc_u32 s39, s39, 0
	s_waitcnt vmcnt(32)
	v_lshlrev_b32_e32 v40, 16, v120
	v_and_b32_e32 v41, 0xffff0000, v120
	v_lshlrev_b32_e32 v42, 16, v121
	v_and_b32_e32 v43, 0xffff0000, v121
	v_lshlrev_b32_e32 v44, 16, v122
	v_and_b32_e32 v45, 0xffff0000, v122
	v_lshlrev_b32_e32 v46, 16, v123
	v_and_b32_e32 v47, 0xffff0000, v123
	v_lshlrev_b32_e32 v48, 16, v124
	v_and_b32_e32 v49, 0xffff0000, v124
	v_lshlrev_b32_e32 v50, 16, v125
	v_and_b32_e32 v51, 0xffff0000, v125
	v_lshlrev_b32_e32 v52, 16, v126
	v_and_b32_e32 v53, 0xffff0000, v126
	v_lshlrev_b32_e32 v54, 16, v127
	v_and_b32_e32 v55, 0xffff0000, v127
	v_mul_f32_e32 v56, v41, v41
	v_mul_f32_e32 v57, v43, v43
	v_fmac_f32_e32 v56, v40, v40
	v_fmac_f32_e32 v57, v42, v42
	v_add_f32_e32 v58, v56, v57
	v_mul_f32_e32 v56, v45, v45
	v_mul_f32_e32 v57, v47, v47
	v_fmac_f32_e32 v56, v44, v44
	v_fmac_f32_e32 v57, v46, v46
	v_add_f32_e32 v56, v56, v57
	v_add_f32_e32 v58, v58, v56
	v_mul_f32_e32 v56, v49, v49
	v_mul_f32_e32 v57, v51, v51
	v_fmac_f32_e32 v56, v48, v48
	v_fmac_f32_e32 v57, v50, v50
	v_add_f32_e32 v56, v56, v57
	v_add_f32_e32 v58, v58, v56
	v_mul_f32_e32 v56, v53, v53
	v_mul_f32_e32 v57, v55, v55
	v_fmac_f32_e32 v56, v52, v52
	v_fmac_f32_e32 v57, v54, v54
	v_add_f32_e32 v56, v56, v57
	v_add_f32_e32 v58, v58, v56
	s_nop 1
	v_add_f32_dpp v58, v58, v58 quad_perm:[1,0,3,2] row_mask:0xf bank_mask:0xf bound_ctrl:1
	s_nop 1
	v_add_f32_dpp v58, v58, v58 quad_perm:[2,3,0,1] row_mask:0xf bank_mask:0xf bound_ctrl:1
	s_nop 1
	v_add_f32_dpp v58, v58, v58 row_half_mirror row_mask:0xf bank_mask:0xf bound_ctrl:1
	s_nop 1
	v_add_f32_dpp v58, v58, v58 row_mirror row_mask:0xf bank_mask:0xf bound_ctrl:1
	v_mov_b32_e32 v56, v58
	s_nop 1
	v_permlane16_swap_b32_e32 v58, v56
; __device__ __forceinline__ void norm_phase(const void* src_lat, int lat_f32, const float* src_ctx, int nrows, const float* gvec, const float* mods_l, int sh_off, int sc_off, bf16_t* U, const float* part, int nparts, float* ctx_out) {
;     ...
;     for (int row = gw; row < nrows; row += ngw) {
;         const int s = row < MLAT ? (row >> 13) : 4;
;         f32x4 v[4]; float ss = 0.f;
;         if (row < MLAT && !lat_f32) { const bf16_t* src = (const bf16_t*)src_lat + (size_t)row * DM + 4 * lane;
; #pragma unroll
;             for (int j = 0; j < 4; ++j) { const u32x2 w = *(const u32x2*)(src + 256 * j);
;                 v[j] = (f32x4){__uint_as_float(w.x << 16), __uint_as_float(w.x & 0xffff0000u), __uint_as_float(w.y << 16), __uint_as_float(w.y & 0xffff0000u)}; } }
;         else { const float* src = row < MLAT ? (const float*)src_lat + (size_t)row * DM : src_ctx + (size_t)(row - MLAT) * DM;
; #pragma unroll
;             for (int j = 0; j < 4; ++j) v[j] = *(const f32x4*)(src + 4 * lane + 256 * j); }
; #pragma unroll
;         for (int j = 0; j < 4; ++j) { ss += (v[j][0] * v[j][0] + v[j][1] * v[j][1]) + (v[j][2] * v[j][2] + v[j][3] * v[j][3]); }
;         if (nparts != 0 && row >= MLAT) {
;             for (int ch = 0; ch < nparts; ch += 4) {
;                 f32x4 pv[4][4];
; #pragma unroll
;                 for (int c4 = 0; c4 < 4; ++c4) { const float* pr = part + ((size_t)(ch + c4) * MCTX + (row - MLAT)) * DM + 4 * lane;
; #pragma unroll
;                     for (int j = 0; j < 4; ++j) pv[c4][j] = *(const f32x4*)(pr + 256 * j); }
; #pragma unroll
;                 for (int c4 = 0; c4 < 4; ++c4)
; #pragma unroll
;                     for (int j = 0; j < 4; ++j) v[j] = v[j] + pv[c4][j]; }
;             ss = 0.f;
; #pragma unroll
;             for (int j = 0; j < 4; ++j) { *(f32x4*)(ctx_out + (size_t)(row - MLAT) * DM + 4 * lane + 256 * j) = v[j]; ss += (v[j][0] * v[j][0] + v[j][1] * v[j][1]) + (v[j][2] * v[j][2] + v[j][3] * v[j][3]); }
;         }
;         const float rs = rsqrtf(wave_sum64(ss) * (1.0f / DM) + EPS);
;         const float* shp = mods_l + s * 6144 + sh_off + 4 * lane; const float* scp = mods_l + s * 6144 + sc_off + 4 * lane;
;         bf16_t* up = U + (size_t)row * DM + 4 * lane;
; #pragma unroll
;         for (int j = 0; j < 4; ++j) { const f32x4 sh = *(const f32x4*)(shp + 256 * j), sc = *(const f32x4*)(scp + 256 * j);
	v_add_f32_e32 v58, v58, v56
	v_mov_b32_e32 v56, v58
	s_nop 1
	v_permlane32_swap_b32_e32 v58, v56
	v_add_f32_e32 v58, v58, v56
	v_fmamk_f32 v60, v58, 0x3a800000, v153
	v_rsq_f32_e32 v60, v60
	s_nop 0
	v_pk_mul_f32 v[40:41], v[40:41], v[60:61] op_sel_hi:[1,0]
	v_pk_mul_f32 v[42:43], v[42:43], v[60:61] op_sel_hi:[1,0]
	v_pk_mul_f32 v[44:45], v[44:45], v[60:61] op_sel_hi:[1,0]
	v_pk_mul_f32 v[46:47], v[46:47], v[60:61] op_sel_hi:[1,0]
	v_pk_mul_f32 v[48:49], v[48:49], v[60:61] op_sel_hi:[1,0]
	v_pk_mul_f32 v[50:51], v[50:51], v[60:61] op_sel_hi:[1,0]
	v_pk_mul_f32 v[52:53], v[52:53], v[60:61] op_sel_hi:[1,0]
	v_pk_mul_f32 v[54:55], v[54:55], v[60:61] op_sel_hi:[1,0]
	v_pk_mul_f32 v[40:41], v[0:1], v[40:41]
	v_pk_mul_f32 v[42:43], v[2:3], v[42:43]
	v_pk_mul_f32 v[44:45], v[4:5], v[44:45]
	v_pk_mul_f32 v[46:47], v[6:7], v[46:47]
	v_pk_mul_f32 v[48:49], v[8:9], v[48:49]
	v_pk_mul_f32 v[50:51], v[10:11], v[50:51]
	v_pk_mul_f32 v[52:53], v[12:13], v[52:53]
	v_pk_mul_f32 v[54:55], v[14:15], v[54:55]
	v_pk_fma_f32 v[40:41], v[84:85], v[40:41], v[68:69]
	v_pk_fma_f32 v[42:43], v[86:87], v[42:43], v[70:71]
	v_pk_fma_f32 v[44:45], v[88:89], v[44:45], v[72:73]
	v_pk_fma_f32 v[46:47], v[90:91], v[46:47], v[74:75]
	v_pk_fma_f32 v[48:49], v[92:93], v[48:49], v[76:77]
	v_pk_fma_f32 v[50:51], v[94:95], v[50:51], v[78:79]
	v_pk_fma_f32 v[52:53], v[96:97], v[52:53], v[80:81]
	v_pk_fma_f32 v[54:55], v[98:99], v[54:55], v[82:83]
	v_cvt_pk_bf16_f32 v40, v40, v41
	v_cvt_pk_bf16_f32 v41, v42, v43
	v_cvt_pk_bf16_f32 v44, v44, v45
	v_cvt_pk_bf16_f32 v45, v46, v47
	v_cvt_pk_bf16_f32 v48, v48, v49
	v_cvt_pk_bf16_f32 v49, v50, v51
	v_cvt_pk_bf16_f32 v52, v52, v53
	v_cvt_pk_bf16_f32 v53, v54, v55
	global_store_dwordx2 v100, v[40:41], s[40:41]
	global_store_dwordx2 v100, v[44:45], s[40:41] offset:512
	global_store_dwordx2 v100, v[48:49], s[40:41] offset:1024
	global_store_dwordx2 v100, v[52:53], s[40:41] offset:1536
	s_add_u32 s40, s40, 0x400000
	s_addc_u32 s41, s41, 0
	global_load_dwordx2 v[120:121], v100, s[38:39]
	global_load_dwordx2 v[122:123], v100, s[38:39] offset:512
	global_load_dwordx2 v[124:125], v100, s[38:39] offset:1024
	global_load_dwordx2 v[126:127], v100, s[38:39] offset:1536
	s_add_u32 s38, s38, 0x400000
	s_addc_u32 s39, s39, 0
	s_waitcnt vmcnt(32)
	v_lshlrev_b32_e32 v40, 16, v128
	v_and_b32_e32 v41, 0xffff0000, v128
	v_lshlrev_b32_e32 v42, 16, v129
	v_and_b32_e32 v43, 0xffff0000, v129
	v_lshlrev_b32_e32 v44, 16, v130
	v_and_b32_e32 v45, 0xffff0000, v130
	v_lshlrev_b32_e32 v46, 16, v131
	v_and_b32_e32 v47, 0xffff0000, v131
	v_lshlrev_b32_e32 v48, 16, v132
	v_and_b32_e32 v49, 0xffff0000, v132
	v_lshlrev_b32_e32 v50, 16, v133
	v_and_b32_e32 v51, 0xffff0000, v133
	v_lshlrev_b32_e32 v52, 16, v134
	v_and_b32_e32 v53, 0xffff0000, v134
	v_lshlrev_b32_e32 v54, 16, v135
	v_and_b32_e32 v55, 0xffff0000, v135
	v_mul_f32_e32 v56, v41, v41
	v_mul_f32_e32 v57, v43, v43
	v_fmac_f32_e32 v56, v40, v40
	v_fmac_f32_e32 v57, v42, v42
	v_add_f32_e32 v58, v56, v57
	v_mul_f32_e32 v56, v45, v45
	v_mul_f32_e32 v57, v47, v47
	v_fmac_f32_e32 v56, v44, v44
	v_fmac_f32_e32 v57, v46, v46
	v_add_f32_e32 v56, v56, v57
	v_add_f32_e32 v58, v58, v56
	v_mul_f32_e32 v56, v49, v49
	v_mul_f32_e32 v57, v51, v51
	v_fmac_f32_e32 v56, v48, v48
	v_fmac_f32_e32 v57, v50, v50
	v_add_f32_e32 v56, v56, v57
	v_add_f32_e32 v58, v58, v56
	v_mul_f32_e32 v56, v53, v53
	v_mul_f32_e32 v57, v55, v55
	v_fmac_f32_e32 v56, v52, v52
	v_fmac_f32_e32 v57, v54, v54
	v_add_f32_e32 v56, v56, v57
	v_add_f32_e32 v58, v58, v56
	s_nop 1
	v_add_f32_dpp v58, v58, v58 quad_perm:[1,0,3,2] row_mask:0xf bank_mask:0xf bound_ctrl:1
	s_nop 1
	v_add_f32_dpp v58, v58, v58 quad_perm:[2,3,0,1] row_mask:0xf bank_mask:0xf bound_ctrl:1
	s_nop 1
	v_add_f32_dpp v58, v58, v58 row_half_mirror row_mask:0xf bank_mask:0xf bound_ctrl:1
	s_nop 1
	v_add_f32_dpp v58, v58, v58 row_mirror row_mask:0xf bank_mask:0xf bound_ctrl:1
	v_mov_b32_e32 v56, v58
	s_nop 1
	v_permlane16_swap_b32_e32 v58, v56
	v_add_f32_e32 v58, v58, v56
	v_mov_b32_e32 v56, v58
	s_nop 1
	v_permlane32_swap_b32_e32 v58, v56
	v_add_f32_e32 v58, v58, v56
	v_fmamk_f32 v60, v58, 0x3a800000, v153
	v_rsq_f32_e32 v60, v60
	s_nop 0
	v_pk_mul_f32 v[40:41], v[40:41], v[60:61] op_sel_hi:[1,0]
	v_pk_mul_f32 v[42:43], v[42:43], v[60:61] op_sel_hi:[1,0]
	v_pk_mul_f32 v[44:45], v[44:45], v[60:61] op_sel_hi:[1,0]
	v_pk_mul_f32 v[46:47], v[46:47], v[60:61] op_sel_hi:[1,0]
	v_pk_mul_f32 v[48:49], v[48:49], v[60:61] op_sel_hi:[1,0]
	v_pk_mul_f32 v[50:51], v[50:51], v[60:61] op_sel_hi:[1,0]
	v_pk_mul_f32 v[52:53], v[52:53], v[60:61] op_sel_hi:[1,0]
	v_pk_mul_f32 v[54:55], v[54:55], v[60:61] op_sel_hi:[1,0]
	v_pk_mul_f32 v[40:41], v[0:1], v[40:41]
	v_pk_mul_f32 v[42:43], v[2:3], v[42:43]
	v_pk_mul_f32 v[44:45], v[4:5], v[44:45]
	v_pk_mul_f32 v[46:47], v[6:7], v[46:47]
	v_pk_mul_f32 v[48:49], v[8:9], v[48:49]
	v_pk_mul_f32 v[50:51], v[10:11], v[50:51]
	v_pk_mul_f32 v[52:53], v[12:13], v[52:53]
	v_pk_mul_f32 v[54:55], v[14:15], v[54:55]
	v_pk_fma_f32 v[40:41], v[84:85], v[40:41], v[68:69]
	v_pk_fma_f32 v[42:43], v[86:87], v[42:43], v[70:71]
	v_pk_fma_f32 v[44:45], v[88:89], v[44:45], v[72:73]
	v_pk_fma_f32 v[46:47], v[90:91], v[46:47], v[74:75]
	v_pk_fma_f32 v[48:49], v[92:93], v[48:49], v[76:77]
	v_pk_fma_f32 v[50:51], v[94:95], v[50:51], v[78:79]
	v_pk_fma_f32 v[52:53], v[96:97], v[52:53], v[80:81]
	v_pk_fma_f32 v[54:55], v[98:99], v[54:55], v[82:83]
	v_cvt_pk_bf16_f32 v40, v40, v41
	v_cvt_pk_bf16_f32 v41, v42, v43
	v_cvt_pk_bf16_f32 v44, v44, v45
	v_cvt_pk_bf16_f32 v45, v46, v47
	v_cvt_pk_bf16_f32 v48, v48, v49
	v_cvt_pk_bf16_f32 v49, v50, v51
	v_cvt_pk_bf16_f32 v52, v52, v53
	v_cvt_pk_bf16_f32 v53, v54, v55
	global_store_dwordx2 v100, v[40:41], s[40:41]
	global_store_dwordx2 v100, v[44:45], s[40:41] offset:512
	global_store_dwordx2 v100, v[48:49], s[40:41] offset:1024
	global_store_dwordx2 v100, v[52:53], s[40:41] offset:1536
	s_add_u32 s40, s40, 0x400000
	s_addc_u32 s41, s41, 0
	global_load_dwordx2 v[128:129], v100, s[38:39]
	global_load_dwordx2 v[130:131], v100, s[38:39] offset:512
	global_load_dwordx2 v[132:133], v100, s[38:39] offset:1024
	global_load_dwordx2 v[134:135], v100, s[38:39] offset:1536
	s_add_u32 s38, s38, 0x400000
	s_addc_u32 s39, s39, 0
	s_waitcnt vmcnt(24)
; __device__ __forceinline__ void norm_phase(const void* src_lat, int lat_f32, const float* src_ctx, int nrows, const float* gvec, const float* mods_l, int sh_off, int sc_off, bf16_t* U, const float* part, int nparts, float* ctx_out) {
;     ...
;     for (int row = gw; row < nrows; row += ngw) {
;         const int s = row < MLAT ? (row >> 13) : 4;
;         f32x4 v[4]; float ss = 0.f;
;         if (row < MLAT && !lat_f32) { const bf16_t* src = (const bf16_t*)src_lat + (size_t)row * DM + 4 * lane;
; #pragma unroll
;             for (int j = 0; j < 4; ++j) { const u32x2 w = *(const u32x2*)(src + 256 * j);
;                 v[j] = (f32x4){__uint_as_float(w.x << 16), __uint_as_float(w.x & 0xffff0000u), __uint_as_float(w.y << 16), __uint_as_float(w.y & 0xffff0000u)}; } }
;         else { const float* src = row < MLAT ? (const float*)src_lat + (size_t)row * DM : src_ctx + (size_t)(row - MLAT) * DM;
; #pragma unroll
;             for (int j = 0; j < 4; ++j) v[j] = *(const f32x4*)(src + 4 * lane + 256 * j); }
; #pragma unroll
;         for (int j = 0; j < 4; ++j) { ss += (v[j][0] * v[j][0] + v[j][1] * v[j][1]) + (v[j][2] * v[j][2] + v[j][3] * v[j][3]); }
;         if (nparts != 0 && row >= MLAT) {
;             for (int ch = 0; ch < nparts; ch += 4) {
;                 f32x4 pv[4][4];
; #pragma unroll
;                 for (int c4 = 0; c4 < 4; ++c4) { const float* pr = part + ((size_t)(ch + c4) * MCTX + (row - MLAT)) * DM + 4 * lane;
; #pragma unroll
;                     for (int j = 0; j < 4; ++j) pv[c4][j] = *(const f32x4*)(pr + 256 * j); }
; #pragma unroll
;                 for (int c4 = 0; c4 < 4; ++c4)
; #pragma unroll
;                     for (int j = 0; j < 4; ++j) v[j] = v[j] + pv[c4][j]; }
;             ss = 0.f;
; #pragma unroll
;             for (int j = 0; j < 4; ++j) { *(f32x4*)(ctx_out + (size_t)(row - MLAT) * DM + 4 * lane + 256 * j) = v[j]; ss += (v[j][0] * v[j][0] + v[j][1] * v[j][1]) + (v[j][2] * v[j][2] + v[j][3] * v[j][3]); }
;         }
;         const float rs = rsqrtf(wave_sum64(ss) * (1.0f / DM) + EPS);
;         const float* shp = mods_l + s * 6144 + sh_off + 4 * lane; const float* scp = mods_l + s * 6144 + sc_off + 4 * lane;
;         bf16_t* up = U + (size_t)row * DM + 4 * lane;
; #pragma unroll
;         for (int j = 0; j < 4; ++j) { const f32x4 sh = *(const f32x4*)(shp + 256 * j), sc = *(const f32x4*)(scp + 256 * j);
	v_pk_add_f32 v[214:215], v[214:215], 1.0 op_sel_hi:[1,0]
	v_pk_add_f32 v[216:217], v[216:217], 1.0 op_sel_hi:[1,0]
	v_pk_add_f32 v[218:219], v[218:219], 1.0 op_sel_hi:[1,0]
	v_pk_add_f32 v[220:221], v[220:221], 1.0 op_sel_hi:[1,0]
	v_pk_add_f32 v[222:223], v[222:223], 1.0 op_sel_hi:[1,0]
	v_pk_add_f32 v[224:225], v[224:225], 1.0 op_sel_hi:[1,0]
	v_pk_add_f32 v[226:227], v[226:227], 1.0 op_sel_hi:[1,0]
	v_pk_add_f32 v[228:229], v[228:229], 1.0 op_sel_hi:[1,0]
	v_lshlrev_b32_e32 v40, 16, v104
	v_and_b32_e32 v41, 0xffff0000, v104
	v_lshlrev_b32_e32 v42, 16, v105
	v_and_b32_e32 v43, 0xffff0000, v105
	v_lshlrev_b32_e32 v44, 16, v106
	v_and_b32_e32 v45, 0xffff0000, v106
	v_lshlrev_b32_e32 v46, 16, v107
	v_and_b32_e32 v47, 0xffff0000, v107
	v_lshlrev_b32_e32 v48, 16, v108
	v_and_b32_e32 v49, 0xffff0000, v108
	v_lshlrev_b32_e32 v50, 16, v109
	v_and_b32_e32 v51, 0xffff0000, v109
	v_lshlrev_b32_e32 v52, 16, v110
	v_and_b32_e32 v53, 0xffff0000, v110
	v_lshlrev_b32_e32 v54, 16, v111
	v_and_b32_e32 v55, 0xffff0000, v111
	v_mul_f32_e32 v56, v41, v41
	v_mul_f32_e32 v57, v43, v43
	v_fmac_f32_e32 v56, v40, v40
	v_fmac_f32_e32 v57, v42, v42
	v_add_f32_e32 v58, v56, v57
	v_mul_f32_e32 v56, v45, v45
	v_mul_f32_e32 v57, v47, v47
	v_fmac_f32_e32 v56, v44, v44
	v_fmac_f32_e32 v57, v46, v46
	v_add_f32_e32 v56, v56, v57
	v_add_f32_e32 v58, v58, v56
	v_mul_f32_e32 v56, v49, v49
	v_mul_f32_e32 v57, v51, v51
	v_fmac_f32_e32 v56, v48, v48
	v_fmac_f32_e32 v57, v50, v50
	v_add_f32_e32 v56, v56, v57
	v_add_f32_e32 v58, v58, v56
	v_mul_f32_e32 v56, v53, v53
	v_mul_f32_e32 v57, v55, v55
	v_fmac_f32_e32 v56, v52, v52
	v_fmac_f32_e32 v57, v54, v54
	v_add_f32_e32 v56, v56, v57
	v_add_f32_e32 v58, v58, v56
	s_nop 1
	v_add_f32_dpp v58, v58, v58 quad_perm:[1,0,3,2] row_mask:0xf bank_mask:0xf bound_ctrl:1
	s_nop 1
	v_add_f32_dpp v58, v58, v58 quad_perm:[2,3,0,1] row_mask:0xf bank_mask:0xf bound_ctrl:1
	s_nop 1
	v_add_f32_dpp v58, v58, v58 row_half_mirror row_mask:0xf bank_mask:0xf bound_ctrl:1
	s_nop 1
	v_add_f32_dpp v58, v58, v58 row_mirror row_mask:0xf bank_mask:0xf bound_ctrl:1
	v_mov_b32_e32 v56, v58
	s_nop 1
	v_permlane16_swap_b32_e32 v58, v56
	v_add_f32_e32 v58, v58, v56
	v_mov_b32_e32 v56, v58
	s_nop 1
	v_permlane32_swap_b32_e32 v58, v56
	v_add_f32_e32 v58, v58, v56
	v_fmamk_f32 v60, v58, 0x3a800000, v153
	v_rsq_f32_e32 v60, v60
	s_nop 0
	v_pk_mul_f32 v[40:41], v[40:41], v[60:61] op_sel_hi:[1,0]
	v_pk_mul_f32 v[42:43], v[42:43], v[60:61] op_sel_hi:[1,0]
	v_pk_mul_f32 v[44:45], v[44:45], v[60:61] op_sel_hi:[1,0]
	v_pk_mul_f32 v[46:47], v[46:47], v[60:61] op_sel_hi:[1,0]
	v_pk_mul_f32 v[48:49], v[48:49], v[60:61] op_sel_hi:[1,0]
	v_pk_mul_f32 v[50:51], v[50:51], v[60:61] op_sel_hi:[1,0]
	v_pk_mul_f32 v[52:53], v[52:53], v[60:61] op_sel_hi:[1,0]
	v_pk_mul_f32 v[54:55], v[54:55], v[60:61] op_sel_hi:[1,0]
	v_pk_mul_f32 v[40:41], v[0:1], v[40:41]
	v_pk_mul_f32 v[42:43], v[2:3], v[42:43]
	v_pk_mul_f32 v[44:45], v[4:5], v[44:45]
	v_pk_mul_f32 v[46:47], v[6:7], v[46:47]
	v_pk_mul_f32 v[48:49], v[8:9], v[48:49]
	v_pk_mul_f32 v[50:51], v[10:11], v[50:51]
	v_pk_mul_f32 v[52:53], v[12:13], v[52:53]
	v_pk_mul_f32 v[54:55], v[14:15], v[54:55]
	v_pk_fma_f32 v[40:41], v[214:215], v[40:41], v[198:199]
	v_pk_fma_f32 v[42:43], v[216:217], v[42:43], v[200:201]
	v_pk_fma_f32 v[44:45], v[218:219], v[44:45], v[202:203]
	v_pk_fma_f32 v[46:47], v[220:221], v[46:47], v[204:205]
	v_pk_fma_f32 v[48:49], v[222:223], v[48:49], v[206:207]
	v_pk_fma_f32 v[50:51], v[224:225], v[50:51], v[208:209]
	v_pk_fma_f32 v[52:53], v[226:227], v[52:53], v[210:211]
	v_pk_fma_f32 v[54:55], v[228:229], v[54:55], v[212:213]
	v_cvt_pk_bf16_f32 v40, v40, v41
	v_cvt_pk_bf16_f32 v41, v42, v43
	v_cvt_pk_bf16_f32 v44, v44, v45
	v_cvt_pk_bf16_f32 v45, v46, v47
	v_cvt_pk_bf16_f32 v48, v48, v49
	v_cvt_pk_bf16_f32 v49, v50, v51
	v_cvt_pk_bf16_f32 v52, v52, v53
	v_cvt_pk_bf16_f32 v53, v54, v55
	global_store_dwordx2 v100, v[40:41], s[40:41]
	global_store_dwordx2 v100, v[44:45], s[40:41] offset:512
	global_store_dwordx2 v100, v[48:49], s[40:41] offset:1024
	global_store_dwordx2 v100, v[52:53], s[40:41] offset:1536
	s_add_u32 s40, s40, 0x400000
	s_addc_u32 s41, s41, 0
	global_load_dwordx2 v[104:105], v100, s[38:39]
	global_load_dwordx2 v[106:107], v100, s[38:39] offset:512
	global_load_dwordx2 v[108:109], v100, s[38:39] offset:1024
	global_load_dwordx2 v[110:111], v100, s[38:39] offset:1536
	s_add_u32 s38, s38, 0x400000
	s_addc_u32 s39, s39, 0
	global_load_dwordx4 v[68:71], v101, s[42:43]
	global_load_dwordx4 v[72:75], v101, s[42:43] offset:1024
	global_load_dwordx4 v[76:79], v101, s[42:43] offset:2048
	global_load_dwordx4 v[80:83], v101, s[42:43] offset:3072
	global_load_dwordx4 v[84:87], v101, s[44:45]
	global_load_dwordx4 v[88:91], v101, s[44:45] offset:1024
	global_load_dwordx4 v[92:95], v101, s[44:45] offset:2048
	global_load_dwordx4 v[96:99], v101, s[44:45] offset:3072
	s_add_u32 s42, s42, 0x6000
	s_addc_u32 s43, s43, 0
	s_add_u32 s44, s44, 0x6000
	s_addc_u32 s45, s45, 0
	s_waitcnt vmcnt(32)
; __device__ __forceinline__ void norm_phase(const void* src_lat, int lat_f32, const float* src_ctx, int nrows, const float* gvec, const float* mods_l, int sh_off, int sc_off, bf16_t* U, const float* part, int nparts, float* ctx_out) {
;     ...
;     for (int row = gw; row < nrows; row += ngw) {
;         const int s = row < MLAT ? (row >> 13) : 4;
;         f32x4 v[4]; float ss = 0.f;
;         if (row < MLAT && !lat_f32) { const bf16_t* src = (const bf16_t*)src_lat + (size_t)row * DM + 4 * lane;
; #pragma unroll
;             for (int j = 0; j < 4; ++j) { const u32x2 w = *(const u32x2*)(src + 256 * j);
;                 v[j] = (f32x4){__uint_as_float(w.x << 16), __uint_as_float(w.x & 0xffff0000u), __uint_as_float(w.y << 16), __uint_as_float(w.y & 0xffff0000u)}; } }
;         else { const float* src = row < MLAT ? (const float*)src_lat + (size_t)row * DM : src_ctx + (size_t)(row - MLAT) * DM;
; #pragma unroll
;             for (int j = 0; j < 4; ++j) v[j] = *(const f32x4*)(src + 4 * lane + 256 * j); }
; #pragma unroll
;         for (int j = 0; j < 4; ++j) { ss += (v[j][0] * v[j][0] + v[j][1] * v[j][1]) + (v[j][2] * v[j][2] + v[j][3] * v[j][3]); }
;         if (nparts != 0 && row >= MLAT) {
;             for (int ch = 0; ch < nparts; ch += 4) {
;                 f32x4 pv[4][4];
; #pragma unroll
;                 for (int c4 = 0; c4 < 4; ++c4) { const float* pr = part + ((size_t)(ch + c4) * MCTX + (row - MLAT)) * DM + 4 * lane;
; #pragma unroll
;                     for (int j = 0; j < 4; ++j) pv[c4][j] = *(const f32x4*)(pr + 256 * j); }
; #pragma unroll
;                 for (int c4 = 0; c4 < 4; ++c4)
; #pragma unroll
;                     for (int j = 0; j < 4; ++j) v[j] = v[j] + pv[c4][j]; }
;             ss = 0.f;
; #pragma unroll
;             for (int j = 0; j < 4; ++j) { *(f32x4*)(ctx_out + (size_t)(row - MLAT) * DM + 4 * lane + 256 * j) = v[j]; ss += (v[j][0] * v[j][0] + v[j][1] * v[j][1]) + (v[j][2] * v[j][2] + v[j][3] * v[j][3]); }
;         }
;         const float rs = rsqrtf(wave_sum64(ss) * (1.0f / DM) + EPS);
;         const float* shp = mods_l + s * 6144 + sh_off + 4 * lane; const float* scp = mods_l + s * 6144 + sc_off + 4 * lane;
;         bf16_t* up = U + (size_t)row * DM + 4 * lane;
; #pragma unroll
;         for (int j = 0; j < 4; ++j) { const f32x4 sh = *(const f32x4*)(shp + 256 * j), sc = *(const f32x4*)(scp + 256 * j);
	v_lshlrev_b32_e32 v40, 16, v112
	v_and_b32_e32 v41, 0xffff0000, v112
	v_lshlrev_b32_e32 v42, 16, v113
	v_and_b32_e32 v43, 0xffff0000, v113
	v_lshlrev_b32_e32 v44, 16, v114
	v_and_b32_e32 v45, 0xffff0000, v114
	v_lshlrev_b32_e32 v46, 16, v115
	v_and_b32_e32 v47, 0xffff0000, v115
	v_lshlrev_b32_e32 v48, 16, v116
	v_and_b32_e32 v49, 0xffff0000, v116
	v_lshlrev_b32_e32 v50, 16, v117
	v_and_b32_e32 v51, 0xffff0000, v117
	v_lshlrev_b32_e32 v52, 16, v118
	v_and_b32_e32 v53, 0xffff0000, v118
	v_lshlrev_b32_e32 v54, 16, v119
	v_and_b32_e32 v55, 0xffff0000, v119
	v_mul_f32_e32 v56, v41, v41
	v_mul_f32_e32 v57, v43, v43
	v_fmac_f32_e32 v56, v40, v40
	v_fmac_f32_e32 v57, v42, v42
	v_add_f32_e32 v58, v56, v57
	v_mul_f32_e32 v56, v45, v45
	v_mul_f32_e32 v57, v47, v47
	v_fmac_f32_e32 v56, v44, v44
	v_fmac_f32_e32 v57, v46, v46
	v_add_f32_e32 v56, v56, v57
	v_add_f32_e32 v58, v58, v56
	v_mul_f32_e32 v56, v49, v49
	v_mul_f32_e32 v57, v51, v51
	v_fmac_f32_e32 v56, v48, v48
	v_fmac_f32_e32 v57, v50, v50
	v_add_f32_e32 v56, v56, v57
	v_add_f32_e32 v58, v58, v56
	v_mul_f32_e32 v56, v53, v53
	v_mul_f32_e32 v57, v55, v55
	v_fmac_f32_e32 v56, v52, v52
	v_fmac_f32_e32 v57, v54, v54
	v_add_f32_e32 v56, v56, v57
	v_add_f32_e32 v58, v58, v56
	s_nop 1
	v_add_f32_dpp v58, v58, v58 quad_perm:[1,0,3,2] row_mask:0xf bank_mask:0xf bound_ctrl:1
	s_nop 1
	v_add_f32_dpp v58, v58, v58 quad_perm:[2,3,0,1] row_mask:0xf bank_mask:0xf bound_ctrl:1
	s_nop 1
	v_add_f32_dpp v58, v58, v58 row_half_mirror row_mask:0xf bank_mask:0xf bound_ctrl:1
	s_nop 1
	v_add_f32_dpp v58, v58, v58 row_mirror row_mask:0xf bank_mask:0xf bound_ctrl:1
	v_mov_b32_e32 v56, v58
	s_nop 1
	v_permlane16_swap_b32_e32 v58, v56
	v_add_f32_e32 v58, v58, v56
	v_mov_b32_e32 v56, v58
	s_nop 1
	v_permlane32_swap_b32_e32 v58, v56
	v_add_f32_e32 v58, v58, v56
	v_fmamk_f32 v60, v58, 0x3a800000, v153
	v_rsq_f32_e32 v60, v60
	s_nop 0
	v_pk_mul_f32 v[40:41], v[40:41], v[60:61] op_sel_hi:[1,0]
	v_pk_mul_f32 v[42:43], v[42:43], v[60:61] op_sel_hi:[1,0]
	v_pk_mul_f32 v[44:45], v[44:45], v[60:61] op_sel_hi:[1,0]
	v_pk_mul_f32 v[46:47], v[46:47], v[60:61] op_sel_hi:[1,0]
	v_pk_mul_f32 v[48:49], v[48:49], v[60:61] op_sel_hi:[1,0]
	v_pk_mul_f32 v[50:51], v[50:51], v[60:61] op_sel_hi:[1,0]
	v_pk_mul_f32 v[52:53], v[52:53], v[60:61] op_sel_hi:[1,0]
	v_pk_mul_f32 v[54:55], v[54:55], v[60:61] op_sel_hi:[1,0]
	v_pk_mul_f32 v[40:41], v[0:1], v[40:41]
	v_pk_mul_f32 v[42:43], v[2:3], v[42:43]
	v_pk_mul_f32 v[44:45], v[4:5], v[44:45]
	v_pk_mul_f32 v[46:47], v[6:7], v[46:47]
	v_pk_mul_f32 v[48:49], v[8:9], v[48:49]
	v_pk_mul_f32 v[50:51], v[10:11], v[50:51]
	v_pk_mul_f32 v[52:53], v[12:13], v[52:53]
	v_pk_mul_f32 v[54:55], v[14:15], v[54:55]
	v_pk_fma_f32 v[40:41], v[214:215], v[40:41], v[198:199]
	v_pk_fma_f32 v[42:43], v[216:217], v[42:43], v[200:201]
	v_pk_fma_f32 v[44:45], v[218:219], v[44:45], v[202:203]
	v_pk_fma_f32 v[46:47], v[220:221], v[46:47], v[204:205]
	v_pk_fma_f32 v[48:49], v[222:223], v[48:49], v[206:207]
	v_pk_fma_f32 v[50:51], v[224:225], v[50:51], v[208:209]
	v_pk_fma_f32 v[52:53], v[226:227], v[52:53], v[210:211]
	v_pk_fma_f32 v[54:55], v[228:229], v[54:55], v[212:213]
	v_cvt_pk_bf16_f32 v40, v40, v41
	v_cvt_pk_bf16_f32 v41, v42, v43
	v_cvt_pk_bf16_f32 v44, v44, v45
	v_cvt_pk_bf16_f32 v45, v46, v47
	v_cvt_pk_bf16_f32 v48, v48, v49
	v_cvt_pk_bf16_f32 v49, v50, v51
	v_cvt_pk_bf16_f32 v52, v52, v53
	v_cvt_pk_bf16_f32 v53, v54, v55
	global_store_dwordx2 v100, v[40:41], s[40:41]
	global_store_dwordx2 v100, v[44:45], s[40:41] offset:512
	global_store_dwordx2 v100, v[48:49], s[40:41] offset:1024
	global_store_dwordx2 v100, v[52:53], s[40:41] offset:1536
	s_add_u32 s40, s40, 0x400000
	s_addc_u32 s41, s41, 0
	global_load_dwordx2 v[112:113], v100, s[38:39]
	global_load_dwordx2 v[114:115], v100, s[38:39] offset:512
	global_load_dwordx2 v[116:117], v100, s[38:39] offset:1024
	global_load_dwordx2 v[118:119], v100, s[38:39] offset:1536
	s_add_u32 s38, s38, 0x400000
	s_addc_u32 s39, s39, 0
	s_waitcnt vmcnt(32)
	v_lshlrev_b32_e32 v40, 16, v120
	v_and_b32_e32 v41, 0xffff0000, v120
	v_lshlrev_b32_e32 v42, 16, v121
	v_and_b32_e32 v43, 0xffff0000, v121
	v_lshlrev_b32_e32 v44, 16, v122
	v_and_b32_e32 v45, 0xffff0000, v122
	v_lshlrev_b32_e32 v46, 16, v123
	v_and_b32_e32 v47, 0xffff0000, v123
	v_lshlrev_b32_e32 v48, 16, v124
	v_and_b32_e32 v49, 0xffff0000, v124
	v_lshlrev_b32_e32 v50, 16, v125
	v_and_b32_e32 v51, 0xffff0000, v125
	v_lshlrev_b32_e32 v52, 16, v126
	v_and_b32_e32 v53, 0xffff0000, v126
	v_lshlrev_b32_e32 v54, 16, v127
	v_and_b32_e32 v55, 0xffff0000, v127
	v_mul_f32_e32 v56, v41, v41
	v_mul_f32_e32 v57, v43, v43
	v_fmac_f32_e32 v56, v40, v40
	v_fmac_f32_e32 v57, v42, v42
	v_add_f32_e32 v58, v56, v57
	v_mul_f32_e32 v56, v45, v45
	v_mul_f32_e32 v57, v47, v47
	v_fmac_f32_e32 v56, v44, v44
	v_fmac_f32_e32 v57, v46, v46
	v_add_f32_e32 v56, v56, v57
	v_add_f32_e32 v58, v58, v56
	v_mul_f32_e32 v56, v49, v49
	v_mul_f32_e32 v57, v51, v51
	v_fmac_f32_e32 v56, v48, v48
	v_fmac_f32_e32 v57, v50, v50
	v_add_f32_e32 v56, v56, v57
	v_add_f32_e32 v58, v58, v56
	v_mul_f32_e32 v56, v53, v53
	v_mul_f32_e32 v57, v55, v55
	v_fmac_f32_e32 v56, v52, v52
	v_fmac_f32_e32 v57, v54, v54
	v_add_f32_e32 v56, v56, v57
	v_add_f32_e32 v58, v58, v56
	s_nop 1
	v_add_f32_dpp v58, v58, v58 quad_perm:[1,0,3,2] row_mask:0xf bank_mask:0xf bound_ctrl:1
	s_nop 1
	v_add_f32_dpp v58, v58, v58 quad_perm:[2,3,0,1] row_mask:0xf bank_mask:0xf bound_ctrl:1
	s_nop 1
	v_add_f32_dpp v58, v58, v58 row_half_mirror row_mask:0xf bank_mask:0xf bound_ctrl:1
	s_nop 1
	v_add_f32_dpp v58, v58, v58 row_mirror row_mask:0xf bank_mask:0xf bound_ctrl:1
	v_mov_b32_e32 v56, v58
	s_nop 1
; __device__ __forceinline__ void norm_phase(const void* src_lat, int lat_f32, const float* src_ctx, int nrows, const float* gvec, const float* mods_l, int sh_off, int sc_off, bf16_t* U, const float* part, int nparts, float* ctx_out) {
;     ...
;         if (row < MLAT && !lat_f32) { const bf16_t* src = (const bf16_t*)src_lat + (size_t)row * DM + 4 * lane;
; #pragma unroll
;             for (int j = 0; j < 4; ++j) { const u32x2 w = *(const u32x2*)(src + 256 * j);
;                 v[j] = (f32x4){__uint_as_float(w.x << 16), __uint_as_float(w.x & 0xffff0000u), __uint_as_float(w.y << 16), __uint_as_float(w.y & 0xffff0000u)}; } }
;         else { const float* src = row < MLAT ? (const float*)src_lat + (size_t)row * DM : src_ctx + (size_t)(row - MLAT) * DM;
; #pragma unroll
;             for (int j = 0; j < 4; ++j) v[j] = *(const f32x4*)(src + 4 * lane + 256 * j); }
; #pragma unroll
;         for (int j = 0; j < 4; ++j) { ss += (v[j][0] * v[j][0] + v[j][1] * v[j][1]) + (v[j][2] * v[j][2] + v[j][3] * v[j][3]); }
;         if (nparts != 0 && row >= MLAT) {
;             for (int ch = 0; ch < nparts; ch += 4) {
;                 f32x4 pv[4][4];
; #pragma unroll
;                 for (int c4 = 0; c4 < 4; ++c4) { const float* pr = part + ((size_t)(ch + c4) * MCTX + (row - MLAT)) * DM + 4 * lane;
; #pragma unroll
;                     for (int j = 0; j < 4; ++j) pv[c4][j] = *(const f32x4*)(pr + 256 * j); }
; #pragma unroll
;                 for (int c4 = 0; c4 < 4; ++c4)
; #pragma unroll
;                     for (int j = 0; j < 4; ++j) v[j] = v[j] + pv[c4][j]; }
;             ss = 0.f;
; #pragma unroll
;             for (int j = 0; j < 4; ++j) { *(f32x4*)(ctx_out + (size_t)(row - MLAT) * DM + 4 * lane + 256 * j) = v[j]; ss += (v[j][0] * v[j][0] + v[j][1] * v[j][1]) + (v[j][2] * v[j][2] + v[j][3] * v[j][3]); }
;         }
;         const float rs = rsqrtf(wave_sum64(ss) * (1.0f / DM) + EPS);
;         const float* shp = mods_l + s * 6144 + sh_off + 4 * lane; const float* scp = mods_l + s * 6144 + sc_off + 4 * lane;
;         bf16_t* up = U + (size_t)row * DM + 4 * lane;
; #pragma unroll
;         for (int j = 0; j < 4; ++j) { const f32x4 sh = *(const f32x4*)(shp + 256 * j), sc = *(const f32x4*)(scp + 256 * j);
;             const f32x4 y = v[j] * rs * gv[j] * (sc + 1.0f) + sh;
;             u32x2 o; o.x = pkbf(y[0], y[1]); o.y = pkbf(y[2], y[3]); *(u32x2*)(up + 256 * j) = o; }
	v_permlane16_swap_b32_e32 v58, v56
	v_add_f32_e32 v58, v58, v56
	v_mov_b32_e32 v56, v58
	s_nop 1
	v_permlane32_swap_b32_e32 v58, v56
	v_add_f32_e32 v58, v58, v56
	v_fmamk_f32 v60, v58, 0x3a800000, v153
	v_rsq_f32_e32 v60, v60
	s_nop 0
	v_pk_mul_f32 v[40:41], v[40:41], v[60:61] op_sel_hi:[1,0]
	v_pk_mul_f32 v[42:43], v[42:43], v[60:61] op_sel_hi:[1,0]
	v_pk_mul_f32 v[44:45], v[44:45], v[60:61] op_sel_hi:[1,0]
	v_pk_mul_f32 v[46:47], v[46:47], v[60:61] op_sel_hi:[1,0]
	v_pk_mul_f32 v[48:49], v[48:49], v[60:61] op_sel_hi:[1,0]
	v_pk_mul_f32 v[50:51], v[50:51], v[60:61] op_sel_hi:[1,0]
	v_pk_mul_f32 v[52:53], v[52:53], v[60:61] op_sel_hi:[1,0]
	v_pk_mul_f32 v[54:55], v[54:55], v[60:61] op_sel_hi:[1,0]
	v_pk_mul_f32 v[40:41], v[0:1], v[40:41]
	v_pk_mul_f32 v[42:43], v[2:3], v[42:43]
	v_pk_mul_f32 v[44:45], v[4:5], v[44:45]
	v_pk_mul_f32 v[46:47], v[6:7], v[46:47]
	v_pk_mul_f32 v[48:49], v[8:9], v[48:49]
	v_pk_mul_f32 v[50:51], v[10:11], v[50:51]
	v_pk_mul_f32 v[52:53], v[12:13], v[52:53]
	v_pk_mul_f32 v[54:55], v[14:15], v[54:55]
	v_pk_fma_f32 v[40:41], v[214:215], v[40:41], v[198:199]
	v_pk_fma_f32 v[42:43], v[216:217], v[42:43], v[200:201]
	v_pk_fma_f32 v[44:45], v[218:219], v[44:45], v[202:203]
	v_pk_fma_f32 v[46:47], v[220:221], v[46:47], v[204:205]
	v_pk_fma_f32 v[48:49], v[222:223], v[48:49], v[206:207]
	v_pk_fma_f32 v[50:51], v[224:225], v[50:51], v[208:209]
	v_pk_fma_f32 v[52:53], v[226:227], v[52:53], v[210:211]
	v_pk_fma_f32 v[54:55], v[228:229], v[54:55], v[212:213]
	v_cvt_pk_bf16_f32 v40, v40, v41
	v_cvt_pk_bf16_f32 v41, v42, v43
	v_cvt_pk_bf16_f32 v44, v44, v45
	v_cvt_pk_bf16_f32 v45, v46, v47
	v_cvt_pk_bf16_f32 v48, v48, v49
	v_cvt_pk_bf16_f32 v49, v50, v51
	v_cvt_pk_bf16_f32 v52, v52, v53
	v_cvt_pk_bf16_f32 v53, v54, v55
	global_store_dwordx2 v100, v[40:41], s[40:41]
	global_store_dwordx2 v100, v[44:45], s[40:41] offset:512
	global_store_dwordx2 v100, v[48:49], s[40:41] offset:1024
	global_store_dwordx2 v100, v[52:53], s[40:41] offset:1536
	s_add_u32 s40, s40, 0x400000
	s_addc_u32 s41, s41, 0
	global_load_dwordx2 v[120:121], v100, s[38:39]
	global_load_dwordx2 v[122:123], v100, s[38:39] offset:512
	global_load_dwordx2 v[124:125], v100, s[38:39] offset:1024
	global_load_dwordx2 v[126:127], v100, s[38:39] offset:1536
	s_add_u32 s38, s38, 0x400000
	s_addc_u32 s39, s39, 0
	s_waitcnt vmcnt(32)
	v_lshlrev_b32_e32 v40, 16, v128
	v_and_b32_e32 v41, 0xffff0000, v128
	v_lshlrev_b32_e32 v42, 16, v129
	v_and_b32_e32 v43, 0xffff0000, v129
	v_lshlrev_b32_e32 v44, 16, v130
	v_and_b32_e32 v45, 0xffff0000, v130
	v_lshlrev_b32_e32 v46, 16, v131
	v_and_b32_e32 v47, 0xffff0000, v131
	v_lshlrev_b32_e32 v48, 16, v132
	v_and_b32_e32 v49, 0xffff0000, v132
	v_lshlrev_b32_e32 v50, 16, v133
	v_and_b32_e32 v51, 0xffff0000, v133
	v_lshlrev_b32_e32 v52, 16, v134
	v_and_b32_e32 v53, 0xffff0000, v134
	v_lshlrev_b32_e32 v54, 16, v135
	v_and_b32_e32 v55, 0xffff0000, v135
	v_mul_f32_e32 v56, v41, v41
	v_mul_f32_e32 v57, v43, v43
	v_fmac_f32_e32 v56, v40, v40
	v_fmac_f32_e32 v57, v42, v42
	v_add_f32_e32 v58, v56, v57
	v_mul_f32_e32 v56, v45, v45
	v_mul_f32_e32 v57, v47, v47
	v_fmac_f32_e32 v56, v44, v44
	v_fmac_f32_e32 v57, v46, v46
	v_add_f32_e32 v56, v56, v57
	v_add_f32_e32 v58, v58, v56
	v_mul_f32_e32 v56, v49, v49
	v_mul_f32_e32 v57, v51, v51
	v_fmac_f32_e32 v56, v48, v48
	v_fmac_f32_e32 v57, v50, v50
	v_add_f32_e32 v56, v56, v57
	v_add_f32_e32 v58, v58, v56
	v_mul_f32_e32 v56, v53, v53
	v_mul_f32_e32 v57, v55, v55
	v_fmac_f32_e32 v56, v52, v52
	v_fmac_f32_e32 v57, v54, v54
	v_add_f32_e32 v56, v56, v57
	v_add_f32_e32 v58, v58, v56
	s_nop 1
	v_add_f32_dpp v58, v58, v58 quad_perm:[1,0,3,2] row_mask:0xf bank_mask:0xf bound_ctrl:1
	s_nop 1
	v_add_f32_dpp v58, v58, v58 quad_perm:[2,3,0,1] row_mask:0xf bank_mask:0xf bound_ctrl:1
	s_nop 1
	v_add_f32_dpp v58, v58, v58 row_half_mirror row_mask:0xf bank_mask:0xf bound_ctrl:1
	s_nop 1
	v_add_f32_dpp v58, v58, v58 row_mirror row_mask:0xf bank_mask:0xf bound_ctrl:1
	v_mov_b32_e32 v56, v58
	s_nop 1
	v_permlane16_swap_b32_e32 v58, v56
	v_add_f32_e32 v58, v58, v56
	v_mov_b32_e32 v56, v58
	s_nop 1
	v_permlane32_swap_b32_e32 v58, v56
	v_add_f32_e32 v58, v58, v56
	v_fmamk_f32 v60, v58, 0x3a800000, v153
	v_rsq_f32_e32 v60, v60
	s_nop 0
	v_pk_mul_f32 v[40:41], v[40:41], v[60:61] op_sel_hi:[1,0]
	v_pk_mul_f32 v[42:43], v[42:43], v[60:61] op_sel_hi:[1,0]
	v_pk_mul_f32 v[44:45], v[44:45], v[60:61] op_sel_hi:[1,0]
	v_pk_mul_f32 v[46:47], v[46:47], v[60:61] op_sel_hi:[1,0]
	v_pk_mul_f32 v[48:49], v[48:49], v[60:61] op_sel_hi:[1,0]
	v_pk_mul_f32 v[50:51], v[50:51], v[60:61] op_sel_hi:[1,0]
	v_pk_mul_f32 v[52:53], v[52:53], v[60:61] op_sel_hi:[1,0]
	v_pk_mul_f32 v[54:55], v[54:55], v[60:61] op_sel_hi:[1,0]
	v_pk_mul_f32 v[40:41], v[0:1], v[40:41]
	v_pk_mul_f32 v[42:43], v[2:3], v[42:43]
	v_pk_mul_f32 v[44:45], v[4:5], v[44:45]
	v_pk_mul_f32 v[46:47], v[6:7], v[46:47]
	v_pk_mul_f32 v[48:49], v[8:9], v[48:49]
	v_pk_mul_f32 v[50:51], v[10:11], v[50:51]
	v_pk_mul_f32 v[52:53], v[12:13], v[52:53]
	v_pk_mul_f32 v[54:55], v[14:15], v[54:55]
	v_pk_fma_f32 v[40:41], v[214:215], v[40:41], v[198:199]
	v_pk_fma_f32 v[42:43], v[216:217], v[42:43], v[200:201]
	v_pk_fma_f32 v[44:45], v[218:219], v[44:45], v[202:203]
	v_pk_fma_f32 v[46:47], v[220:221], v[46:47], v[204:205]
	v_pk_fma_f32 v[48:49], v[222:223], v[48:49], v[206:207]
	v_pk_fma_f32 v[50:51], v[224:225], v[50:51], v[208:209]
	v_pk_fma_f32 v[52:53], v[226:227], v[52:53], v[210:211]
	v_pk_fma_f32 v[54:55], v[228:229], v[54:55], v[212:213]
	v_cvt_pk_bf16_f32 v40, v40, v41
	v_cvt_pk_bf16_f32 v41, v42, v43
	v_cvt_pk_bf16_f32 v44, v44, v45
	v_cvt_pk_bf16_f32 v45, v46, v47
	v_cvt_pk_bf16_f32 v48, v48, v49
	v_cvt_pk_bf16_f32 v49, v50, v51
	v_cvt_pk_bf16_f32 v52, v52, v53
	v_cvt_pk_bf16_f32 v53, v54, v55
	global_store_dwordx2 v100, v[40:41], s[40:41]
	global_store_dwordx2 v100, v[44:45], s[40:41] offset:512
	global_store_dwordx2 v100, v[48:49], s[40:41] offset:1024
	global_store_dwordx2 v100, v[52:53], s[40:41] offset:1536
	s_add_u32 s40, s40, 0x400000
	s_addc_u32 s41, s41, 0
	global_load_dwordx2 v[128:129], v100, s[38:39]
	global_load_dwordx2 v[130:131], v100, s[38:39] offset:512
	global_load_dwordx2 v[132:133], v100, s[38:39] offset:1024
	global_load_dwordx2 v[134:135], v100, s[38:39] offset:1536
	s_add_u32 s38, s38, 0x400000
	s_addc_u32 s39, s39, 0
	s_waitcnt vmcnt(24)
; __device__ __forceinline__ void norm_phase(const void* src_lat, int lat_f32, const float* src_ctx, int nrows, const float* gvec, const float* mods_l, int sh_off, int sc_off, bf16_t* U, const float* part, int nparts, float* ctx_out) {
;     ...
;         if (row < MLAT && !lat_f32) { const bf16_t* src = (const bf16_t*)src_lat + (size_t)row * DM + 4 * lane;
; #pragma unroll
;             for (int j = 0; j < 4; ++j) { const u32x2 w = *(const u32x2*)(src + 256 * j);
;                 v[j] = (f32x4){__uint_as_float(w.x << 16), __uint_as_float(w.x & 0xffff0000u), __uint_as_float(w.y << 16), __uint_as_float(w.y & 0xffff0000u)}; } }
;         else { const float* src = row < MLAT ? (const float*)src_lat + (size_t)row * DM : src_ctx + (size_t)(row - MLAT) * DM;
; #pragma unroll
;             for (int j = 0; j < 4; ++j) v[j] = *(const f32x4*)(src + 4 * lane + 256 * j); }
; #pragma unroll
;         for (int j = 0; j < 4; ++j) { ss += (v[j][0] * v[j][0] + v[j][1] * v[j][1]) + (v[j][2] * v[j][2] + v[j][3] * v[j][3]); }
;         if (nparts != 0 && row >= MLAT) {
;             for (int ch = 0; ch < nparts; ch += 4) {
;                 f32x4 pv[4][4];
; #pragma unroll
;                 for (int c4 = 0; c4 < 4; ++c4) { const float* pr = part + ((size_t)(ch + c4) * MCTX + (row - MLAT)) * DM + 4 * lane;
; #pragma unroll
;                     for (int j = 0; j < 4; ++j) pv[c4][j] = *(const f32x4*)(pr + 256 * j); }
; #pragma unroll
;                 for (int c4 = 0; c4 < 4; ++c4)
; #pragma unroll
;                     for (int j = 0; j < 4; ++j) v[j] = v[j] + pv[c4][j]; }
;             ss = 0.f;
; #pragma unroll
;             for (int j = 0; j < 4; ++j) { *(f32x4*)(ctx_out + (size_t)(row - MLAT) * DM + 4 * lane + 256 * j) = v[j]; ss += (v[j][0] * v[j][0] + v[j][1] * v[j][1]) + (v[j][2] * v[j][2] + v[j][3] * v[j][3]); }
;         }
;         const float rs = rsqrtf(wave_sum64(ss) * (1.0f / DM) + EPS);
;         const float* shp = mods_l + s * 6144 + sh_off + 4 * lane; const float* scp = mods_l + s * 6144 + sc_off + 4 * lane;
;         bf16_t* up = U + (size_t)row * DM + 4 * lane;
; #pragma unroll
;         for (int j = 0; j < 4; ++j) { const f32x4 sh = *(const f32x4*)(shp + 256 * j), sc = *(const f32x4*)(scp + 256 * j);
;             const f32x4 y = v[j] * rs * gv[j] * (sc + 1.0f) + sh;
;             u32x2 o; o.x = pkbf(y[0], y[1]); o.y = pkbf(y[2], y[3]); *(u32x2*)(up + 256 * j) = o; }
	v_pk_add_f32 v[84:85], v[84:85], 1.0 op_sel_hi:[1,0]
	v_pk_add_f32 v[86:87], v[86:87], 1.0 op_sel_hi:[1,0]
	v_pk_add_f32 v[88:89], v[88:89], 1.0 op_sel_hi:[1,0]
	v_pk_add_f32 v[90:91], v[90:91], 1.0 op_sel_hi:[1,0]
	v_pk_add_f32 v[92:93], v[92:93], 1.0 op_sel_hi:[1,0]
	v_pk_add_f32 v[94:95], v[94:95], 1.0 op_sel_hi:[1,0]
	v_pk_add_f32 v[96:97], v[96:97], 1.0 op_sel_hi:[1,0]
	v_pk_add_f32 v[98:99], v[98:99], 1.0 op_sel_hi:[1,0]
	v_lshlrev_b32_e32 v40, 16, v104
	v_and_b32_e32 v41, 0xffff0000, v104
	v_lshlrev_b32_e32 v42, 16, v105
	v_and_b32_e32 v43, 0xffff0000, v105
	v_lshlrev_b32_e32 v44, 16, v106
	v_and_b32_e32 v45, 0xffff0000, v106
	v_lshlrev_b32_e32 v46, 16, v107
	v_and_b32_e32 v47, 0xffff0000, v107
	v_lshlrev_b32_e32 v48, 16, v108
	v_and_b32_e32 v49, 0xffff0000, v108
	v_lshlrev_b32_e32 v50, 16, v109
	v_and_b32_e32 v51, 0xffff0000, v109
	v_lshlrev_b32_e32 v52, 16, v110
	v_and_b32_e32 v53, 0xffff0000, v110
	v_lshlrev_b32_e32 v54, 16, v111
	v_and_b32_e32 v55, 0xffff0000, v111
	v_mul_f32_e32 v56, v41, v41
	v_mul_f32_e32 v57, v43, v43
	v_fmac_f32_e32 v56, v40, v40
	v_fmac_f32_e32 v57, v42, v42
	v_add_f32_e32 v58, v56, v57
	v_mul_f32_e32 v56, v45, v45
	v_mul_f32_e32 v57, v47, v47
	v_fmac_f32_e32 v56, v44, v44
	v_fmac_f32_e32 v57, v46, v46
	v_add_f32_e32 v56, v56, v57
	v_add_f32_e32 v58, v58, v56
	v_mul_f32_e32 v56, v49, v49
	v_mul_f32_e32 v57, v51, v51
	v_fmac_f32_e32 v56, v48, v48
	v_fmac_f32_e32 v57, v50, v50
	v_add_f32_e32 v56, v56, v57
	v_add_f32_e32 v58, v58, v56
	v_mul_f32_e32 v56, v53, v53
	v_mul_f32_e32 v57, v55, v55
	v_fmac_f32_e32 v56, v52, v52
	v_fmac_f32_e32 v57, v54, v54
	v_add_f32_e32 v56, v56, v57
	v_add_f32_e32 v58, v58, v56
	s_nop 1
	v_add_f32_dpp v58, v58, v58 quad_perm:[1,0,3,2] row_mask:0xf bank_mask:0xf bound_ctrl:1
	s_nop 1
	v_add_f32_dpp v58, v58, v58 quad_perm:[2,3,0,1] row_mask:0xf bank_mask:0xf bound_ctrl:1
	s_nop 1
	v_add_f32_dpp v58, v58, v58 row_half_mirror row_mask:0xf bank_mask:0xf bound_ctrl:1
	s_nop 1
	v_add_f32_dpp v58, v58, v58 row_mirror row_mask:0xf bank_mask:0xf bound_ctrl:1
	v_mov_b32_e32 v56, v58
	s_nop 1
	v_permlane16_swap_b32_e32 v58, v56
	v_add_f32_e32 v58, v58, v56
	v_mov_b32_e32 v56, v58
	s_nop 1
	v_permlane32_swap_b32_e32 v58, v56
	v_add_f32_e32 v58, v58, v56
	v_fmamk_f32 v60, v58, 0x3a800000, v153
	v_rsq_f32_e32 v60, v60
	s_nop 0
	v_pk_mul_f32 v[40:41], v[40:41], v[60:61] op_sel_hi:[1,0]
	v_pk_mul_f32 v[42:43], v[42:43], v[60:61] op_sel_hi:[1,0]
	v_pk_mul_f32 v[44:45], v[44:45], v[60:61] op_sel_hi:[1,0]
	v_pk_mul_f32 v[46:47], v[46:47], v[60:61] op_sel_hi:[1,0]
	v_pk_mul_f32 v[48:49], v[48:49], v[60:61] op_sel_hi:[1,0]
	v_pk_mul_f32 v[50:51], v[50:51], v[60:61] op_sel_hi:[1,0]
	v_pk_mul_f32 v[52:53], v[52:53], v[60:61] op_sel_hi:[1,0]
	v_pk_mul_f32 v[54:55], v[54:55], v[60:61] op_sel_hi:[1,0]
	v_pk_mul_f32 v[40:41], v[0:1], v[40:41]
	v_pk_mul_f32 v[42:43], v[2:3], v[42:43]
	v_pk_mul_f32 v[44:45], v[4:5], v[44:45]
	v_pk_mul_f32 v[46:47], v[6:7], v[46:47]
	v_pk_mul_f32 v[48:49], v[8:9], v[48:49]
	v_pk_mul_f32 v[50:51], v[10:11], v[50:51]
	v_pk_mul_f32 v[52:53], v[12:13], v[52:53]
	v_pk_mul_f32 v[54:55], v[14:15], v[54:55]
	v_pk_fma_f32 v[40:41], v[84:85], v[40:41], v[68:69]
	v_pk_fma_f32 v[42:43], v[86:87], v[42:43], v[70:71]
	v_pk_fma_f32 v[44:45], v[88:89], v[44:45], v[72:73]
	v_pk_fma_f32 v[46:47], v[90:91], v[46:47], v[74:75]
	v_pk_fma_f32 v[48:49], v[92:93], v[48:49], v[76:77]
	v_pk_fma_f32 v[50:51], v[94:95], v[50:51], v[78:79]
	v_pk_fma_f32 v[52:53], v[96:97], v[52:53], v[80:81]
	v_pk_fma_f32 v[54:55], v[98:99], v[54:55], v[82:83]
	v_cvt_pk_bf16_f32 v40, v40, v41
	v_cvt_pk_bf16_f32 v41, v42, v43
	v_cvt_pk_bf16_f32 v44, v44, v45
	v_cvt_pk_bf16_f32 v45, v46, v47
	v_cvt_pk_bf16_f32 v48, v48, v49
	v_cvt_pk_bf16_f32 v49, v50, v51
	v_cvt_pk_bf16_f32 v52, v52, v53
	v_cvt_pk_bf16_f32 v53, v54, v55
	global_store_dwordx2 v100, v[40:41], s[40:41]
	global_store_dwordx2 v100, v[44:45], s[40:41] offset:512
	global_store_dwordx2 v100, v[48:49], s[40:41] offset:1024
	global_store_dwordx2 v100, v[52:53], s[40:41] offset:1536
	s_add_u32 s40, s40, 0x400000
	s_addc_u32 s41, s41, 0
	s_waitcnt vmcnt(20)
	v_lshlrev_b32_e32 v40, 16, v112
	v_and_b32_e32 v41, 0xffff0000, v112
	v_lshlrev_b32_e32 v42, 16, v113
	v_and_b32_e32 v43, 0xffff0000, v113
	v_lshlrev_b32_e32 v44, 16, v114
	v_and_b32_e32 v45, 0xffff0000, v114
	v_lshlrev_b32_e32 v46, 16, v115
	v_and_b32_e32 v47, 0xffff0000, v115
	v_lshlrev_b32_e32 v48, 16, v116
	v_and_b32_e32 v49, 0xffff0000, v116
	v_lshlrev_b32_e32 v50, 16, v117
	v_and_b32_e32 v51, 0xffff0000, v117
	v_lshlrev_b32_e32 v52, 16, v118
	v_and_b32_e32 v53, 0xffff0000, v118
	v_lshlrev_b32_e32 v54, 16, v119
	v_and_b32_e32 v55, 0xffff0000, v119
	v_mul_f32_e32 v56, v41, v41
	v_mul_f32_e32 v57, v43, v43
	v_fmac_f32_e32 v56, v40, v40
	v_fmac_f32_e32 v57, v42, v42
	v_add_f32_e32 v58, v56, v57
	v_mul_f32_e32 v56, v45, v45
	v_mul_f32_e32 v57, v47, v47
	v_fmac_f32_e32 v56, v44, v44
	v_fmac_f32_e32 v57, v46, v46
	v_add_f32_e32 v56, v56, v57
	v_add_f32_e32 v58, v58, v56
	v_mul_f32_e32 v56, v49, v49
	v_mul_f32_e32 v57, v51, v51
	v_fmac_f32_e32 v56, v48, v48
	v_fmac_f32_e32 v57, v50, v50
	v_add_f32_e32 v56, v56, v57
	v_add_f32_e32 v58, v58, v56
	v_mul_f32_e32 v56, v53, v53
	v_mul_f32_e32 v57, v55, v55
	v_fmac_f32_e32 v56, v52, v52
	v_fmac_f32_e32 v57, v54, v54
	v_add_f32_e32 v56, v56, v57
	v_add_f32_e32 v58, v58, v56
	s_nop 1
	v_add_f32_dpp v58, v58, v58 quad_perm:[1,0,3,2] row_mask:0xf bank_mask:0xf bound_ctrl:1
	s_nop 1
	v_add_f32_dpp v58, v58, v58 quad_perm:[2,3,0,1] row_mask:0xf bank_mask:0xf bound_ctrl:1
	s_nop 1
	v_add_f32_dpp v58, v58, v58 row_half_mirror row_mask:0xf bank_mask:0xf bound_ctrl:1
	s_nop 1
; __device__ __forceinline__ void norm_phase(const void* src_lat, int lat_f32, const float* src_ctx, int nrows, const float* gvec, const float* mods_l, int sh_off, int sc_off, bf16_t* U, const float* part, int nparts, float* ctx_out) {
;     ...
;         if (row < MLAT && !lat_f32) { const bf16_t* src = (const bf16_t*)src_lat + (size_t)row * DM + 4 * lane;
; #pragma unroll
;             for (int j = 0; j < 4; ++j) { const u32x2 w = *(const u32x2*)(src + 256 * j);
;                 v[j] = (f32x4){__uint_as_float(w.x << 16), __uint_as_float(w.x & 0xffff0000u), __uint_as_float(w.y << 16), __uint_as_float(w.y & 0xffff0000u)}; } }
;         else { const float* src = row < MLAT ? (const float*)src_lat + (size_t)row * DM : src_ctx + (size_t)(row - MLAT) * DM;
; #pragma unroll
;             for (int j = 0; j < 4; ++j) v[j] = *(const f32x4*)(src + 4 * lane + 256 * j); }
; #pragma unroll
;         for (int j = 0; j < 4; ++j) { ss += (v[j][0] * v[j][0] + v[j][1] * v[j][1]) + (v[j][2] * v[j][2] + v[j][3] * v[j][3]); }
;         if (nparts != 0 && row >= MLAT) {
;             for (int ch = 0; ch < nparts; ch += 4) {
;                 f32x4 pv[4][4];
; #pragma unroll
;                 for (int c4 = 0; c4 < 4; ++c4) { const float* pr = part + ((size_t)(ch + c4) * MCTX + (row - MLAT)) * DM + 4 * lane;
; #pragma unroll
;                     for (int j = 0; j < 4; ++j) pv[c4][j] = *(const f32x4*)(pr + 256 * j); }
; #pragma unroll
;                 for (int c4 = 0; c4 < 4; ++c4)
; #pragma unroll
;                     for (int j = 0; j < 4; ++j) v[j] = v[j] + pv[c4][j]; }
;             ss = 0.f;
; #pragma unroll
;             for (int j = 0; j < 4; ++j) { *(f32x4*)(ctx_out + (size_t)(row - MLAT) * DM + 4 * lane + 256 * j) = v[j]; ss += (v[j][0] * v[j][0] + v[j][1] * v[j][1]) + (v[j][2] * v[j][2] + v[j][3] * v[j][3]); }
;         }
;         const float rs = rsqrtf(wave_sum64(ss) * (1.0f / DM) + EPS);
;         const float* shp = mods_l + s * 6144 + sh_off + 4 * lane; const float* scp = mods_l + s * 6144 + sc_off + 4 * lane;
;         bf16_t* up = U + (size_t)row * DM + 4 * lane;
; #pragma unroll
;         for (int j = 0; j < 4; ++j) { const f32x4 sh = *(const f32x4*)(shp + 256 * j), sc = *(const f32x4*)(scp + 256 * j);
;             const f32x4 y = v[j] * rs * gv[j] * (sc + 1.0f) + sh;
;             u32x2 o; o.x = pkbf(y[0], y[1]); o.y = pkbf(y[2], y[3]); *(u32x2*)(up + 256 * j) = o; }
	v_add_f32_dpp v58, v58, v58 row_mirror row_mask:0xf bank_mask:0xf bound_ctrl:1
	v_mov_b32_e32 v56, v58
	s_nop 1
	v_permlane16_swap_b32_e32 v58, v56
	v_add_f32_e32 v58, v58, v56
	v_mov_b32_e32 v56, v58
	s_nop 1
	v_permlane32_swap_b32_e32 v58, v56
	v_add_f32_e32 v58, v58, v56
	v_fmamk_f32 v60, v58, 0x3a800000, v153
	v_rsq_f32_e32 v60, v60
	s_nop 0
	v_pk_mul_f32 v[40:41], v[40:41], v[60:61] op_sel_hi:[1,0]
	v_pk_mul_f32 v[42:43], v[42:43], v[60:61] op_sel_hi:[1,0]
	v_pk_mul_f32 v[44:45], v[44:45], v[60:61] op_sel_hi:[1,0]
	v_pk_mul_f32 v[46:47], v[46:47], v[60:61] op_sel_hi:[1,0]
	v_pk_mul_f32 v[48:49], v[48:49], v[60:61] op_sel_hi:[1,0]
	v_pk_mul_f32 v[50:51], v[50:51], v[60:61] op_sel_hi:[1,0]
	v_pk_mul_f32 v[52:53], v[52:53], v[60:61] op_sel_hi:[1,0]
	v_pk_mul_f32 v[54:55], v[54:55], v[60:61] op_sel_hi:[1,0]
	v_pk_mul_f32 v[40:41], v[0:1], v[40:41]
	v_pk_mul_f32 v[42:43], v[2:3], v[42:43]
	v_pk_mul_f32 v[44:45], v[4:5], v[44:45]
	v_pk_mul_f32 v[46:47], v[6:7], v[46:47]
	v_pk_mul_f32 v[48:49], v[8:9], v[48:49]
	v_pk_mul_f32 v[50:51], v[10:11], v[50:51]
	v_pk_mul_f32 v[52:53], v[12:13], v[52:53]
	v_pk_mul_f32 v[54:55], v[14:15], v[54:55]
	v_pk_fma_f32 v[40:41], v[84:85], v[40:41], v[68:69]
	v_pk_fma_f32 v[42:43], v[86:87], v[42:43], v[70:71]
	v_pk_fma_f32 v[44:45], v[88:89], v[44:45], v[72:73]
	v_pk_fma_f32 v[46:47], v[90:91], v[46:47], v[74:75]
	v_pk_fma_f32 v[48:49], v[92:93], v[48:49], v[76:77]
	v_pk_fma_f32 v[50:51], v[94:95], v[50:51], v[78:79]
	v_pk_fma_f32 v[52:53], v[96:97], v[52:53], v[80:81]
	v_pk_fma_f32 v[54:55], v[98:99], v[54:55], v[82:83]
	v_cvt_pk_bf16_f32 v40, v40, v41
	v_cvt_pk_bf16_f32 v41, v42, v43
	v_cvt_pk_bf16_f32 v44, v44, v45
	v_cvt_pk_bf16_f32 v45, v46, v47
	v_cvt_pk_bf16_f32 v48, v48, v49
	v_cvt_pk_bf16_f32 v49, v50, v51
	v_cvt_pk_bf16_f32 v52, v52, v53
	v_cvt_pk_bf16_f32 v53, v54, v55
	global_store_dwordx2 v100, v[40:41], s[40:41]
	global_store_dwordx2 v100, v[44:45], s[40:41] offset:512
	global_store_dwordx2 v100, v[48:49], s[40:41] offset:1024
	global_store_dwordx2 v100, v[52:53], s[40:41] offset:1536
	s_add_u32 s40, s40, 0x400000
	s_addc_u32 s41, s41, 0
	s_waitcnt vmcnt(16)
	v_lshlrev_b32_e32 v40, 16, v120
	v_and_b32_e32 v41, 0xffff0000, v120
	v_lshlrev_b32_e32 v42, 16, v121
	v_and_b32_e32 v43, 0xffff0000, v121
	v_lshlrev_b32_e32 v44, 16, v122
	v_and_b32_e32 v45, 0xffff0000, v122
	v_lshlrev_b32_e32 v46, 16, v123
	v_and_b32_e32 v47, 0xffff0000, v123
	v_lshlrev_b32_e32 v48, 16, v124
	v_and_b32_e32 v49, 0xffff0000, v124
	v_lshlrev_b32_e32 v50, 16, v125
	v_and_b32_e32 v51, 0xffff0000, v125
	v_lshlrev_b32_e32 v52, 16, v126
	v_and_b32_e32 v53, 0xffff0000, v126
	v_lshlrev_b32_e32 v54, 16, v127
	v_and_b32_e32 v55, 0xffff0000, v127
	v_mul_f32_e32 v56, v41, v41
	v_mul_f32_e32 v57, v43, v43
	v_fmac_f32_e32 v56, v40, v40
	v_fmac_f32_e32 v57, v42, v42
	v_add_f32_e32 v58, v56, v57
	v_mul_f32_e32 v56, v45, v45
	v_mul_f32_e32 v57, v47, v47
	v_fmac_f32_e32 v56, v44, v44
	v_fmac_f32_e32 v57, v46, v46
	v_add_f32_e32 v56, v56, v57
	v_add_f32_e32 v58, v58, v56
	v_mul_f32_e32 v56, v49, v49
	v_mul_f32_e32 v57, v51, v51
	v_fmac_f32_e32 v56, v48, v48
	v_fmac_f32_e32 v57, v50, v50
	v_add_f32_e32 v56, v56, v57
	v_add_f32_e32 v58, v58, v56
	v_mul_f32_e32 v56, v53, v53
	v_mul_f32_e32 v57, v55, v55
	v_fmac_f32_e32 v56, v52, v52
	v_fmac_f32_e32 v57, v54, v54
	v_add_f32_e32 v56, v56, v57
	v_add_f32_e32 v58, v58, v56
	s_nop 1
	v_add_f32_dpp v58, v58, v58 quad_perm:[1,0,3,2] row_mask:0xf bank_mask:0xf bound_ctrl:1
	s_nop 1
	v_add_f32_dpp v58, v58, v58 quad_perm:[2,3,0,1] row_mask:0xf bank_mask:0xf bound_ctrl:1
	s_nop 1
	v_add_f32_dpp v58, v58, v58 row_half_mirror row_mask:0xf bank_mask:0xf bound_ctrl:1
	s_nop 1
	v_add_f32_dpp v58, v58, v58 row_mirror row_mask:0xf bank_mask:0xf bound_ctrl:1
	v_mov_b32_e32 v56, v58
	s_nop 1
	v_permlane16_swap_b32_e32 v58, v56
	v_add_f32_e32 v58, v58, v56
	v_mov_b32_e32 v56, v58
	s_nop 1
	v_permlane32_swap_b32_e32 v58, v56
	v_add_f32_e32 v58, v58, v56
	v_fmamk_f32 v60, v58, 0x3a800000, v153
	v_rsq_f32_e32 v60, v60
	s_nop 0
	v_pk_mul_f32 v[40:41], v[40:41], v[60:61] op_sel_hi:[1,0]
	v_pk_mul_f32 v[42:43], v[42:43], v[60:61] op_sel_hi:[1,0]
	v_pk_mul_f32 v[44:45], v[44:45], v[60:61] op_sel_hi:[1,0]
	v_pk_mul_f32 v[46:47], v[46:47], v[60:61] op_sel_hi:[1,0]
	v_pk_mul_f32 v[48:49], v[48:49], v[60:61] op_sel_hi:[1,0]
	v_pk_mul_f32 v[50:51], v[50:51], v[60:61] op_sel_hi:[1,0]
	v_pk_mul_f32 v[52:53], v[52:53], v[60:61] op_sel_hi:[1,0]
	v_pk_mul_f32 v[54:55], v[54:55], v[60:61] op_sel_hi:[1,0]
	v_pk_mul_f32 v[40:41], v[0:1], v[40:41]
	v_pk_mul_f32 v[42:43], v[2:3], v[42:43]
	v_pk_mul_f32 v[44:45], v[4:5], v[44:45]
	v_pk_mul_f32 v[46:47], v[6:7], v[46:47]
	v_pk_mul_f32 v[48:49], v[8:9], v[48:49]
	v_pk_mul_f32 v[50:51], v[10:11], v[50:51]
	v_pk_mul_f32 v[52:53], v[12:13], v[52:53]
	v_pk_mul_f32 v[54:55], v[14:15], v[54:55]
	v_pk_fma_f32 v[40:41], v[84:85], v[40:41], v[68:69]
	v_pk_fma_f32 v[42:43], v[86:87], v[42:43], v[70:71]
	v_pk_fma_f32 v[44:45], v[88:89], v[44:45], v[72:73]
	v_pk_fma_f32 v[46:47], v[90:91], v[46:47], v[74:75]
	v_pk_fma_f32 v[48:49], v[92:93], v[48:49], v[76:77]
	v_pk_fma_f32 v[50:51], v[94:95], v[50:51], v[78:79]
	v_pk_fma_f32 v[52:53], v[96:97], v[52:53], v[80:81]
	v_pk_fma_f32 v[54:55], v[98:99], v[54:55], v[82:83]
	v_cvt_pk_bf16_f32 v40, v40, v41
	v_cvt_pk_bf16_f32 v41, v42, v43
	v_cvt_pk_bf16_f32 v44, v44, v45
	v_cvt_pk_bf16_f32 v45, v46, v47
	v_cvt_pk_bf16_f32 v48, v48, v49
	v_cvt_pk_bf16_f32 v49, v50, v51
	v_cvt_pk_bf16_f32 v52, v52, v53
	v_cvt_pk_bf16_f32 v53, v54, v55
	global_store_dwordx2 v100, v[40:41], s[40:41]
	global_store_dwordx2 v100, v[44:45], s[40:41] offset:512
	global_store_dwordx2 v100, v[48:49], s[40:41] offset:1024
	global_store_dwordx2 v100, v[52:53], s[40:41] offset:1536
	s_add_u32 s40, s40, 0x400000
	s_addc_u32 s41, s41, 0
	s_waitcnt vmcnt(12)
; __device__ __forceinline__ void norm_phase(const void* src_lat, int lat_f32, const float* src_ctx, int nrows, const float* gvec, const float* mods_l, int sh_off, int sc_off, bf16_t* U, const float* part, int nparts, float* ctx_out) {
;     ...
;         if (row < MLAT && !lat_f32) { const bf16_t* src = (const bf16_t*)src_lat + (size_t)row * DM + 4 * lane;
; #pragma unroll
;             for (int j = 0; j < 4; ++j) { const u32x2 w = *(const u32x2*)(src + 256 * j);
;                 v[j] = (f32x4){__uint_as_float(w.x << 16), __uint_as_float(w.x & 0xffff0000u), __uint_as_float(w.y << 16), __uint_as_float(w.y & 0xffff0000u)}; } }
;         else { const float* src = row < MLAT ? (const float*)src_lat + (size_t)row * DM : src_ctx + (size_t)(row - MLAT) * DM;
; #pragma unroll
;             for (int j = 0; j < 4; ++j) v[j] = *(const f32x4*)(src + 4 * lane + 256 * j); }
; #pragma unroll
;         for (int j = 0; j < 4; ++j) { ss += (v[j][0] * v[j][0] + v[j][1] * v[j][1]) + (v[j][2] * v[j][2] + v[j][3] * v[j][3]); }
;         if (nparts != 0 && row >= MLAT) {
;             for (int ch = 0; ch < nparts; ch += 4) {
;                 f32x4 pv[4][4];
; #pragma unroll
;                 for (int c4 = 0; c4 < 4; ++c4) { const float* pr = part + ((size_t)(ch + c4) * MCTX + (row - MLAT)) * DM + 4 * lane;
; #pragma unroll
;                     for (int j = 0; j < 4; ++j) pv[c4][j] = *(const f32x4*)(pr + 256 * j); }
; #pragma unroll
;                 for (int c4 = 0; c4 < 4; ++c4)
; #pragma unroll
;                     for (int j = 0; j < 4; ++j) v[j] = v[j] + pv[c4][j]; }
;             ss = 0.f;
; #pragma unroll
;             for (int j = 0; j < 4; ++j) { *(f32x4*)(ctx_out + (size_t)(row - MLAT) * DM + 4 * lane + 256 * j) = v[j]; ss += (v[j][0] * v[j][0] + v[j][1] * v[j][1]) + (v[j][2] * v[j][2] + v[j][3] * v[j][3]); }
;         }
;         const float rs = rsqrtf(wave_sum64(ss) * (1.0f / DM) + EPS);
;         const float* shp = mods_l + s * 6144 + sh_off + 4 * lane; const float* scp = mods_l + s * 6144 + sc_off + 4 * lane;
;         bf16_t* up = U + (size_t)row * DM + 4 * lane;
; #pragma unroll
;         for (int j = 0; j < 4; ++j) { const f32x4 sh = *(const f32x4*)(shp + 256 * j), sc = *(const f32x4*)(scp + 256 * j);
;             const f32x4 y = v[j] * rs * gv[j] * (sc + 1.0f) + sh;
;             u32x2 o; o.x = pkbf(y[0], y[1]); o.y = pkbf(y[2], y[3]); *(u32x2*)(up + 256 * j) = o; }
	v_lshlrev_b32_e32 v40, 16, v128
	v_and_b32_e32 v41, 0xffff0000, v128
	v_lshlrev_b32_e32 v42, 16, v129
	v_and_b32_e32 v43, 0xffff0000, v129
	v_lshlrev_b32_e32 v44, 16, v130
	v_and_b32_e32 v45, 0xffff0000, v130
	v_lshlrev_b32_e32 v46, 16, v131
	v_and_b32_e32 v47, 0xffff0000, v131
	v_lshlrev_b32_e32 v48, 16, v132
	v_and_b32_e32 v49, 0xffff0000, v132
	v_lshlrev_b32_e32 v50, 16, v133
	v_and_b32_e32 v51, 0xffff0000, v133
	v_lshlrev_b32_e32 v52, 16, v134
	v_and_b32_e32 v53, 0xffff0000, v134
	v_lshlrev_b32_e32 v54, 16, v135
	v_and_b32_e32 v55, 0xffff0000, v135
	v_mul_f32_e32 v56, v41, v41
	v_mul_f32_e32 v57, v43, v43
	v_fmac_f32_e32 v56, v40, v40
	v_fmac_f32_e32 v57, v42, v42
	v_add_f32_e32 v58, v56, v57
	v_mul_f32_e32 v56, v45, v45
	v_mul_f32_e32 v57, v47, v47
	v_fmac_f32_e32 v56, v44, v44
	v_fmac_f32_e32 v57, v46, v46
	v_add_f32_e32 v56, v56, v57
	v_add_f32_e32 v58, v58, v56
	v_mul_f32_e32 v56, v49, v49
	v_mul_f32_e32 v57, v51, v51
	v_fmac_f32_e32 v56, v48, v48
	v_fmac_f32_e32 v57, v50, v50
	v_add_f32_e32 v56, v56, v57
	v_add_f32_e32 v58, v58, v56
	v_mul_f32_e32 v56, v53, v53
	v_mul_f32_e32 v57, v55, v55
	v_fmac_f32_e32 v56, v52, v52
	v_fmac_f32_e32 v57, v54, v54
	v_add_f32_e32 v56, v56, v57
	v_add_f32_e32 v58, v58, v56
	s_nop 1
	v_add_f32_dpp v58, v58, v58 quad_perm:[1,0,3,2] row_mask:0xf bank_mask:0xf bound_ctrl:1
	s_nop 1
	v_add_f32_dpp v58, v58, v58 quad_perm:[2,3,0,1] row_mask:0xf bank_mask:0xf bound_ctrl:1
	s_nop 1
	v_add_f32_dpp v58, v58, v58 row_half_mirror row_mask:0xf bank_mask:0xf bound_ctrl:1
	s_nop 1
	v_add_f32_dpp v58, v58, v58 row_mirror row_mask:0xf bank_mask:0xf bound_ctrl:1
	v_mov_b32_e32 v56, v58
	s_nop 1
	v_permlane16_swap_b32_e32 v58, v56
	v_add_f32_e32 v58, v58, v56
	v_mov_b32_e32 v56, v58
	s_nop 1
	v_permlane32_swap_b32_e32 v58, v56
	v_add_f32_e32 v58, v58, v56
	v_fmamk_f32 v60, v58, 0x3a800000, v153
	v_rsq_f32_e32 v60, v60
	s_nop 0
	v_pk_mul_f32 v[40:41], v[40:41], v[60:61] op_sel_hi:[1,0]
	v_pk_mul_f32 v[42:43], v[42:43], v[60:61] op_sel_hi:[1,0]
	v_pk_mul_f32 v[44:45], v[44:45], v[60:61] op_sel_hi:[1,0]
	v_pk_mul_f32 v[46:47], v[46:47], v[60:61] op_sel_hi:[1,0]
	v_pk_mul_f32 v[48:49], v[48:49], v[60:61] op_sel_hi:[1,0]
	v_pk_mul_f32 v[50:51], v[50:51], v[60:61] op_sel_hi:[1,0]
	v_pk_mul_f32 v[52:53], v[52:53], v[60:61] op_sel_hi:[1,0]
	v_pk_mul_f32 v[54:55], v[54:55], v[60:61] op_sel_hi:[1,0]
	v_pk_mul_f32 v[40:41], v[0:1], v[40:41]
	v_pk_mul_f32 v[42:43], v[2:3], v[42:43]
	v_pk_mul_f32 v[44:45], v[4:5], v[44:45]
	v_pk_mul_f32 v[46:47], v[6:7], v[46:47]
	v_pk_mul_f32 v[48:49], v[8:9], v[48:49]
	v_pk_mul_f32 v[50:51], v[10:11], v[50:51]
	v_pk_mul_f32 v[52:53], v[12:13], v[52:53]
	v_pk_mul_f32 v[54:55], v[14:15], v[54:55]
	v_pk_fma_f32 v[40:41], v[84:85], v[40:41], v[68:69]
	v_pk_fma_f32 v[42:43], v[86:87], v[42:43], v[70:71]
	v_pk_fma_f32 v[44:45], v[88:89], v[44:45], v[72:73]
	v_pk_fma_f32 v[46:47], v[90:91], v[46:47], v[74:75]
	v_pk_fma_f32 v[48:49], v[92:93], v[48:49], v[76:77]
	v_pk_fma_f32 v[50:51], v[94:95], v[50:51], v[78:79]
	v_pk_fma_f32 v[52:53], v[96:97], v[52:53], v[80:81]
	v_pk_fma_f32 v[54:55], v[98:99], v[54:55], v[82:83]
	v_cvt_pk_bf16_f32 v40, v40, v41
	v_cvt_pk_bf16_f32 v41, v42, v43
	v_cvt_pk_bf16_f32 v44, v44, v45
	v_cvt_pk_bf16_f32 v45, v46, v47
	v_cvt_pk_bf16_f32 v48, v48, v49
	v_cvt_pk_bf16_f32 v49, v50, v51
	v_cvt_pk_bf16_f32 v52, v52, v53
	v_cvt_pk_bf16_f32 v53, v54, v55
	global_store_dwordx2 v100, v[40:41], s[40:41]
	global_store_dwordx2 v100, v[44:45], s[40:41] offset:512
	global_store_dwordx2 v100, v[48:49], s[40:41] offset:1024
	global_store_dwordx2 v100, v[52:53], s[40:41] offset:1536
	s_add_u32 s40, s40, 0x400000
	s_addc_u32 s41, s41, 0
	s_add_i32 s0, s0, 0x8000
	v_add_co_u32_e32 v38, vcc, 0x4000000, v38
	s_nop 1
	v_addc_co_u32_e32 v39, vcc, 0, v39, vcc
	s_cmp_lt_i32 s0, s26
	s_cbranch_scc1 .LBB0_732
	s_branch .LBB0_738

; __global__ void __launch_bounds__(512, 2) fwd_megakernel(Args a) {
;     ...
;             EpiRes E{WSP(bf16_t, WS_HB), WSP(float, WS_HC), l == 0 ? (void*)WSP(bf16_t, WS_HB) : (void*)A->out, WSP(float, WS_HC), WSP(float, WS_MODS) + l * 5 * 6144 + 5120, WSP(float, WS_PART), 0, l == 1};
.LBB0_863:
	s_or_b64 exec, exec, s[0:1]
	v_readlane_b32 s0, v240, 38
	v_readlane_b32 s1, v240, 39
	s_and_b64 vcc, exec, s[0:1]
	v_mov_b64_e32 v[158:159], s[70:71]
	s_waitcnt lgkmcnt(0)
	s_barrier
	s_cbranch_vccz .LBB0_865
	v_readlane_b32 s98, v240, 62
	v_readlane_b32 s99, v240, 63
	v_mov_b32_e32 v158, s98
	v_mov_b32_e32 v159, s99

; __global__ void __launch_bounds__(512, 2) fwd_megakernel(Args a) {
	.amdhsa_kernel _Z14fwd_megakernel4Args
		.amdhsa_group_segment_fixed_size 0
		.amdhsa_private_segment_fixed_size 0
		.amdhsa_kernarg_size 432
		.amdhsa_user_sgpr_count 2
		.amdhsa_user_sgpr_dispatch_ptr 0
		.amdhsa_user_sgpr_queue_ptr 0
		.amdhsa_user_sgpr_kernarg_segment_ptr 1
		.amdhsa_user_sgpr_dispatch_id 0
		.amdhsa_user_sgpr_kernarg_preload_length 0
		.amdhsa_user_sgpr_kernarg_preload_offset 0
		.amdhsa_user_sgpr_private_segment_size 0
		.amdhsa_uses_dynamic_stack 0
		.amdhsa_enable_private_segment 0
		.amdhsa_system_sgpr_workgroup_id_x 1
		.amdhsa_system_sgpr_workgroup_id_y 0
		.amdhsa_system_sgpr_workgroup_id_z 0
		.amdhsa_system_sgpr_workgroup_info 0
		.amdhsa_system_vgpr_workitem_id 2
		.amdhsa_next_free_vgpr 256
		.amdhsa_next_free_sgpr 100
		.amdhsa_accum_offset 256
		.amdhsa_reserve_vcc 1
		.amdhsa_float_round_mode_32 0
		.amdhsa_float_round_mode_16_64 0
		.amdhsa_float_denorm_mode_32 3
		.amdhsa_float_denorm_mode_16_64 3
		.amdhsa_dx10_clamp 1
		.amdhsa_ieee_mode 1
		.amdhsa_fp16_overflow 0
		.amdhsa_tg_split 0
		.amdhsa_exception_fp_ieee_invalid_op 0
		.amdhsa_exception_fp_denorm_src 0
		.amdhsa_exception_fp_ieee_div_zero 0
		.amdhsa_exception_fp_ieee_overflow 0
		.amdhsa_exception_fp_ieee_underflow 0
		.amdhsa_exception_fp_ieee_inexact 0
		.amdhsa_exception_int_div_zero 0
	.end_amdhsa_kernel

; __global__ void __launch_bounds__(512, 2) fwd_megakernel(Args a) {
amdhsa.kernels:
  - .agpr_count:     0
    .args:
      - .offset:         0
        .size:           176
        .value_kind:     by_value
      - .offset:         176
        .size:           4
        .value_kind:     hidden_block_count_x
      - .offset:         180
        .size:           4
        .value_kind:     hidden_block_count_y
      - .offset:         184
        .size:           4
        .value_kind:     hidden_block_count_z
      - .offset:         188
        .size:           2
        .value_kind:     hidden_group_size_x
      - .offset:         190
        .size:           2
        .value_kind:     hidden_group_size_y
      - .offset:         192
        .size:           2
        .value_kind:     hidden_group_size_z
      - .offset:         194
        .size:           2
        .value_kind:     hidden_remainder_x
      - .offset:         196
        .size:           2
        .value_kind:     hidden_remainder_y
      - .offset:         198
        .size:           2
        .value_kind:     hidden_remainder_z
      - .offset:         216
        .size:           8
        .value_kind:     hidden_global_offset_x
      - .offset:         224
        .size:           8
        .value_kind:     hidden_global_offset_y
      - .offset:         232
        .size:           8
        .value_kind:     hidden_global_offset_z
      - .offset:         240
        .size:           2
        .value_kind:     hidden_grid_dims
      - .offset:         264
        .size:           8
        .value_kind:     hidden_multigrid_sync_arg
      - .offset:         296
        .size:           4
        .value_kind:     hidden_dynamic_lds_size
    .group_segment_fixed_size: 0
    .kernarg_segment_align: 8
    .kernarg_segment_size: 432
    .language:       OpenCL C
    .language_version:
      - 2
      - 0
    .max_flat_workgroup_size: 512
    .name:           _Z14fwd_megakernel4Args
    .private_segment_fixed_size: 0
    .sgpr_count:     106
    .sgpr_spill_count: 117
    .symbol:         _Z14fwd_megakernel4Args.kd
    .uniform_work_group_size: 1
    .uses_dynamic_stack: false
    .vgpr_count:     256
    .vgpr_spill_count: 0
    .wavefront_size: 64
